# v40 + scan consumer loop: v values of two consecutive steps fetched by one ds_read2_b64 (half an LDS instruction less per step)
# baseline (speedup 1.0000x reference)
; template <int RPL, int NSW>
; __device__ __forceinline__ void scan_item(const P& p, LAS unsigned char* lds, int seqbase, int L, int head, int dir, int part, int step0, int nsteps, int mode, float* qc, float* smid) {
;     ...
;             SCAN_LD(0);
; #pragma unroll 16
;             for (int s = 0; s < TC; ++s) {
;                 const f32x2 w0 = {xw[0], xw[1]}, w1 = {xw[2], xw[3]}, kd0 = {xkd[0], xkd[1]}, kd1 = {xkd[2], xkd[3]}, kk0 = {xkk[0], xkk[1]}, kk1 = {xkk[2], xkk[3]},
;                             b0 = {xb[0], xb[1]}, b1 = {xb[2], xb[3]}, r0 = {xr[0], xr[1]}, r1 = {xr[2], xr[3]};
;                 float vr[RPL];
; #pragma unroll
;                 for (int q = 0; q < RPL; ++q) vr[q] = vrow[q];
;                 { const int sn = (s + 1 < TC) ? s + 1 : s; SCAN_LD(sn); }
;                 float sa[RPL];
; #pragma unroll
;                 for (int q = 0; q < RPL; ++q) { const f32x2 t = S[q][0] * kk0 + S[q][1] * kk1; sa[q] = t.x + t.y; }
;                 if (RPL == 2) {
;                     sa[0] += dppx<0xB1>(sa[0]); sa[RPL - 1] += dppx<0xB1>(sa[RPL - 1]); sa[0] += dppx<0x4E>(sa[0]); sa[RPL - 1] += dppx<0x4E>(sa[RPL - 1]);
;                     sa[0] += dppx<0x141>(sa[0]); sa[RPL - 1] += dppx<0x141>(sa[RPL - 1]); sa[0] += dppx<0x140>(sa[0]); sa[RPL - 1] += dppx<0x140>(sa[RPL - 1]);
;                 } else {
; #pragma unroll
;                     for (int q = 0; q < RPL; ++q) sa[q] = reduce16(sa[q]);
;                 }
;                 float ov[RPL];
;                 if (RPL == 2) {
;                     const f32x2 vva = {vr[0], vr[0]}, nsa = {-sa[0], -sa[0]}, vvb = {vr[RPL - 1], vr[RPL - 1]}, nsb = {-sa[RPL - 1], -sa[RPL - 1]};
;                     f32x2 a0 = nsa * b0, c0 = nsb * b0, a1 = nsa * b1, c1 = nsb * b1;
;                     a0 = vva * kd0 + a0; c0 = vvb * kd0 + c0; a1 = vva * kd1 + a1; c1 = vvb * kd1 + c1;
;                     S[0][0] = S[0][0] * w0 + a0; S[RPL - 1][0] = S[RPL - 1][0] * w0 + c0; S[0][1] = S[0][1] * w1 + a1; S[RPL - 1][1] = S[RPL - 1][1] * w1 + c1;
;                     f32x2 ua = S[0][0] * r0, ub = S[RPL - 1][0] * r0;
;                     ua = S[0][1] * r1 + ua; ub = S[RPL - 1][1] * r1 + ub;
;                     ov[0] = ua.x + ua.y; ov[RPL - 1] = ub.x + ub.y;
;                 } else {
; #pragma unroll
;                 for (int q = 0; q < RPL; ++q) {
.Lmy_scan_chunk:
	s_bitcmp1_b32 s4, 0
	s_cselect_b32 s5, 0xf000, 0
	v_add_u32_e32 v134, s5, v152
	v_add_u32_e32 v135, s5, v153
	v_add_u32_e32 v110, 0xa000, v135
	v_add_u32_e32 v111, 0xa800, v135
	ds_read_b128 v[16:19], v134 offset:16384
	ds_read_b128 v[12:15], v134 offset:8192
	ds_read2_b64 v[156:159], v110 offset0:0 offset1:16
	ds_read_b128 v[8:11], v134 offset:0
	ds_read_b128 v[20:23], v134 offset:24576
	ds_read_b128 v[24:27], v134 offset:32768
	v_add_u32_e32 v137, s5, v154
	v_cndmask_b32_e32 v136, v155, v137, vcc
	ds_read_b128 v[72:75], v134 offset:16640
	ds_read_b128 v[68:71], v134 offset:8448
	ds_read_b128 v[64:67], v134 offset:256
	ds_read_b128 v[76:79], v134 offset:24832
	ds_read_b128 v[80:83], v134 offset:33024
	v_add_u32_e32 v137, 0x400, v136
	v_add_u32_e32 v138, 0x800, v136
	v_add_u32_e32 v139, 0xc00, v136
	v_add_u32_e32 v140, 0x1000, v136
	v_add_u32_e32 v141, 0x1400, v136
	v_add_u32_e32 v142, 0x1800, v136
	v_add_u32_e32 v143, 0x1c00, v136
	v_add_u32_e32 v144, 0x2000, v136
	v_add_u32_e32 v145, 0x2400, v136
	v_add_u32_e32 v146, 0x2800, v136
	v_add_u32_e32 v147, 0x2c00, v136
	v_add_u32_e32 v148, 0x3000, v136
	v_add_u32_e32 v149, 0x3400, v136
	v_add_u32_e32 v150, 0x3800, v136
	v_add_u32_e32 v151, 0x3c00, v136
	s_waitcnt lgkmcnt(8)
	v_pk_mul_f32 v[128:129], v[118:119], v[18:19] op_sel:[0,1]
	v_pk_fma_f32 v[128:129], v[116:117], v[18:19], v[128:129] op_sel_hi:[1,0,1]
	v_pk_fma_f32 v[128:129], v[114:115], v[16:17], v[128:129] op_sel:[0,1,0]
	v_pk_fma_f32 v[128:129], v[112:113], v[16:17], v[128:129] op_sel_hi:[1,0,1]
	v_pk_mul_f32 v[126:127], v[156:157], v[14:15] op_sel:[0,1]
	v_pk_mul_f32 v[124:125], v[156:157], v[14:15] op_sel_hi:[1,0]
	v_add_f32_dpp v128, v128, v128 quad_perm:[1,0,3,2] row_mask:0xf bank_mask:0xf bound_ctrl:1
	v_add_f32_dpp v129, v129, v129 quad_perm:[1,0,3,2] row_mask:0xf bank_mask:0xf bound_ctrl:1
	v_pk_mul_f32 v[122:123], v[156:157], v[12:13] op_sel:[0,1]
	v_add_f32_dpp v128, v128, v128 quad_perm:[2,3,0,1] row_mask:0xf bank_mask:0xf bound_ctrl:1
	v_add_f32_dpp v129, v129, v129 quad_perm:[2,3,0,1] row_mask:0xf bank_mask:0xf bound_ctrl:1
	v_pk_mul_f32 v[120:121], v[156:157], v[12:13] op_sel_hi:[1,0]
	v_add_f32_dpp v128, v128, v128 row_half_mirror row_mask:0xf bank_mask:0xf bound_ctrl:1
	v_add_f32_dpp v129, v129, v129 row_half_mirror row_mask:0xf bank_mask:0xf bound_ctrl:1
	s_waitcnt lgkmcnt(0)
	v_pk_fma_f32 v[118:119], v[118:119], v[10:11], v[126:127] op_sel:[0,1,0]
	v_add_f32_dpp v132, v128, v128 row_mirror row_mask:0xf bank_mask:0xf bound_ctrl:1
	v_add_f32_dpp v133, v129, v129 row_mirror row_mask:0xf bank_mask:0xf bound_ctrl:1
	v_pk_fma_f32 v[116:117], v[116:117], v[10:11], v[124:125] op_sel_hi:[1,0,1]
	v_pk_fma_f32 v[114:115], v[114:115], v[8:9], v[122:123] op_sel:[0,1,0]
	v_pk_fma_f32 v[112:113], v[112:113], v[8:9], v[120:121] op_sel_hi:[1,0,1]
	v_pk_fma_f32 v[118:119], v[22:23], v[132:133], v[118:119] op_sel:[1,0,0] neg_lo:[0,1,0] neg_hi:[0,1,0]
	v_pk_fma_f32 v[116:117], v[22:23], v[132:133], v[116:117] op_sel_hi:[0,1,1] neg_lo:[0,1,0] neg_hi:[0,1,0]
	v_pk_fma_f32 v[114:115], v[20:21], v[132:133], v[114:115] op_sel:[1,0,0] neg_lo:[0,1,0] neg_hi:[0,1,0]
	v_pk_fma_f32 v[112:113], v[20:21], v[132:133], v[112:113] op_sel_hi:[0,1,1] neg_lo:[0,1,0] neg_hi:[0,1,0]
	ds_read_b128 v[100:103], v134 offset:25088
	v_pk_mul_f32 v[128:129], v[118:119], v[74:75] op_sel:[0,1]
	v_pk_mul_f32 v[130:131], v[118:119], v[26:27] op_sel:[0,1]
	v_pk_fma_f32 v[128:129], v[116:117], v[74:75], v[128:129] op_sel_hi:[1,0,1]
	v_pk_fma_f32 v[130:131], v[116:117], v[26:27], v[130:131] op_sel_hi:[1,0,1]
	ds_read_b128 v[104:107], v134 offset:33280
	v_pk_fma_f32 v[128:129], v[114:115], v[72:73], v[128:129] op_sel:[0,1,0]
	v_pk_fma_f32 v[130:131], v[114:115], v[24:25], v[130:131] op_sel:[0,1,0]
	v_pk_fma_f32 v[128:129], v[112:113], v[72:73], v[128:129] op_sel_hi:[1,0,1]
	v_pk_fma_f32 v[130:131], v[112:113], v[24:25], v[130:131] op_sel_hi:[1,0,1]
	ds_read_b128 v[96:99], v134 offset:16896
	v_add_f32_dpp v128, v128, v128 quad_perm:[1,0,3,2] row_mask:0xf bank_mask:0xf bound_ctrl:1
	v_add_f32_dpp v129, v129, v129 quad_perm:[1,0,3,2] row_mask:0xf bank_mask:0xf bound_ctrl:1
	v_add_f32_dpp v130, v130, v130 quad_perm:[1,0,3,2] row_mask:0xf bank_mask:0xf bound_ctrl:1
	v_add_f32_dpp v131, v131, v131 quad_perm:[1,0,3,2] row_mask:0xf bank_mask:0xf bound_ctrl:1
	ds_read_b128 v[92:95], v134 offset:8704
	v_add_f32_dpp v128, v128, v128 quad_perm:[2,3,0,1] row_mask:0xf bank_mask:0xf bound_ctrl:1
	v_add_f32_dpp v129, v129, v129 quad_perm:[2,3,0,1] row_mask:0xf bank_mask:0xf bound_ctrl:1
	v_add_f32_dpp v130, v130, v130 quad_perm:[2,3,0,1] row_mask:0xf bank_mask:0xf bound_ctrl:1
	v_add_f32_dpp v131, v131, v131 quad_perm:[2,3,0,1] row_mask:0xf bank_mask:0xf bound_ctrl:1
	v_pk_mul_f32 v[126:127], v[158:159], v[70:71] op_sel:[0,1]
	v_pk_mul_f32 v[124:125], v[158:159], v[70:71] op_sel_hi:[1,0]
	ds_read2_b64 v[160:163], v110 offset0:32 offset1:48
	v_add_f32_dpp v128, v128, v128 row_half_mirror row_mask:0xf bank_mask:0xf bound_ctrl:1
	v_add_f32_dpp v129, v129, v129 row_half_mirror row_mask:0xf bank_mask:0xf bound_ctrl:1
	ds_write2_b32 v136, v130, v131 offset0:0 offset1:4
	v_pk_mul_f32 v[122:123], v[158:159], v[68:69] op_sel:[0,1]
	v_add_f32_dpp v132, v128, v128 row_mirror row_mask:0xf bank_mask:0xf bound_ctrl:1
	v_add_f32_dpp v133, v129, v129 row_mirror row_mask:0xf bank_mask:0xf bound_ctrl:1
	v_pk_mul_f32 v[120:121], v[158:159], v[68:69] op_sel_hi:[1,0]
	ds_read_b128 v[88:91], v134 offset:512
	v_pk_fma_f32 v[118:119], v[118:119], v[66:67], v[126:127] op_sel:[0,1,0]
	v_pk_fma_f32 v[116:117], v[116:117], v[66:67], v[124:125] op_sel_hi:[1,0,1]
	v_pk_fma_f32 v[114:115], v[114:115], v[64:65], v[122:123] op_sel:[0,1,0]
	v_pk_fma_f32 v[112:113], v[112:113], v[64:65], v[120:121] op_sel_hi:[1,0,1]
	v_pk_fma_f32 v[118:119], v[78:79], v[132:133], v[118:119] op_sel:[1,0,0] neg_lo:[0,1,0] neg_hi:[0,1,0]
	v_pk_fma_f32 v[116:117], v[78:79], v[132:133], v[116:117] op_sel_hi:[0,1,1] neg_lo:[0,1,0] neg_hi:[0,1,0]
	v_pk_fma_f32 v[114:115], v[76:77], v[132:133], v[114:115] op_sel:[1,0,0] neg_lo:[0,1,0] neg_hi:[0,1,0]
	v_pk_fma_f32 v[112:113], v[76:77], v[132:133], v[112:113] op_sel_hi:[0,1,1] neg_lo:[0,1,0] neg_hi:[0,1,0]
	ds_read_b128 v[20:23], v134 offset:25344
	s_waitcnt lgkmcnt(5)
; template <int RPL, int NSW>
; __device__ __forceinline__ void scan_item(const P& p, LAS unsigned char* lds, int seqbase, int L, int head, int dir, int part, int step0, int nsteps, int mode, float* qc, float* smid) {
;     ...
;             SCAN_LD(0);
; #pragma unroll 16
;             for (int s = 0; s < TC; ++s) {
;                 const f32x2 w0 = {xw[0], xw[1]}, w1 = {xw[2], xw[3]}, kd0 = {xkd[0], xkd[1]}, kd1 = {xkd[2], xkd[3]}, kk0 = {xkk[0], xkk[1]}, kk1 = {xkk[2], xkk[3]},
;                             b0 = {xb[0], xb[1]}, b1 = {xb[2], xb[3]}, r0 = {xr[0], xr[1]}, r1 = {xr[2], xr[3]};
;                 float vr[RPL];
; #pragma unroll
;                 for (int q = 0; q < RPL; ++q) vr[q] = vrow[q];
;                 { const int sn = (s + 1 < TC) ? s + 1 : s; SCAN_LD(sn); }
;                 float sa[RPL];
; #pragma unroll
;                 for (int q = 0; q < RPL; ++q) { const f32x2 t = S[q][0] * kk0 + S[q][1] * kk1; sa[q] = t.x + t.y; }
;                 if (RPL == 2) {
;                     sa[0] += dppx<0xB1>(sa[0]); sa[RPL - 1] += dppx<0xB1>(sa[RPL - 1]); sa[0] += dppx<0x4E>(sa[0]); sa[RPL - 1] += dppx<0x4E>(sa[RPL - 1]);
;                     sa[0] += dppx<0x141>(sa[0]); sa[RPL - 1] += dppx<0x141>(sa[RPL - 1]); sa[0] += dppx<0x140>(sa[0]); sa[RPL - 1] += dppx<0x140>(sa[RPL - 1]);
;                 } else {
; #pragma unroll
;                     for (int q = 0; q < RPL; ++q) sa[q] = reduce16(sa[q]);
;                 }
;                 float ov[RPL];
;                 if (RPL == 2) {
;                     const f32x2 vva = {vr[0], vr[0]}, nsa = {-sa[0], -sa[0]}, vvb = {vr[RPL - 1], vr[RPL - 1]}, nsb = {-sa[RPL - 1], -sa[RPL - 1]};
;                     f32x2 a0 = nsa * b0, c0 = nsb * b0, a1 = nsa * b1, c1 = nsb * b1;
;                     a0 = vva * kd0 + a0; c0 = vvb * kd0 + c0; a1 = vva * kd1 + a1; c1 = vvb * kd1 + c1;
;                     S[0][0] = S[0][0] * w0 + a0; S[RPL - 1][0] = S[RPL - 1][0] * w0 + c0; S[0][1] = S[0][1] * w1 + a1; S[RPL - 1][1] = S[RPL - 1][1] * w1 + c1;
;                     f32x2 ua = S[0][0] * r0, ub = S[RPL - 1][0] * r0;
;                     ua = S[0][1] * r1 + ua; ub = S[RPL - 1][1] * r1 + ub;
;                     ov[0] = ua.x + ua.y; ov[RPL - 1] = ub.x + ub.y;
;                 } else {
; #pragma unroll
;                 for (int q = 0; q < RPL; ++q) {
	v_pk_mul_f32 v[128:129], v[118:119], v[98:99] op_sel:[0,1]
	v_pk_mul_f32 v[130:131], v[118:119], v[82:83] op_sel:[0,1]
	v_pk_fma_f32 v[128:129], v[116:117], v[98:99], v[128:129] op_sel_hi:[1,0,1]
	v_pk_fma_f32 v[130:131], v[116:117], v[82:83], v[130:131] op_sel_hi:[1,0,1]
	ds_read_b128 v[24:27], v134 offset:33536
	v_pk_fma_f32 v[128:129], v[114:115], v[96:97], v[128:129] op_sel:[0,1,0]
	v_pk_fma_f32 v[130:131], v[114:115], v[80:81], v[130:131] op_sel:[0,1,0]
	v_pk_fma_f32 v[128:129], v[112:113], v[96:97], v[128:129] op_sel_hi:[1,0,1]
	v_pk_fma_f32 v[130:131], v[112:113], v[80:81], v[130:131] op_sel_hi:[1,0,1]
	ds_read_b128 v[16:19], v134 offset:17152
	v_add_f32_dpp v128, v128, v128 quad_perm:[1,0,3,2] row_mask:0xf bank_mask:0xf bound_ctrl:1
	v_add_f32_dpp v129, v129, v129 quad_perm:[1,0,3,2] row_mask:0xf bank_mask:0xf bound_ctrl:1
	v_add_f32_dpp v130, v130, v130 quad_perm:[1,0,3,2] row_mask:0xf bank_mask:0xf bound_ctrl:1
	v_add_f32_dpp v131, v131, v131 quad_perm:[1,0,3,2] row_mask:0xf bank_mask:0xf bound_ctrl:1
	ds_read_b128 v[12:15], v134 offset:8960
	v_add_f32_dpp v128, v128, v128 quad_perm:[2,3,0,1] row_mask:0xf bank_mask:0xf bound_ctrl:1
	v_add_f32_dpp v129, v129, v129 quad_perm:[2,3,0,1] row_mask:0xf bank_mask:0xf bound_ctrl:1
	v_add_f32_dpp v130, v130, v130 quad_perm:[2,3,0,1] row_mask:0xf bank_mask:0xf bound_ctrl:1
	v_add_f32_dpp v131, v131, v131 quad_perm:[2,3,0,1] row_mask:0xf bank_mask:0xf bound_ctrl:1
	s_waitcnt lgkmcnt(4)
	v_pk_mul_f32 v[126:127], v[160:161], v[94:95] op_sel:[0,1]
	v_pk_mul_f32 v[124:125], v[160:161], v[94:95] op_sel_hi:[1,0]
	ds_read_b128 v[8:11], v134 offset:768
	v_add_f32_dpp v128, v128, v128 row_half_mirror row_mask:0xf bank_mask:0xf bound_ctrl:1
	v_add_f32_dpp v129, v129, v129 row_half_mirror row_mask:0xf bank_mask:0xf bound_ctrl:1
	ds_write2_b32 v136, v130, v131 offset0:128 offset1:132
	v_pk_mul_f32 v[122:123], v[160:161], v[92:93] op_sel:[0,1]
	v_add_f32_dpp v132, v128, v128 row_mirror row_mask:0xf bank_mask:0xf bound_ctrl:1
	v_add_f32_dpp v133, v129, v129 row_mirror row_mask:0xf bank_mask:0xf bound_ctrl:1
	v_pk_mul_f32 v[120:121], v[160:161], v[92:93] op_sel_hi:[1,0]
	v_pk_fma_f32 v[118:119], v[118:119], v[90:91], v[126:127] op_sel:[0,1,0]
	v_pk_fma_f32 v[116:117], v[116:117], v[90:91], v[124:125] op_sel_hi:[1,0,1]
	v_pk_fma_f32 v[114:115], v[114:115], v[88:89], v[122:123] op_sel:[0,1,0]
	v_pk_fma_f32 v[112:113], v[112:113], v[88:89], v[120:121] op_sel_hi:[1,0,1]
	v_pk_fma_f32 v[118:119], v[102:103], v[132:133], v[118:119] op_sel:[1,0,0] neg_lo:[0,1,0] neg_hi:[0,1,0]
	v_pk_fma_f32 v[116:117], v[102:103], v[132:133], v[116:117] op_sel_hi:[0,1,1] neg_lo:[0,1,0] neg_hi:[0,1,0]
	v_pk_fma_f32 v[114:115], v[100:101], v[132:133], v[114:115] op_sel:[1,0,0] neg_lo:[0,1,0] neg_hi:[0,1,0]
	v_pk_fma_f32 v[112:113], v[100:101], v[132:133], v[112:113] op_sel_hi:[0,1,1] neg_lo:[0,1,0] neg_hi:[0,1,0]
	ds_read_b128 v[76:79], v134 offset:25600
	s_waitcnt lgkmcnt(4)
	v_pk_mul_f32 v[128:129], v[118:119], v[18:19] op_sel:[0,1]
	v_pk_mul_f32 v[130:131], v[118:119], v[106:107] op_sel:[0,1]
	v_pk_fma_f32 v[128:129], v[116:117], v[18:19], v[128:129] op_sel_hi:[1,0,1]
	v_pk_fma_f32 v[130:131], v[116:117], v[106:107], v[130:131] op_sel_hi:[1,0,1]
	ds_read_b128 v[80:83], v134 offset:33792
	v_pk_fma_f32 v[128:129], v[114:115], v[16:17], v[128:129] op_sel:[0,1,0]
	v_pk_fma_f32 v[130:131], v[114:115], v[104:105], v[130:131] op_sel:[0,1,0]
	v_pk_fma_f32 v[128:129], v[112:113], v[16:17], v[128:129] op_sel_hi:[1,0,1]
	v_pk_fma_f32 v[130:131], v[112:113], v[104:105], v[130:131] op_sel_hi:[1,0,1]
	ds_read_b128 v[72:75], v134 offset:17408
	v_add_f32_dpp v128, v128, v128 quad_perm:[1,0,3,2] row_mask:0xf bank_mask:0xf bound_ctrl:1
	v_add_f32_dpp v129, v129, v129 quad_perm:[1,0,3,2] row_mask:0xf bank_mask:0xf bound_ctrl:1
	v_add_f32_dpp v130, v130, v130 quad_perm:[1,0,3,2] row_mask:0xf bank_mask:0xf bound_ctrl:1
	v_add_f32_dpp v131, v131, v131 quad_perm:[1,0,3,2] row_mask:0xf bank_mask:0xf bound_ctrl:1
	ds_read_b128 v[68:71], v134 offset:9216
	v_add_f32_dpp v128, v128, v128 quad_perm:[2,3,0,1] row_mask:0xf bank_mask:0xf bound_ctrl:1
	v_add_f32_dpp v129, v129, v129 quad_perm:[2,3,0,1] row_mask:0xf bank_mask:0xf bound_ctrl:1
	v_add_f32_dpp v130, v130, v130 quad_perm:[2,3,0,1] row_mask:0xf bank_mask:0xf bound_ctrl:1
	v_add_f32_dpp v131, v131, v131 quad_perm:[2,3,0,1] row_mask:0xf bank_mask:0xf bound_ctrl:1
	s_waitcnt lgkmcnt(4)
	v_pk_mul_f32 v[126:127], v[162:163], v[14:15] op_sel:[0,1]
	v_pk_mul_f32 v[124:125], v[162:163], v[14:15] op_sel_hi:[1,0]
	ds_read2_b64 v[156:159], v110 offset0:64 offset1:80
	v_add_f32_dpp v128, v128, v128 row_half_mirror row_mask:0xf bank_mask:0xf bound_ctrl:1
	v_add_f32_dpp v129, v129, v129 row_half_mirror row_mask:0xf bank_mask:0xf bound_ctrl:1
	ds_write2_b32 v137, v130, v131 offset0:0 offset1:4
	v_pk_mul_f32 v[122:123], v[162:163], v[12:13] op_sel:[0,1]
	v_add_f32_dpp v132, v128, v128 row_mirror row_mask:0xf bank_mask:0xf bound_ctrl:1
	v_add_f32_dpp v133, v129, v129 row_mirror row_mask:0xf bank_mask:0xf bound_ctrl:1
	v_pk_mul_f32 v[120:121], v[162:163], v[12:13] op_sel_hi:[1,0]
	ds_read_b128 v[64:67], v134 offset:1024
	v_pk_fma_f32 v[118:119], v[118:119], v[10:11], v[126:127] op_sel:[0,1,0]
	v_pk_fma_f32 v[116:117], v[116:117], v[10:11], v[124:125] op_sel_hi:[1,0,1]
	v_pk_fma_f32 v[114:115], v[114:115], v[8:9], v[122:123] op_sel:[0,1,0]
	v_pk_fma_f32 v[112:113], v[112:113], v[8:9], v[120:121] op_sel_hi:[1,0,1]
	v_pk_fma_f32 v[118:119], v[22:23], v[132:133], v[118:119] op_sel:[1,0,0] neg_lo:[0,1,0] neg_hi:[0,1,0]
	v_pk_fma_f32 v[116:117], v[22:23], v[132:133], v[116:117] op_sel_hi:[0,1,1] neg_lo:[0,1,0] neg_hi:[0,1,0]
	v_pk_fma_f32 v[114:115], v[20:21], v[132:133], v[114:115] op_sel:[1,0,0] neg_lo:[0,1,0] neg_hi:[0,1,0]
	v_pk_fma_f32 v[112:113], v[20:21], v[132:133], v[112:113] op_sel_hi:[0,1,1] neg_lo:[0,1,0] neg_hi:[0,1,0]
	ds_read_b128 v[100:103], v134 offset:25856
	s_waitcnt lgkmcnt(4)
; template <int RPL, int NSW>
; __device__ __forceinline__ void scan_item(const P& p, LAS unsigned char* lds, int seqbase, int L, int head, int dir, int part, int step0, int nsteps, int mode, float* qc, float* smid) {
;     ...
;             for (int s = 0; s < TC; ++s) {
;                 const f32x2 w0 = {xw[0], xw[1]}, w1 = {xw[2], xw[3]}, kd0 = {xkd[0], xkd[1]}, kd1 = {xkd[2], xkd[3]}, kk0 = {xkk[0], xkk[1]}, kk1 = {xkk[2], xkk[3]},
;                             b0 = {xb[0], xb[1]}, b1 = {xb[2], xb[3]}, r0 = {xr[0], xr[1]}, r1 = {xr[2], xr[3]};
;                 float vr[RPL];
; #pragma unroll
;                 for (int q = 0; q < RPL; ++q) vr[q] = vrow[q];
;                 { const int sn = (s + 1 < TC) ? s + 1 : s; SCAN_LD(sn); }
;                 float sa[RPL];
; #pragma unroll
;                 for (int q = 0; q < RPL; ++q) { const f32x2 t = S[q][0] * kk0 + S[q][1] * kk1; sa[q] = t.x + t.y; }
;                 if (RPL == 2) {
;                     sa[0] += dppx<0xB1>(sa[0]); sa[RPL - 1] += dppx<0xB1>(sa[RPL - 1]); sa[0] += dppx<0x4E>(sa[0]); sa[RPL - 1] += dppx<0x4E>(sa[RPL - 1]);
;                     sa[0] += dppx<0x141>(sa[0]); sa[RPL - 1] += dppx<0x141>(sa[RPL - 1]); sa[0] += dppx<0x140>(sa[0]); sa[RPL - 1] += dppx<0x140>(sa[RPL - 1]);
;                 } else {
; #pragma unroll
;                     for (int q = 0; q < RPL; ++q) sa[q] = reduce16(sa[q]);
;                 }
;                 float ov[RPL];
;                 if (RPL == 2) {
;                     const f32x2 vva = {vr[0], vr[0]}, nsa = {-sa[0], -sa[0]}, vvb = {vr[RPL - 1], vr[RPL - 1]}, nsb = {-sa[RPL - 1], -sa[RPL - 1]};
;                     f32x2 a0 = nsa * b0, c0 = nsb * b0, a1 = nsa * b1, c1 = nsb * b1;
;                     a0 = vva * kd0 + a0; c0 = vvb * kd0 + c0; a1 = vva * kd1 + a1; c1 = vvb * kd1 + c1;
;                     S[0][0] = S[0][0] * w0 + a0; S[RPL - 1][0] = S[RPL - 1][0] * w0 + c0; S[0][1] = S[0][1] * w1 + a1; S[RPL - 1][1] = S[RPL - 1][1] * w1 + c1;
;                     f32x2 ua = S[0][0] * r0, ub = S[RPL - 1][0] * r0;
;                     ua = S[0][1] * r1 + ua; ub = S[RPL - 1][1] * r1 + ub;
;                     ov[0] = ua.x + ua.y; ov[RPL - 1] = ub.x + ub.y;
;                 } else {
; #pragma unroll
;                 for (int q = 0; q < RPL; ++q) {
;                     const f32x2 vv = {vr[q], vr[q]}, ns = {-sa[q], -sa[q]};
	v_pk_mul_f32 v[128:129], v[118:119], v[74:75] op_sel:[0,1]
	v_pk_mul_f32 v[130:131], v[118:119], v[26:27] op_sel:[0,1]
	v_pk_fma_f32 v[128:129], v[116:117], v[74:75], v[128:129] op_sel_hi:[1,0,1]
	v_pk_fma_f32 v[130:131], v[116:117], v[26:27], v[130:131] op_sel_hi:[1,0,1]
	ds_read_b128 v[104:107], v134 offset:34048
	v_pk_fma_f32 v[128:129], v[114:115], v[72:73], v[128:129] op_sel:[0,1,0]
	v_pk_fma_f32 v[130:131], v[114:115], v[24:25], v[130:131] op_sel:[0,1,0]
	v_pk_fma_f32 v[128:129], v[112:113], v[72:73], v[128:129] op_sel_hi:[1,0,1]
	v_pk_fma_f32 v[130:131], v[112:113], v[24:25], v[130:131] op_sel_hi:[1,0,1]
	ds_read_b128 v[96:99], v134 offset:17664
	v_add_f32_dpp v128, v128, v128 quad_perm:[1,0,3,2] row_mask:0xf bank_mask:0xf bound_ctrl:1
	v_add_f32_dpp v129, v129, v129 quad_perm:[1,0,3,2] row_mask:0xf bank_mask:0xf bound_ctrl:1
	v_add_f32_dpp v130, v130, v130 quad_perm:[1,0,3,2] row_mask:0xf bank_mask:0xf bound_ctrl:1
	v_add_f32_dpp v131, v131, v131 quad_perm:[1,0,3,2] row_mask:0xf bank_mask:0xf bound_ctrl:1
	ds_read_b128 v[92:95], v134 offset:9472
	v_add_f32_dpp v128, v128, v128 quad_perm:[2,3,0,1] row_mask:0xf bank_mask:0xf bound_ctrl:1
	v_add_f32_dpp v129, v129, v129 quad_perm:[2,3,0,1] row_mask:0xf bank_mask:0xf bound_ctrl:1
	v_add_f32_dpp v130, v130, v130 quad_perm:[2,3,0,1] row_mask:0xf bank_mask:0xf bound_ctrl:1
	v_add_f32_dpp v131, v131, v131 quad_perm:[2,3,0,1] row_mask:0xf bank_mask:0xf bound_ctrl:1
	s_waitcnt lgkmcnt(4)
	v_pk_mul_f32 v[126:127], v[156:157], v[70:71] op_sel:[0,1]
	v_pk_mul_f32 v[124:125], v[156:157], v[70:71] op_sel_hi:[1,0]
	ds_read_b128 v[88:91], v134 offset:1280
	v_add_f32_dpp v128, v128, v128 row_half_mirror row_mask:0xf bank_mask:0xf bound_ctrl:1
	v_add_f32_dpp v129, v129, v129 row_half_mirror row_mask:0xf bank_mask:0xf bound_ctrl:1
	ds_write2_b32 v137, v130, v131 offset0:128 offset1:132
	v_pk_mul_f32 v[122:123], v[156:157], v[68:69] op_sel:[0,1]
	v_add_f32_dpp v132, v128, v128 row_mirror row_mask:0xf bank_mask:0xf bound_ctrl:1
	v_add_f32_dpp v133, v129, v129 row_mirror row_mask:0xf bank_mask:0xf bound_ctrl:1
	v_pk_mul_f32 v[120:121], v[156:157], v[68:69] op_sel_hi:[1,0]
	v_pk_fma_f32 v[118:119], v[118:119], v[66:67], v[126:127] op_sel:[0,1,0]
	v_pk_fma_f32 v[116:117], v[116:117], v[66:67], v[124:125] op_sel_hi:[1,0,1]
	v_pk_fma_f32 v[114:115], v[114:115], v[64:65], v[122:123] op_sel:[0,1,0]
	v_pk_fma_f32 v[112:113], v[112:113], v[64:65], v[120:121] op_sel_hi:[1,0,1]
	v_pk_fma_f32 v[118:119], v[78:79], v[132:133], v[118:119] op_sel:[1,0,0] neg_lo:[0,1,0] neg_hi:[0,1,0]
	v_pk_fma_f32 v[116:117], v[78:79], v[132:133], v[116:117] op_sel_hi:[0,1,1] neg_lo:[0,1,0] neg_hi:[0,1,0]
	v_pk_fma_f32 v[114:115], v[76:77], v[132:133], v[114:115] op_sel:[1,0,0] neg_lo:[0,1,0] neg_hi:[0,1,0]
	v_pk_fma_f32 v[112:113], v[76:77], v[132:133], v[112:113] op_sel_hi:[0,1,1] neg_lo:[0,1,0] neg_hi:[0,1,0]
	ds_read_b128 v[20:23], v134 offset:26112
	s_waitcnt lgkmcnt(4)
	v_pk_mul_f32 v[128:129], v[118:119], v[98:99] op_sel:[0,1]
	v_pk_mul_f32 v[130:131], v[118:119], v[82:83] op_sel:[0,1]
	v_pk_fma_f32 v[128:129], v[116:117], v[98:99], v[128:129] op_sel_hi:[1,0,1]
	v_pk_fma_f32 v[130:131], v[116:117], v[82:83], v[130:131] op_sel_hi:[1,0,1]
	ds_read_b128 v[24:27], v134 offset:34304
	v_pk_fma_f32 v[128:129], v[114:115], v[96:97], v[128:129] op_sel:[0,1,0]
	v_pk_fma_f32 v[130:131], v[114:115], v[80:81], v[130:131] op_sel:[0,1,0]
	v_pk_fma_f32 v[128:129], v[112:113], v[96:97], v[128:129] op_sel_hi:[1,0,1]
	v_pk_fma_f32 v[130:131], v[112:113], v[80:81], v[130:131] op_sel_hi:[1,0,1]
	ds_read_b128 v[16:19], v134 offset:17920
	v_add_f32_dpp v128, v128, v128 quad_perm:[1,0,3,2] row_mask:0xf bank_mask:0xf bound_ctrl:1
	v_add_f32_dpp v129, v129, v129 quad_perm:[1,0,3,2] row_mask:0xf bank_mask:0xf bound_ctrl:1
	v_add_f32_dpp v130, v130, v130 quad_perm:[1,0,3,2] row_mask:0xf bank_mask:0xf bound_ctrl:1
	v_add_f32_dpp v131, v131, v131 quad_perm:[1,0,3,2] row_mask:0xf bank_mask:0xf bound_ctrl:1
	ds_read_b128 v[12:15], v134 offset:9728
	v_add_f32_dpp v128, v128, v128 quad_perm:[2,3,0,1] row_mask:0xf bank_mask:0xf bound_ctrl:1
	v_add_f32_dpp v129, v129, v129 quad_perm:[2,3,0,1] row_mask:0xf bank_mask:0xf bound_ctrl:1
	v_add_f32_dpp v130, v130, v130 quad_perm:[2,3,0,1] row_mask:0xf bank_mask:0xf bound_ctrl:1
	v_add_f32_dpp v131, v131, v131 quad_perm:[2,3,0,1] row_mask:0xf bank_mask:0xf bound_ctrl:1
	s_waitcnt lgkmcnt(4)
	v_pk_mul_f32 v[126:127], v[158:159], v[94:95] op_sel:[0,1]
	v_pk_mul_f32 v[124:125], v[158:159], v[94:95] op_sel_hi:[1,0]
	ds_read2_b64 v[160:163], v110 offset0:96 offset1:112
	v_add_f32_dpp v128, v128, v128 row_half_mirror row_mask:0xf bank_mask:0xf bound_ctrl:1
	v_add_f32_dpp v129, v129, v129 row_half_mirror row_mask:0xf bank_mask:0xf bound_ctrl:1
	ds_write2_b32 v138, v130, v131 offset0:0 offset1:4
	v_pk_mul_f32 v[122:123], v[158:159], v[92:93] op_sel:[0,1]
	v_add_f32_dpp v132, v128, v128 row_mirror row_mask:0xf bank_mask:0xf bound_ctrl:1
	v_add_f32_dpp v133, v129, v129 row_mirror row_mask:0xf bank_mask:0xf bound_ctrl:1
	v_pk_mul_f32 v[120:121], v[158:159], v[92:93] op_sel_hi:[1,0]
	ds_read_b128 v[8:11], v134 offset:1536
	v_pk_fma_f32 v[118:119], v[118:119], v[90:91], v[126:127] op_sel:[0,1,0]
	v_pk_fma_f32 v[116:117], v[116:117], v[90:91], v[124:125] op_sel_hi:[1,0,1]
	v_pk_fma_f32 v[114:115], v[114:115], v[88:89], v[122:123] op_sel:[0,1,0]
	v_pk_fma_f32 v[112:113], v[112:113], v[88:89], v[120:121] op_sel_hi:[1,0,1]
	v_pk_fma_f32 v[118:119], v[102:103], v[132:133], v[118:119] op_sel:[1,0,0] neg_lo:[0,1,0] neg_hi:[0,1,0]
	v_pk_fma_f32 v[116:117], v[102:103], v[132:133], v[116:117] op_sel_hi:[0,1,1] neg_lo:[0,1,0] neg_hi:[0,1,0]
	v_pk_fma_f32 v[114:115], v[100:101], v[132:133], v[114:115] op_sel:[1,0,0] neg_lo:[0,1,0] neg_hi:[0,1,0]
	v_pk_fma_f32 v[112:113], v[100:101], v[132:133], v[112:113] op_sel_hi:[0,1,1] neg_lo:[0,1,0] neg_hi:[0,1,0]
	ds_read_b128 v[76:79], v134 offset:26368
	s_waitcnt lgkmcnt(4)
; template <int RPL, int NSW>
; __device__ __forceinline__ void scan_item(const P& p, LAS unsigned char* lds, int seqbase, int L, int head, int dir, int part, int step0, int nsteps, int mode, float* qc, float* smid) {
;     ...
;             for (int s = 0; s < TC; ++s) {
;                 const f32x2 w0 = {xw[0], xw[1]}, w1 = {xw[2], xw[3]}, kd0 = {xkd[0], xkd[1]}, kd1 = {xkd[2], xkd[3]}, kk0 = {xkk[0], xkk[1]}, kk1 = {xkk[2], xkk[3]},
;                             b0 = {xb[0], xb[1]}, b1 = {xb[2], xb[3]}, r0 = {xr[0], xr[1]}, r1 = {xr[2], xr[3]};
;                 float vr[RPL];
; #pragma unroll
;                 for (int q = 0; q < RPL; ++q) vr[q] = vrow[q];
;                 { const int sn = (s + 1 < TC) ? s + 1 : s; SCAN_LD(sn); }
;                 float sa[RPL];
; #pragma unroll
;                 for (int q = 0; q < RPL; ++q) { const f32x2 t = S[q][0] * kk0 + S[q][1] * kk1; sa[q] = t.x + t.y; }
;                 if (RPL == 2) {
;                     sa[0] += dppx<0xB1>(sa[0]); sa[RPL - 1] += dppx<0xB1>(sa[RPL - 1]); sa[0] += dppx<0x4E>(sa[0]); sa[RPL - 1] += dppx<0x4E>(sa[RPL - 1]);
;                     sa[0] += dppx<0x141>(sa[0]); sa[RPL - 1] += dppx<0x141>(sa[RPL - 1]); sa[0] += dppx<0x140>(sa[0]); sa[RPL - 1] += dppx<0x140>(sa[RPL - 1]);
;                 } else {
; #pragma unroll
;                     for (int q = 0; q < RPL; ++q) sa[q] = reduce16(sa[q]);
;                 }
;                 float ov[RPL];
;                 if (RPL == 2) {
;                     const f32x2 vva = {vr[0], vr[0]}, nsa = {-sa[0], -sa[0]}, vvb = {vr[RPL - 1], vr[RPL - 1]}, nsb = {-sa[RPL - 1], -sa[RPL - 1]};
;                     f32x2 a0 = nsa * b0, c0 = nsb * b0, a1 = nsa * b1, c1 = nsb * b1;
;                     a0 = vva * kd0 + a0; c0 = vvb * kd0 + c0; a1 = vva * kd1 + a1; c1 = vvb * kd1 + c1;
;                     S[0][0] = S[0][0] * w0 + a0; S[RPL - 1][0] = S[RPL - 1][0] * w0 + c0; S[0][1] = S[0][1] * w1 + a1; S[RPL - 1][1] = S[RPL - 1][1] * w1 + c1;
;                     f32x2 ua = S[0][0] * r0, ub = S[RPL - 1][0] * r0;
;                     ua = S[0][1] * r1 + ua; ub = S[RPL - 1][1] * r1 + ub;
;                     ov[0] = ua.x + ua.y; ov[RPL - 1] = ub.x + ub.y;
;                 } else {
; #pragma unroll
;                 for (int q = 0; q < RPL; ++q) {
;                     const f32x2 vv = {vr[q], vr[q]}, ns = {-sa[q], -sa[q]};
	v_pk_mul_f32 v[128:129], v[118:119], v[18:19] op_sel:[0,1]
	v_pk_mul_f32 v[130:131], v[118:119], v[106:107] op_sel:[0,1]
	v_pk_fma_f32 v[128:129], v[116:117], v[18:19], v[128:129] op_sel_hi:[1,0,1]
	v_pk_fma_f32 v[130:131], v[116:117], v[106:107], v[130:131] op_sel_hi:[1,0,1]
	ds_read_b128 v[80:83], v134 offset:34560
	v_pk_fma_f32 v[128:129], v[114:115], v[16:17], v[128:129] op_sel:[0,1,0]
	v_pk_fma_f32 v[130:131], v[114:115], v[104:105], v[130:131] op_sel:[0,1,0]
	v_pk_fma_f32 v[128:129], v[112:113], v[16:17], v[128:129] op_sel_hi:[1,0,1]
	v_pk_fma_f32 v[130:131], v[112:113], v[104:105], v[130:131] op_sel_hi:[1,0,1]
	ds_read_b128 v[72:75], v134 offset:18176
	v_add_f32_dpp v128, v128, v128 quad_perm:[1,0,3,2] row_mask:0xf bank_mask:0xf bound_ctrl:1
	v_add_f32_dpp v129, v129, v129 quad_perm:[1,0,3,2] row_mask:0xf bank_mask:0xf bound_ctrl:1
	v_add_f32_dpp v130, v130, v130 quad_perm:[1,0,3,2] row_mask:0xf bank_mask:0xf bound_ctrl:1
	v_add_f32_dpp v131, v131, v131 quad_perm:[1,0,3,2] row_mask:0xf bank_mask:0xf bound_ctrl:1
	ds_read_b128 v[68:71], v134 offset:9984
	v_add_f32_dpp v128, v128, v128 quad_perm:[2,3,0,1] row_mask:0xf bank_mask:0xf bound_ctrl:1
	v_add_f32_dpp v129, v129, v129 quad_perm:[2,3,0,1] row_mask:0xf bank_mask:0xf bound_ctrl:1
	v_add_f32_dpp v130, v130, v130 quad_perm:[2,3,0,1] row_mask:0xf bank_mask:0xf bound_ctrl:1
	v_add_f32_dpp v131, v131, v131 quad_perm:[2,3,0,1] row_mask:0xf bank_mask:0xf bound_ctrl:1
	s_waitcnt lgkmcnt(4)
	v_pk_mul_f32 v[126:127], v[160:161], v[14:15] op_sel:[0,1]
	v_pk_mul_f32 v[124:125], v[160:161], v[14:15] op_sel_hi:[1,0]
	ds_read_b128 v[64:67], v134 offset:1792
	v_add_f32_dpp v128, v128, v128 row_half_mirror row_mask:0xf bank_mask:0xf bound_ctrl:1
	v_add_f32_dpp v129, v129, v129 row_half_mirror row_mask:0xf bank_mask:0xf bound_ctrl:1
	ds_write2_b32 v138, v130, v131 offset0:128 offset1:132
	v_pk_mul_f32 v[122:123], v[160:161], v[12:13] op_sel:[0,1]
	v_add_f32_dpp v132, v128, v128 row_mirror row_mask:0xf bank_mask:0xf bound_ctrl:1
	v_add_f32_dpp v133, v129, v129 row_mirror row_mask:0xf bank_mask:0xf bound_ctrl:1
	v_pk_mul_f32 v[120:121], v[160:161], v[12:13] op_sel_hi:[1,0]
	v_pk_fma_f32 v[118:119], v[118:119], v[10:11], v[126:127] op_sel:[0,1,0]
	v_pk_fma_f32 v[116:117], v[116:117], v[10:11], v[124:125] op_sel_hi:[1,0,1]
	v_pk_fma_f32 v[114:115], v[114:115], v[8:9], v[122:123] op_sel:[0,1,0]
	v_pk_fma_f32 v[112:113], v[112:113], v[8:9], v[120:121] op_sel_hi:[1,0,1]
	v_pk_fma_f32 v[118:119], v[22:23], v[132:133], v[118:119] op_sel:[1,0,0] neg_lo:[0,1,0] neg_hi:[0,1,0]
	v_pk_fma_f32 v[116:117], v[22:23], v[132:133], v[116:117] op_sel_hi:[0,1,1] neg_lo:[0,1,0] neg_hi:[0,1,0]
	v_pk_fma_f32 v[114:115], v[20:21], v[132:133], v[114:115] op_sel:[1,0,0] neg_lo:[0,1,0] neg_hi:[0,1,0]
	v_pk_fma_f32 v[112:113], v[20:21], v[132:133], v[112:113] op_sel_hi:[0,1,1] neg_lo:[0,1,0] neg_hi:[0,1,0]
	ds_read_b128 v[100:103], v134 offset:26624
	s_waitcnt lgkmcnt(4)
	v_pk_mul_f32 v[128:129], v[118:119], v[74:75] op_sel:[0,1]
	v_pk_mul_f32 v[130:131], v[118:119], v[26:27] op_sel:[0,1]
	v_pk_fma_f32 v[128:129], v[116:117], v[74:75], v[128:129] op_sel_hi:[1,0,1]
	v_pk_fma_f32 v[130:131], v[116:117], v[26:27], v[130:131] op_sel_hi:[1,0,1]
	ds_read_b128 v[104:107], v134 offset:34816
	v_pk_fma_f32 v[128:129], v[114:115], v[72:73], v[128:129] op_sel:[0,1,0]
	v_pk_fma_f32 v[130:131], v[114:115], v[24:25], v[130:131] op_sel:[0,1,0]
	v_pk_fma_f32 v[128:129], v[112:113], v[72:73], v[128:129] op_sel_hi:[1,0,1]
	v_pk_fma_f32 v[130:131], v[112:113], v[24:25], v[130:131] op_sel_hi:[1,0,1]
	ds_read_b128 v[96:99], v134 offset:18432
	v_add_f32_dpp v128, v128, v128 quad_perm:[1,0,3,2] row_mask:0xf bank_mask:0xf bound_ctrl:1
	v_add_f32_dpp v129, v129, v129 quad_perm:[1,0,3,2] row_mask:0xf bank_mask:0xf bound_ctrl:1
	v_add_f32_dpp v130, v130, v130 quad_perm:[1,0,3,2] row_mask:0xf bank_mask:0xf bound_ctrl:1
	v_add_f32_dpp v131, v131, v131 quad_perm:[1,0,3,2] row_mask:0xf bank_mask:0xf bound_ctrl:1
	ds_read_b128 v[92:95], v134 offset:10240
	v_add_f32_dpp v128, v128, v128 quad_perm:[2,3,0,1] row_mask:0xf bank_mask:0xf bound_ctrl:1
	v_add_f32_dpp v129, v129, v129 quad_perm:[2,3,0,1] row_mask:0xf bank_mask:0xf bound_ctrl:1
	v_add_f32_dpp v130, v130, v130 quad_perm:[2,3,0,1] row_mask:0xf bank_mask:0xf bound_ctrl:1
	v_add_f32_dpp v131, v131, v131 quad_perm:[2,3,0,1] row_mask:0xf bank_mask:0xf bound_ctrl:1
	s_waitcnt lgkmcnt(4)
	v_pk_mul_f32 v[126:127], v[162:163], v[70:71] op_sel:[0,1]
	v_pk_mul_f32 v[124:125], v[162:163], v[70:71] op_sel_hi:[1,0]
	ds_read2_b64 v[156:159], v110 offset0:128 offset1:144
	v_add_f32_dpp v128, v128, v128 row_half_mirror row_mask:0xf bank_mask:0xf bound_ctrl:1
	v_add_f32_dpp v129, v129, v129 row_half_mirror row_mask:0xf bank_mask:0xf bound_ctrl:1
	ds_write2_b32 v139, v130, v131 offset0:0 offset1:4
	v_pk_mul_f32 v[122:123], v[162:163], v[68:69] op_sel:[0,1]
	v_add_f32_dpp v132, v128, v128 row_mirror row_mask:0xf bank_mask:0xf bound_ctrl:1
	v_add_f32_dpp v133, v129, v129 row_mirror row_mask:0xf bank_mask:0xf bound_ctrl:1
	v_pk_mul_f32 v[120:121], v[162:163], v[68:69] op_sel_hi:[1,0]
	ds_read_b128 v[88:91], v134 offset:2048
	v_pk_fma_f32 v[118:119], v[118:119], v[66:67], v[126:127] op_sel:[0,1,0]
	v_pk_fma_f32 v[116:117], v[116:117], v[66:67], v[124:125] op_sel_hi:[1,0,1]
	v_pk_fma_f32 v[114:115], v[114:115], v[64:65], v[122:123] op_sel:[0,1,0]
	v_pk_fma_f32 v[112:113], v[112:113], v[64:65], v[120:121] op_sel_hi:[1,0,1]
	v_pk_fma_f32 v[118:119], v[78:79], v[132:133], v[118:119] op_sel:[1,0,0] neg_lo:[0,1,0] neg_hi:[0,1,0]
	v_pk_fma_f32 v[116:117], v[78:79], v[132:133], v[116:117] op_sel_hi:[0,1,1] neg_lo:[0,1,0] neg_hi:[0,1,0]
	v_pk_fma_f32 v[114:115], v[76:77], v[132:133], v[114:115] op_sel:[1,0,0] neg_lo:[0,1,0] neg_hi:[0,1,0]
	v_pk_fma_f32 v[112:113], v[76:77], v[132:133], v[112:113] op_sel_hi:[0,1,1] neg_lo:[0,1,0] neg_hi:[0,1,0]
	ds_read_b128 v[20:23], v134 offset:26880
	s_waitcnt lgkmcnt(4)
; template <int RPL, int NSW>
; __device__ __forceinline__ void scan_item(const P& p, LAS unsigned char* lds, int seqbase, int L, int head, int dir, int part, int step0, int nsteps, int mode, float* qc, float* smid) {
;     ...
;             for (int s = 0; s < TC; ++s) {
;                 const f32x2 w0 = {xw[0], xw[1]}, w1 = {xw[2], xw[3]}, kd0 = {xkd[0], xkd[1]}, kd1 = {xkd[2], xkd[3]}, kk0 = {xkk[0], xkk[1]}, kk1 = {xkk[2], xkk[3]},
;                             b0 = {xb[0], xb[1]}, b1 = {xb[2], xb[3]}, r0 = {xr[0], xr[1]}, r1 = {xr[2], xr[3]};
;                 float vr[RPL];
; #pragma unroll
;                 for (int q = 0; q < RPL; ++q) vr[q] = vrow[q];
;                 { const int sn = (s + 1 < TC) ? s + 1 : s; SCAN_LD(sn); }
;                 float sa[RPL];
; #pragma unroll
;                 for (int q = 0; q < RPL; ++q) { const f32x2 t = S[q][0] * kk0 + S[q][1] * kk1; sa[q] = t.x + t.y; }
;                 if (RPL == 2) {
;                     sa[0] += dppx<0xB1>(sa[0]); sa[RPL - 1] += dppx<0xB1>(sa[RPL - 1]); sa[0] += dppx<0x4E>(sa[0]); sa[RPL - 1] += dppx<0x4E>(sa[RPL - 1]);
;                     sa[0] += dppx<0x141>(sa[0]); sa[RPL - 1] += dppx<0x141>(sa[RPL - 1]); sa[0] += dppx<0x140>(sa[0]); sa[RPL - 1] += dppx<0x140>(sa[RPL - 1]);
;                 } else {
; #pragma unroll
;                     for (int q = 0; q < RPL; ++q) sa[q] = reduce16(sa[q]);
;                 }
;                 float ov[RPL];
;                 if (RPL == 2) {
;                     const f32x2 vva = {vr[0], vr[0]}, nsa = {-sa[0], -sa[0]}, vvb = {vr[RPL - 1], vr[RPL - 1]}, nsb = {-sa[RPL - 1], -sa[RPL - 1]};
;                     f32x2 a0 = nsa * b0, c0 = nsb * b0, a1 = nsa * b1, c1 = nsb * b1;
;                     a0 = vva * kd0 + a0; c0 = vvb * kd0 + c0; a1 = vva * kd1 + a1; c1 = vvb * kd1 + c1;
;                     S[0][0] = S[0][0] * w0 + a0; S[RPL - 1][0] = S[RPL - 1][0] * w0 + c0; S[0][1] = S[0][1] * w1 + a1; S[RPL - 1][1] = S[RPL - 1][1] * w1 + c1;
;                     f32x2 ua = S[0][0] * r0, ub = S[RPL - 1][0] * r0;
;                     ua = S[0][1] * r1 + ua; ub = S[RPL - 1][1] * r1 + ub;
;                     ov[0] = ua.x + ua.y; ov[RPL - 1] = ub.x + ub.y;
;                 } else {
; #pragma unroll
;                 for (int q = 0; q < RPL; ++q) {
;                     const f32x2 vv = {vr[q], vr[q]}, ns = {-sa[q], -sa[q]};
	v_pk_mul_f32 v[128:129], v[118:119], v[98:99] op_sel:[0,1]
	v_pk_mul_f32 v[130:131], v[118:119], v[82:83] op_sel:[0,1]
	v_pk_fma_f32 v[128:129], v[116:117], v[98:99], v[128:129] op_sel_hi:[1,0,1]
	v_pk_fma_f32 v[130:131], v[116:117], v[82:83], v[130:131] op_sel_hi:[1,0,1]
	ds_read_b128 v[24:27], v134 offset:35072
	v_pk_fma_f32 v[128:129], v[114:115], v[96:97], v[128:129] op_sel:[0,1,0]
	v_pk_fma_f32 v[130:131], v[114:115], v[80:81], v[130:131] op_sel:[0,1,0]
	v_pk_fma_f32 v[128:129], v[112:113], v[96:97], v[128:129] op_sel_hi:[1,0,1]
	v_pk_fma_f32 v[130:131], v[112:113], v[80:81], v[130:131] op_sel_hi:[1,0,1]
	ds_read_b128 v[16:19], v134 offset:18688
	v_add_f32_dpp v128, v128, v128 quad_perm:[1,0,3,2] row_mask:0xf bank_mask:0xf bound_ctrl:1
	v_add_f32_dpp v129, v129, v129 quad_perm:[1,0,3,2] row_mask:0xf bank_mask:0xf bound_ctrl:1
	v_add_f32_dpp v130, v130, v130 quad_perm:[1,0,3,2] row_mask:0xf bank_mask:0xf bound_ctrl:1
	v_add_f32_dpp v131, v131, v131 quad_perm:[1,0,3,2] row_mask:0xf bank_mask:0xf bound_ctrl:1
	ds_read_b128 v[12:15], v134 offset:10496
	v_add_f32_dpp v128, v128, v128 quad_perm:[2,3,0,1] row_mask:0xf bank_mask:0xf bound_ctrl:1
	v_add_f32_dpp v129, v129, v129 quad_perm:[2,3,0,1] row_mask:0xf bank_mask:0xf bound_ctrl:1
	v_add_f32_dpp v130, v130, v130 quad_perm:[2,3,0,1] row_mask:0xf bank_mask:0xf bound_ctrl:1
	v_add_f32_dpp v131, v131, v131 quad_perm:[2,3,0,1] row_mask:0xf bank_mask:0xf bound_ctrl:1
	s_waitcnt lgkmcnt(4)
	v_pk_mul_f32 v[126:127], v[156:157], v[94:95] op_sel:[0,1]
	v_pk_mul_f32 v[124:125], v[156:157], v[94:95] op_sel_hi:[1,0]
	ds_read_b128 v[8:11], v134 offset:2304
	v_add_f32_dpp v128, v128, v128 row_half_mirror row_mask:0xf bank_mask:0xf bound_ctrl:1
	v_add_f32_dpp v129, v129, v129 row_half_mirror row_mask:0xf bank_mask:0xf bound_ctrl:1
	ds_write2_b32 v139, v130, v131 offset0:128 offset1:132
	v_pk_mul_f32 v[122:123], v[156:157], v[92:93] op_sel:[0,1]
	v_add_f32_dpp v132, v128, v128 row_mirror row_mask:0xf bank_mask:0xf bound_ctrl:1
	v_add_f32_dpp v133, v129, v129 row_mirror row_mask:0xf bank_mask:0xf bound_ctrl:1
	v_pk_mul_f32 v[120:121], v[156:157], v[92:93] op_sel_hi:[1,0]
	v_pk_fma_f32 v[118:119], v[118:119], v[90:91], v[126:127] op_sel:[0,1,0]
	v_pk_fma_f32 v[116:117], v[116:117], v[90:91], v[124:125] op_sel_hi:[1,0,1]
	v_pk_fma_f32 v[114:115], v[114:115], v[88:89], v[122:123] op_sel:[0,1,0]
	v_pk_fma_f32 v[112:113], v[112:113], v[88:89], v[120:121] op_sel_hi:[1,0,1]
	v_pk_fma_f32 v[118:119], v[102:103], v[132:133], v[118:119] op_sel:[1,0,0] neg_lo:[0,1,0] neg_hi:[0,1,0]
	v_pk_fma_f32 v[116:117], v[102:103], v[132:133], v[116:117] op_sel_hi:[0,1,1] neg_lo:[0,1,0] neg_hi:[0,1,0]
	v_pk_fma_f32 v[114:115], v[100:101], v[132:133], v[114:115] op_sel:[1,0,0] neg_lo:[0,1,0] neg_hi:[0,1,0]
	v_pk_fma_f32 v[112:113], v[100:101], v[132:133], v[112:113] op_sel_hi:[0,1,1] neg_lo:[0,1,0] neg_hi:[0,1,0]
	ds_read_b128 v[76:79], v134 offset:27136
	s_waitcnt lgkmcnt(4)
	v_pk_mul_f32 v[128:129], v[118:119], v[18:19] op_sel:[0,1]
	v_pk_mul_f32 v[130:131], v[118:119], v[106:107] op_sel:[0,1]
	v_pk_fma_f32 v[128:129], v[116:117], v[18:19], v[128:129] op_sel_hi:[1,0,1]
	v_pk_fma_f32 v[130:131], v[116:117], v[106:107], v[130:131] op_sel_hi:[1,0,1]
	ds_read_b128 v[80:83], v134 offset:35328
	v_pk_fma_f32 v[128:129], v[114:115], v[16:17], v[128:129] op_sel:[0,1,0]
	v_pk_fma_f32 v[130:131], v[114:115], v[104:105], v[130:131] op_sel:[0,1,0]
	v_pk_fma_f32 v[128:129], v[112:113], v[16:17], v[128:129] op_sel_hi:[1,0,1]
	v_pk_fma_f32 v[130:131], v[112:113], v[104:105], v[130:131] op_sel_hi:[1,0,1]
	ds_read_b128 v[72:75], v134 offset:18944
	v_add_f32_dpp v128, v128, v128 quad_perm:[1,0,3,2] row_mask:0xf bank_mask:0xf bound_ctrl:1
	v_add_f32_dpp v129, v129, v129 quad_perm:[1,0,3,2] row_mask:0xf bank_mask:0xf bound_ctrl:1
	v_add_f32_dpp v130, v130, v130 quad_perm:[1,0,3,2] row_mask:0xf bank_mask:0xf bound_ctrl:1
	v_add_f32_dpp v131, v131, v131 quad_perm:[1,0,3,2] row_mask:0xf bank_mask:0xf bound_ctrl:1
	ds_read_b128 v[68:71], v134 offset:10752
	v_add_f32_dpp v128, v128, v128 quad_perm:[2,3,0,1] row_mask:0xf bank_mask:0xf bound_ctrl:1
	v_add_f32_dpp v129, v129, v129 quad_perm:[2,3,0,1] row_mask:0xf bank_mask:0xf bound_ctrl:1
	v_add_f32_dpp v130, v130, v130 quad_perm:[2,3,0,1] row_mask:0xf bank_mask:0xf bound_ctrl:1
	v_add_f32_dpp v131, v131, v131 quad_perm:[2,3,0,1] row_mask:0xf bank_mask:0xf bound_ctrl:1
	s_waitcnt lgkmcnt(4)
	v_pk_mul_f32 v[126:127], v[158:159], v[14:15] op_sel:[0,1]
	v_pk_mul_f32 v[124:125], v[158:159], v[14:15] op_sel_hi:[1,0]
	ds_read2_b64 v[160:163], v110 offset0:160 offset1:176
	v_add_f32_dpp v128, v128, v128 row_half_mirror row_mask:0xf bank_mask:0xf bound_ctrl:1
	v_add_f32_dpp v129, v129, v129 row_half_mirror row_mask:0xf bank_mask:0xf bound_ctrl:1
	ds_write2_b32 v140, v130, v131 offset0:0 offset1:4
	v_pk_mul_f32 v[122:123], v[158:159], v[12:13] op_sel:[0,1]
	v_add_f32_dpp v132, v128, v128 row_mirror row_mask:0xf bank_mask:0xf bound_ctrl:1
	v_add_f32_dpp v133, v129, v129 row_mirror row_mask:0xf bank_mask:0xf bound_ctrl:1
	v_pk_mul_f32 v[120:121], v[158:159], v[12:13] op_sel_hi:[1,0]
	ds_read_b128 v[64:67], v134 offset:2560
	v_pk_fma_f32 v[118:119], v[118:119], v[10:11], v[126:127] op_sel:[0,1,0]
	v_pk_fma_f32 v[116:117], v[116:117], v[10:11], v[124:125] op_sel_hi:[1,0,1]
	v_pk_fma_f32 v[114:115], v[114:115], v[8:9], v[122:123] op_sel:[0,1,0]
	v_pk_fma_f32 v[112:113], v[112:113], v[8:9], v[120:121] op_sel_hi:[1,0,1]
	v_pk_fma_f32 v[118:119], v[22:23], v[132:133], v[118:119] op_sel:[1,0,0] neg_lo:[0,1,0] neg_hi:[0,1,0]
	v_pk_fma_f32 v[116:117], v[22:23], v[132:133], v[116:117] op_sel_hi:[0,1,1] neg_lo:[0,1,0] neg_hi:[0,1,0]
	v_pk_fma_f32 v[114:115], v[20:21], v[132:133], v[114:115] op_sel:[1,0,0] neg_lo:[0,1,0] neg_hi:[0,1,0]
	v_pk_fma_f32 v[112:113], v[20:21], v[132:133], v[112:113] op_sel_hi:[0,1,1] neg_lo:[0,1,0] neg_hi:[0,1,0]
	ds_read_b128 v[100:103], v134 offset:27392
	s_waitcnt lgkmcnt(4)
; template <int RPL, int NSW>
; __device__ __forceinline__ void scan_item(const P& p, LAS unsigned char* lds, int seqbase, int L, int head, int dir, int part, int step0, int nsteps, int mode, float* qc, float* smid) {
;     ...
;             for (int s = 0; s < TC; ++s) {
;                 const f32x2 w0 = {xw[0], xw[1]}, w1 = {xw[2], xw[3]}, kd0 = {xkd[0], xkd[1]}, kd1 = {xkd[2], xkd[3]}, kk0 = {xkk[0], xkk[1]}, kk1 = {xkk[2], xkk[3]},
;                             b0 = {xb[0], xb[1]}, b1 = {xb[2], xb[3]}, r0 = {xr[0], xr[1]}, r1 = {xr[2], xr[3]};
;                 float vr[RPL];
; #pragma unroll
;                 for (int q = 0; q < RPL; ++q) vr[q] = vrow[q];
;                 { const int sn = (s + 1 < TC) ? s + 1 : s; SCAN_LD(sn); }
;                 float sa[RPL];
; #pragma unroll
;                 for (int q = 0; q < RPL; ++q) { const f32x2 t = S[q][0] * kk0 + S[q][1] * kk1; sa[q] = t.x + t.y; }
;                 if (RPL == 2) {
;                     sa[0] += dppx<0xB1>(sa[0]); sa[RPL - 1] += dppx<0xB1>(sa[RPL - 1]); sa[0] += dppx<0x4E>(sa[0]); sa[RPL - 1] += dppx<0x4E>(sa[RPL - 1]);
;                     sa[0] += dppx<0x141>(sa[0]); sa[RPL - 1] += dppx<0x141>(sa[RPL - 1]); sa[0] += dppx<0x140>(sa[0]); sa[RPL - 1] += dppx<0x140>(sa[RPL - 1]);
;                 } else {
; #pragma unroll
;                     for (int q = 0; q < RPL; ++q) sa[q] = reduce16(sa[q]);
;                 }
;                 float ov[RPL];
;                 if (RPL == 2) {
;                     const f32x2 vva = {vr[0], vr[0]}, nsa = {-sa[0], -sa[0]}, vvb = {vr[RPL - 1], vr[RPL - 1]}, nsb = {-sa[RPL - 1], -sa[RPL - 1]};
;                     f32x2 a0 = nsa * b0, c0 = nsb * b0, a1 = nsa * b1, c1 = nsb * b1;
;                     a0 = vva * kd0 + a0; c0 = vvb * kd0 + c0; a1 = vva * kd1 + a1; c1 = vvb * kd1 + c1;
;                     S[0][0] = S[0][0] * w0 + a0; S[RPL - 1][0] = S[RPL - 1][0] * w0 + c0; S[0][1] = S[0][1] * w1 + a1; S[RPL - 1][1] = S[RPL - 1][1] * w1 + c1;
;                     f32x2 ua = S[0][0] * r0, ub = S[RPL - 1][0] * r0;
;                     ua = S[0][1] * r1 + ua; ub = S[RPL - 1][1] * r1 + ub;
;                     ov[0] = ua.x + ua.y; ov[RPL - 1] = ub.x + ub.y;
;                 } else {
; #pragma unroll
;                 for (int q = 0; q < RPL; ++q) {
;                     const f32x2 vv = {vr[q], vr[q]}, ns = {-sa[q], -sa[q]};
	v_pk_mul_f32 v[128:129], v[118:119], v[74:75] op_sel:[0,1]
	v_pk_mul_f32 v[130:131], v[118:119], v[26:27] op_sel:[0,1]
	v_pk_fma_f32 v[128:129], v[116:117], v[74:75], v[128:129] op_sel_hi:[1,0,1]
	v_pk_fma_f32 v[130:131], v[116:117], v[26:27], v[130:131] op_sel_hi:[1,0,1]
	ds_read_b128 v[104:107], v134 offset:35584
	v_pk_fma_f32 v[128:129], v[114:115], v[72:73], v[128:129] op_sel:[0,1,0]
	v_pk_fma_f32 v[130:131], v[114:115], v[24:25], v[130:131] op_sel:[0,1,0]
	v_pk_fma_f32 v[128:129], v[112:113], v[72:73], v[128:129] op_sel_hi:[1,0,1]
	v_pk_fma_f32 v[130:131], v[112:113], v[24:25], v[130:131] op_sel_hi:[1,0,1]
	ds_read_b128 v[96:99], v134 offset:19200
	v_add_f32_dpp v128, v128, v128 quad_perm:[1,0,3,2] row_mask:0xf bank_mask:0xf bound_ctrl:1
	v_add_f32_dpp v129, v129, v129 quad_perm:[1,0,3,2] row_mask:0xf bank_mask:0xf bound_ctrl:1
	v_add_f32_dpp v130, v130, v130 quad_perm:[1,0,3,2] row_mask:0xf bank_mask:0xf bound_ctrl:1
	v_add_f32_dpp v131, v131, v131 quad_perm:[1,0,3,2] row_mask:0xf bank_mask:0xf bound_ctrl:1
	ds_read_b128 v[92:95], v134 offset:11008
	v_add_f32_dpp v128, v128, v128 quad_perm:[2,3,0,1] row_mask:0xf bank_mask:0xf bound_ctrl:1
	v_add_f32_dpp v129, v129, v129 quad_perm:[2,3,0,1] row_mask:0xf bank_mask:0xf bound_ctrl:1
	v_add_f32_dpp v130, v130, v130 quad_perm:[2,3,0,1] row_mask:0xf bank_mask:0xf bound_ctrl:1
	v_add_f32_dpp v131, v131, v131 quad_perm:[2,3,0,1] row_mask:0xf bank_mask:0xf bound_ctrl:1
	s_waitcnt lgkmcnt(4)
	v_pk_mul_f32 v[126:127], v[160:161], v[70:71] op_sel:[0,1]
	v_pk_mul_f32 v[124:125], v[160:161], v[70:71] op_sel_hi:[1,0]
	ds_read_b128 v[88:91], v134 offset:2816
	v_add_f32_dpp v128, v128, v128 row_half_mirror row_mask:0xf bank_mask:0xf bound_ctrl:1
	v_add_f32_dpp v129, v129, v129 row_half_mirror row_mask:0xf bank_mask:0xf bound_ctrl:1
	ds_write2_b32 v140, v130, v131 offset0:128 offset1:132
	v_pk_mul_f32 v[122:123], v[160:161], v[68:69] op_sel:[0,1]
	v_add_f32_dpp v132, v128, v128 row_mirror row_mask:0xf bank_mask:0xf bound_ctrl:1
	v_add_f32_dpp v133, v129, v129 row_mirror row_mask:0xf bank_mask:0xf bound_ctrl:1
	v_pk_mul_f32 v[120:121], v[160:161], v[68:69] op_sel_hi:[1,0]
	v_pk_fma_f32 v[118:119], v[118:119], v[66:67], v[126:127] op_sel:[0,1,0]
	v_pk_fma_f32 v[116:117], v[116:117], v[66:67], v[124:125] op_sel_hi:[1,0,1]
	v_pk_fma_f32 v[114:115], v[114:115], v[64:65], v[122:123] op_sel:[0,1,0]
	v_pk_fma_f32 v[112:113], v[112:113], v[64:65], v[120:121] op_sel_hi:[1,0,1]
	v_pk_fma_f32 v[118:119], v[78:79], v[132:133], v[118:119] op_sel:[1,0,0] neg_lo:[0,1,0] neg_hi:[0,1,0]
	v_pk_fma_f32 v[116:117], v[78:79], v[132:133], v[116:117] op_sel_hi:[0,1,1] neg_lo:[0,1,0] neg_hi:[0,1,0]
	v_pk_fma_f32 v[114:115], v[76:77], v[132:133], v[114:115] op_sel:[1,0,0] neg_lo:[0,1,0] neg_hi:[0,1,0]
	v_pk_fma_f32 v[112:113], v[76:77], v[132:133], v[112:113] op_sel_hi:[0,1,1] neg_lo:[0,1,0] neg_hi:[0,1,0]
	ds_read_b128 v[20:23], v134 offset:27648
	s_waitcnt lgkmcnt(4)
	v_pk_mul_f32 v[128:129], v[118:119], v[98:99] op_sel:[0,1]
	v_pk_mul_f32 v[130:131], v[118:119], v[82:83] op_sel:[0,1]
	v_pk_fma_f32 v[128:129], v[116:117], v[98:99], v[128:129] op_sel_hi:[1,0,1]
	v_pk_fma_f32 v[130:131], v[116:117], v[82:83], v[130:131] op_sel_hi:[1,0,1]
	ds_read_b128 v[24:27], v134 offset:35840
	v_pk_fma_f32 v[128:129], v[114:115], v[96:97], v[128:129] op_sel:[0,1,0]
	v_pk_fma_f32 v[130:131], v[114:115], v[80:81], v[130:131] op_sel:[0,1,0]
	v_pk_fma_f32 v[128:129], v[112:113], v[96:97], v[128:129] op_sel_hi:[1,0,1]
	v_pk_fma_f32 v[130:131], v[112:113], v[80:81], v[130:131] op_sel_hi:[1,0,1]
	ds_read_b128 v[16:19], v134 offset:19456
	v_add_f32_dpp v128, v128, v128 quad_perm:[1,0,3,2] row_mask:0xf bank_mask:0xf bound_ctrl:1
	v_add_f32_dpp v129, v129, v129 quad_perm:[1,0,3,2] row_mask:0xf bank_mask:0xf bound_ctrl:1
	v_add_f32_dpp v130, v130, v130 quad_perm:[1,0,3,2] row_mask:0xf bank_mask:0xf bound_ctrl:1
	v_add_f32_dpp v131, v131, v131 quad_perm:[1,0,3,2] row_mask:0xf bank_mask:0xf bound_ctrl:1
	ds_read_b128 v[12:15], v134 offset:11264
	v_add_f32_dpp v128, v128, v128 quad_perm:[2,3,0,1] row_mask:0xf bank_mask:0xf bound_ctrl:1
	v_add_f32_dpp v129, v129, v129 quad_perm:[2,3,0,1] row_mask:0xf bank_mask:0xf bound_ctrl:1
	v_add_f32_dpp v130, v130, v130 quad_perm:[2,3,0,1] row_mask:0xf bank_mask:0xf bound_ctrl:1
	v_add_f32_dpp v131, v131, v131 quad_perm:[2,3,0,1] row_mask:0xf bank_mask:0xf bound_ctrl:1
	s_waitcnt lgkmcnt(4)
	v_pk_mul_f32 v[126:127], v[162:163], v[94:95] op_sel:[0,1]
	v_pk_mul_f32 v[124:125], v[162:163], v[94:95] op_sel_hi:[1,0]
	ds_read2_b64 v[156:159], v110 offset0:192 offset1:208
	v_add_f32_dpp v128, v128, v128 row_half_mirror row_mask:0xf bank_mask:0xf bound_ctrl:1
	v_add_f32_dpp v129, v129, v129 row_half_mirror row_mask:0xf bank_mask:0xf bound_ctrl:1
	ds_write2_b32 v141, v130, v131 offset0:0 offset1:4
	v_pk_mul_f32 v[122:123], v[162:163], v[92:93] op_sel:[0,1]
	v_add_f32_dpp v132, v128, v128 row_mirror row_mask:0xf bank_mask:0xf bound_ctrl:1
	v_add_f32_dpp v133, v129, v129 row_mirror row_mask:0xf bank_mask:0xf bound_ctrl:1
	v_pk_mul_f32 v[120:121], v[162:163], v[92:93] op_sel_hi:[1,0]
	ds_read_b128 v[8:11], v134 offset:3072
	v_pk_fma_f32 v[118:119], v[118:119], v[90:91], v[126:127] op_sel:[0,1,0]
	v_pk_fma_f32 v[116:117], v[116:117], v[90:91], v[124:125] op_sel_hi:[1,0,1]
	v_pk_fma_f32 v[114:115], v[114:115], v[88:89], v[122:123] op_sel:[0,1,0]
	v_pk_fma_f32 v[112:113], v[112:113], v[88:89], v[120:121] op_sel_hi:[1,0,1]
	v_pk_fma_f32 v[118:119], v[102:103], v[132:133], v[118:119] op_sel:[1,0,0] neg_lo:[0,1,0] neg_hi:[0,1,0]
	v_pk_fma_f32 v[116:117], v[102:103], v[132:133], v[116:117] op_sel_hi:[0,1,1] neg_lo:[0,1,0] neg_hi:[0,1,0]
	v_pk_fma_f32 v[114:115], v[100:101], v[132:133], v[114:115] op_sel:[1,0,0] neg_lo:[0,1,0] neg_hi:[0,1,0]
	v_pk_fma_f32 v[112:113], v[100:101], v[132:133], v[112:113] op_sel_hi:[0,1,1] neg_lo:[0,1,0] neg_hi:[0,1,0]
	ds_read_b128 v[76:79], v134 offset:27904
	s_waitcnt lgkmcnt(4)
; template <int RPL, int NSW>
; __device__ __forceinline__ void scan_item(const P& p, LAS unsigned char* lds, int seqbase, int L, int head, int dir, int part, int step0, int nsteps, int mode, float* qc, float* smid) {
;     ...
;             for (int s = 0; s < TC; ++s) {
;                 const f32x2 w0 = {xw[0], xw[1]}, w1 = {xw[2], xw[3]}, kd0 = {xkd[0], xkd[1]}, kd1 = {xkd[2], xkd[3]}, kk0 = {xkk[0], xkk[1]}, kk1 = {xkk[2], xkk[3]},
;                             b0 = {xb[0], xb[1]}, b1 = {xb[2], xb[3]}, r0 = {xr[0], xr[1]}, r1 = {xr[2], xr[3]};
;                 float vr[RPL];
; #pragma unroll
;                 for (int q = 0; q < RPL; ++q) vr[q] = vrow[q];
;                 { const int sn = (s + 1 < TC) ? s + 1 : s; SCAN_LD(sn); }
;                 float sa[RPL];
; #pragma unroll
;                 for (int q = 0; q < RPL; ++q) { const f32x2 t = S[q][0] * kk0 + S[q][1] * kk1; sa[q] = t.x + t.y; }
;                 if (RPL == 2) {
;                     sa[0] += dppx<0xB1>(sa[0]); sa[RPL - 1] += dppx<0xB1>(sa[RPL - 1]); sa[0] += dppx<0x4E>(sa[0]); sa[RPL - 1] += dppx<0x4E>(sa[RPL - 1]);
;                     sa[0] += dppx<0x141>(sa[0]); sa[RPL - 1] += dppx<0x141>(sa[RPL - 1]); sa[0] += dppx<0x140>(sa[0]); sa[RPL - 1] += dppx<0x140>(sa[RPL - 1]);
;                 } else {
; #pragma unroll
;                     for (int q = 0; q < RPL; ++q) sa[q] = reduce16(sa[q]);
;                 }
;                 float ov[RPL];
;                 if (RPL == 2) {
;                     const f32x2 vva = {vr[0], vr[0]}, nsa = {-sa[0], -sa[0]}, vvb = {vr[RPL - 1], vr[RPL - 1]}, nsb = {-sa[RPL - 1], -sa[RPL - 1]};
;                     f32x2 a0 = nsa * b0, c0 = nsb * b0, a1 = nsa * b1, c1 = nsb * b1;
;                     a0 = vva * kd0 + a0; c0 = vvb * kd0 + c0; a1 = vva * kd1 + a1; c1 = vvb * kd1 + c1;
;                     S[0][0] = S[0][0] * w0 + a0; S[RPL - 1][0] = S[RPL - 1][0] * w0 + c0; S[0][1] = S[0][1] * w1 + a1; S[RPL - 1][1] = S[RPL - 1][1] * w1 + c1;
;                     f32x2 ua = S[0][0] * r0, ub = S[RPL - 1][0] * r0;
;                     ua = S[0][1] * r1 + ua; ub = S[RPL - 1][1] * r1 + ub;
;                     ov[0] = ua.x + ua.y; ov[RPL - 1] = ub.x + ub.y;
;                 } else {
; #pragma unroll
;                 for (int q = 0; q < RPL; ++q) {
;                     const f32x2 vv = {vr[q], vr[q]}, ns = {-sa[q], -sa[q]};
	v_pk_mul_f32 v[128:129], v[118:119], v[18:19] op_sel:[0,1]
	v_pk_mul_f32 v[130:131], v[118:119], v[106:107] op_sel:[0,1]
	v_pk_fma_f32 v[128:129], v[116:117], v[18:19], v[128:129] op_sel_hi:[1,0,1]
	v_pk_fma_f32 v[130:131], v[116:117], v[106:107], v[130:131] op_sel_hi:[1,0,1]
	ds_read_b128 v[80:83], v134 offset:36096
	v_pk_fma_f32 v[128:129], v[114:115], v[16:17], v[128:129] op_sel:[0,1,0]
	v_pk_fma_f32 v[130:131], v[114:115], v[104:105], v[130:131] op_sel:[0,1,0]
	v_pk_fma_f32 v[128:129], v[112:113], v[16:17], v[128:129] op_sel_hi:[1,0,1]
	v_pk_fma_f32 v[130:131], v[112:113], v[104:105], v[130:131] op_sel_hi:[1,0,1]
	ds_read_b128 v[72:75], v134 offset:19712
	v_add_f32_dpp v128, v128, v128 quad_perm:[1,0,3,2] row_mask:0xf bank_mask:0xf bound_ctrl:1
	v_add_f32_dpp v129, v129, v129 quad_perm:[1,0,3,2] row_mask:0xf bank_mask:0xf bound_ctrl:1
	v_add_f32_dpp v130, v130, v130 quad_perm:[1,0,3,2] row_mask:0xf bank_mask:0xf bound_ctrl:1
	v_add_f32_dpp v131, v131, v131 quad_perm:[1,0,3,2] row_mask:0xf bank_mask:0xf bound_ctrl:1
	ds_read_b128 v[68:71], v134 offset:11520
	v_add_f32_dpp v128, v128, v128 quad_perm:[2,3,0,1] row_mask:0xf bank_mask:0xf bound_ctrl:1
	v_add_f32_dpp v129, v129, v129 quad_perm:[2,3,0,1] row_mask:0xf bank_mask:0xf bound_ctrl:1
	v_add_f32_dpp v130, v130, v130 quad_perm:[2,3,0,1] row_mask:0xf bank_mask:0xf bound_ctrl:1
	v_add_f32_dpp v131, v131, v131 quad_perm:[2,3,0,1] row_mask:0xf bank_mask:0xf bound_ctrl:1
	s_waitcnt lgkmcnt(4)
	v_pk_mul_f32 v[126:127], v[156:157], v[14:15] op_sel:[0,1]
	v_pk_mul_f32 v[124:125], v[156:157], v[14:15] op_sel_hi:[1,0]
	ds_read_b128 v[64:67], v134 offset:3328
	v_add_f32_dpp v128, v128, v128 row_half_mirror row_mask:0xf bank_mask:0xf bound_ctrl:1
	v_add_f32_dpp v129, v129, v129 row_half_mirror row_mask:0xf bank_mask:0xf bound_ctrl:1
	ds_write2_b32 v141, v130, v131 offset0:128 offset1:132
	v_pk_mul_f32 v[122:123], v[156:157], v[12:13] op_sel:[0,1]
	v_add_f32_dpp v132, v128, v128 row_mirror row_mask:0xf bank_mask:0xf bound_ctrl:1
	v_add_f32_dpp v133, v129, v129 row_mirror row_mask:0xf bank_mask:0xf bound_ctrl:1
	v_pk_mul_f32 v[120:121], v[156:157], v[12:13] op_sel_hi:[1,0]
	v_pk_fma_f32 v[118:119], v[118:119], v[10:11], v[126:127] op_sel:[0,1,0]
	v_pk_fma_f32 v[116:117], v[116:117], v[10:11], v[124:125] op_sel_hi:[1,0,1]
	v_pk_fma_f32 v[114:115], v[114:115], v[8:9], v[122:123] op_sel:[0,1,0]
	v_pk_fma_f32 v[112:113], v[112:113], v[8:9], v[120:121] op_sel_hi:[1,0,1]
	v_pk_fma_f32 v[118:119], v[22:23], v[132:133], v[118:119] op_sel:[1,0,0] neg_lo:[0,1,0] neg_hi:[0,1,0]
	v_pk_fma_f32 v[116:117], v[22:23], v[132:133], v[116:117] op_sel_hi:[0,1,1] neg_lo:[0,1,0] neg_hi:[0,1,0]
	v_pk_fma_f32 v[114:115], v[20:21], v[132:133], v[114:115] op_sel:[1,0,0] neg_lo:[0,1,0] neg_hi:[0,1,0]
	v_pk_fma_f32 v[112:113], v[20:21], v[132:133], v[112:113] op_sel_hi:[0,1,1] neg_lo:[0,1,0] neg_hi:[0,1,0]
	ds_read_b128 v[100:103], v134 offset:28160
	s_waitcnt lgkmcnt(4)
	v_pk_mul_f32 v[128:129], v[118:119], v[74:75] op_sel:[0,1]
	v_pk_mul_f32 v[130:131], v[118:119], v[26:27] op_sel:[0,1]
	v_pk_fma_f32 v[128:129], v[116:117], v[74:75], v[128:129] op_sel_hi:[1,0,1]
	v_pk_fma_f32 v[130:131], v[116:117], v[26:27], v[130:131] op_sel_hi:[1,0,1]
	ds_read_b128 v[104:107], v134 offset:36352
	v_pk_fma_f32 v[128:129], v[114:115], v[72:73], v[128:129] op_sel:[0,1,0]
	v_pk_fma_f32 v[130:131], v[114:115], v[24:25], v[130:131] op_sel:[0,1,0]
	v_pk_fma_f32 v[128:129], v[112:113], v[72:73], v[128:129] op_sel_hi:[1,0,1]
	v_pk_fma_f32 v[130:131], v[112:113], v[24:25], v[130:131] op_sel_hi:[1,0,1]
	ds_read_b128 v[96:99], v134 offset:19968
	v_add_f32_dpp v128, v128, v128 quad_perm:[1,0,3,2] row_mask:0xf bank_mask:0xf bound_ctrl:1
	v_add_f32_dpp v129, v129, v129 quad_perm:[1,0,3,2] row_mask:0xf bank_mask:0xf bound_ctrl:1
	v_add_f32_dpp v130, v130, v130 quad_perm:[1,0,3,2] row_mask:0xf bank_mask:0xf bound_ctrl:1
	v_add_f32_dpp v131, v131, v131 quad_perm:[1,0,3,2] row_mask:0xf bank_mask:0xf bound_ctrl:1
	ds_read_b128 v[92:95], v134 offset:11776
	v_add_f32_dpp v128, v128, v128 quad_perm:[2,3,0,1] row_mask:0xf bank_mask:0xf bound_ctrl:1
	v_add_f32_dpp v129, v129, v129 quad_perm:[2,3,0,1] row_mask:0xf bank_mask:0xf bound_ctrl:1
	v_add_f32_dpp v130, v130, v130 quad_perm:[2,3,0,1] row_mask:0xf bank_mask:0xf bound_ctrl:1
	v_add_f32_dpp v131, v131, v131 quad_perm:[2,3,0,1] row_mask:0xf bank_mask:0xf bound_ctrl:1
	s_waitcnt lgkmcnt(4)
	v_pk_mul_f32 v[126:127], v[158:159], v[70:71] op_sel:[0,1]
	v_pk_mul_f32 v[124:125], v[158:159], v[70:71] op_sel_hi:[1,0]
	ds_read2_b64 v[160:163], v110 offset0:224 offset1:240
	v_add_f32_dpp v128, v128, v128 row_half_mirror row_mask:0xf bank_mask:0xf bound_ctrl:1
	v_add_f32_dpp v129, v129, v129 row_half_mirror row_mask:0xf bank_mask:0xf bound_ctrl:1
	ds_write2_b32 v142, v130, v131 offset0:0 offset1:4
	v_pk_mul_f32 v[122:123], v[158:159], v[68:69] op_sel:[0,1]
	v_add_f32_dpp v132, v128, v128 row_mirror row_mask:0xf bank_mask:0xf bound_ctrl:1
	v_add_f32_dpp v133, v129, v129 row_mirror row_mask:0xf bank_mask:0xf bound_ctrl:1
	v_pk_mul_f32 v[120:121], v[158:159], v[68:69] op_sel_hi:[1,0]
	ds_read_b128 v[88:91], v134 offset:3584
	v_pk_fma_f32 v[118:119], v[118:119], v[66:67], v[126:127] op_sel:[0,1,0]
	v_pk_fma_f32 v[116:117], v[116:117], v[66:67], v[124:125] op_sel_hi:[1,0,1]
	v_pk_fma_f32 v[114:115], v[114:115], v[64:65], v[122:123] op_sel:[0,1,0]
	v_pk_fma_f32 v[112:113], v[112:113], v[64:65], v[120:121] op_sel_hi:[1,0,1]
	v_pk_fma_f32 v[118:119], v[78:79], v[132:133], v[118:119] op_sel:[1,0,0] neg_lo:[0,1,0] neg_hi:[0,1,0]
	v_pk_fma_f32 v[116:117], v[78:79], v[132:133], v[116:117] op_sel_hi:[0,1,1] neg_lo:[0,1,0] neg_hi:[0,1,0]
	v_pk_fma_f32 v[114:115], v[76:77], v[132:133], v[114:115] op_sel:[1,0,0] neg_lo:[0,1,0] neg_hi:[0,1,0]
	v_pk_fma_f32 v[112:113], v[76:77], v[132:133], v[112:113] op_sel_hi:[0,1,1] neg_lo:[0,1,0] neg_hi:[0,1,0]
	ds_read_b128 v[20:23], v134 offset:28416
	s_waitcnt lgkmcnt(4)
; template <int RPL, int NSW>
; __device__ __forceinline__ void scan_item(const P& p, LAS unsigned char* lds, int seqbase, int L, int head, int dir, int part, int step0, int nsteps, int mode, float* qc, float* smid) {
;     ...
;             for (int s = 0; s < TC; ++s) {
;                 const f32x2 w0 = {xw[0], xw[1]}, w1 = {xw[2], xw[3]}, kd0 = {xkd[0], xkd[1]}, kd1 = {xkd[2], xkd[3]}, kk0 = {xkk[0], xkk[1]}, kk1 = {xkk[2], xkk[3]},
;                             b0 = {xb[0], xb[1]}, b1 = {xb[2], xb[3]}, r0 = {xr[0], xr[1]}, r1 = {xr[2], xr[3]};
;                 float vr[RPL];
; #pragma unroll
;                 for (int q = 0; q < RPL; ++q) vr[q] = vrow[q];
;                 { const int sn = (s + 1 < TC) ? s + 1 : s; SCAN_LD(sn); }
;                 float sa[RPL];
; #pragma unroll
;                 for (int q = 0; q < RPL; ++q) { const f32x2 t = S[q][0] * kk0 + S[q][1] * kk1; sa[q] = t.x + t.y; }
;                 if (RPL == 2) {
;                     sa[0] += dppx<0xB1>(sa[0]); sa[RPL - 1] += dppx<0xB1>(sa[RPL - 1]); sa[0] += dppx<0x4E>(sa[0]); sa[RPL - 1] += dppx<0x4E>(sa[RPL - 1]);
;                     sa[0] += dppx<0x141>(sa[0]); sa[RPL - 1] += dppx<0x141>(sa[RPL - 1]); sa[0] += dppx<0x140>(sa[0]); sa[RPL - 1] += dppx<0x140>(sa[RPL - 1]);
;                 } else {
; #pragma unroll
;                     for (int q = 0; q < RPL; ++q) sa[q] = reduce16(sa[q]);
;                 }
;                 float ov[RPL];
;                 if (RPL == 2) {
;                     const f32x2 vva = {vr[0], vr[0]}, nsa = {-sa[0], -sa[0]}, vvb = {vr[RPL - 1], vr[RPL - 1]}, nsb = {-sa[RPL - 1], -sa[RPL - 1]};
;                     f32x2 a0 = nsa * b0, c0 = nsb * b0, a1 = nsa * b1, c1 = nsb * b1;
;                     a0 = vva * kd0 + a0; c0 = vvb * kd0 + c0; a1 = vva * kd1 + a1; c1 = vvb * kd1 + c1;
;                     S[0][0] = S[0][0] * w0 + a0; S[RPL - 1][0] = S[RPL - 1][0] * w0 + c0; S[0][1] = S[0][1] * w1 + a1; S[RPL - 1][1] = S[RPL - 1][1] * w1 + c1;
;                     f32x2 ua = S[0][0] * r0, ub = S[RPL - 1][0] * r0;
;                     ua = S[0][1] * r1 + ua; ub = S[RPL - 1][1] * r1 + ub;
;                     ov[0] = ua.x + ua.y; ov[RPL - 1] = ub.x + ub.y;
;                 } else {
; #pragma unroll
;                 for (int q = 0; q < RPL; ++q) {
;                     const f32x2 vv = {vr[q], vr[q]}, ns = {-sa[q], -sa[q]};
	v_pk_mul_f32 v[128:129], v[118:119], v[98:99] op_sel:[0,1]
	v_pk_mul_f32 v[130:131], v[118:119], v[82:83] op_sel:[0,1]
	v_pk_fma_f32 v[128:129], v[116:117], v[98:99], v[128:129] op_sel_hi:[1,0,1]
	v_pk_fma_f32 v[130:131], v[116:117], v[82:83], v[130:131] op_sel_hi:[1,0,1]
	ds_read_b128 v[24:27], v134 offset:36608
	v_pk_fma_f32 v[128:129], v[114:115], v[96:97], v[128:129] op_sel:[0,1,0]
	v_pk_fma_f32 v[130:131], v[114:115], v[80:81], v[130:131] op_sel:[0,1,0]
	v_pk_fma_f32 v[128:129], v[112:113], v[96:97], v[128:129] op_sel_hi:[1,0,1]
	v_pk_fma_f32 v[130:131], v[112:113], v[80:81], v[130:131] op_sel_hi:[1,0,1]
	ds_read_b128 v[16:19], v134 offset:20224
	v_add_f32_dpp v128, v128, v128 quad_perm:[1,0,3,2] row_mask:0xf bank_mask:0xf bound_ctrl:1
	v_add_f32_dpp v129, v129, v129 quad_perm:[1,0,3,2] row_mask:0xf bank_mask:0xf bound_ctrl:1
	v_add_f32_dpp v130, v130, v130 quad_perm:[1,0,3,2] row_mask:0xf bank_mask:0xf bound_ctrl:1
	v_add_f32_dpp v131, v131, v131 quad_perm:[1,0,3,2] row_mask:0xf bank_mask:0xf bound_ctrl:1
	ds_read_b128 v[12:15], v134 offset:12032
	v_add_f32_dpp v128, v128, v128 quad_perm:[2,3,0,1] row_mask:0xf bank_mask:0xf bound_ctrl:1
	v_add_f32_dpp v129, v129, v129 quad_perm:[2,3,0,1] row_mask:0xf bank_mask:0xf bound_ctrl:1
	v_add_f32_dpp v130, v130, v130 quad_perm:[2,3,0,1] row_mask:0xf bank_mask:0xf bound_ctrl:1
	v_add_f32_dpp v131, v131, v131 quad_perm:[2,3,0,1] row_mask:0xf bank_mask:0xf bound_ctrl:1
	s_waitcnt lgkmcnt(4)
	v_pk_mul_f32 v[126:127], v[160:161], v[94:95] op_sel:[0,1]
	v_pk_mul_f32 v[124:125], v[160:161], v[94:95] op_sel_hi:[1,0]
	ds_read_b128 v[8:11], v134 offset:3840
	v_add_f32_dpp v128, v128, v128 row_half_mirror row_mask:0xf bank_mask:0xf bound_ctrl:1
	v_add_f32_dpp v129, v129, v129 row_half_mirror row_mask:0xf bank_mask:0xf bound_ctrl:1
	ds_write2_b32 v142, v130, v131 offset0:128 offset1:132
	v_pk_mul_f32 v[122:123], v[160:161], v[92:93] op_sel:[0,1]
	v_add_f32_dpp v132, v128, v128 row_mirror row_mask:0xf bank_mask:0xf bound_ctrl:1
	v_add_f32_dpp v133, v129, v129 row_mirror row_mask:0xf bank_mask:0xf bound_ctrl:1
	v_pk_mul_f32 v[120:121], v[160:161], v[92:93] op_sel_hi:[1,0]
	v_pk_fma_f32 v[118:119], v[118:119], v[90:91], v[126:127] op_sel:[0,1,0]
	v_pk_fma_f32 v[116:117], v[116:117], v[90:91], v[124:125] op_sel_hi:[1,0,1]
	v_pk_fma_f32 v[114:115], v[114:115], v[88:89], v[122:123] op_sel:[0,1,0]
	v_pk_fma_f32 v[112:113], v[112:113], v[88:89], v[120:121] op_sel_hi:[1,0,1]
	v_pk_fma_f32 v[118:119], v[102:103], v[132:133], v[118:119] op_sel:[1,0,0] neg_lo:[0,1,0] neg_hi:[0,1,0]
	v_pk_fma_f32 v[116:117], v[102:103], v[132:133], v[116:117] op_sel_hi:[0,1,1] neg_lo:[0,1,0] neg_hi:[0,1,0]
	v_pk_fma_f32 v[114:115], v[100:101], v[132:133], v[114:115] op_sel:[1,0,0] neg_lo:[0,1,0] neg_hi:[0,1,0]
	v_pk_fma_f32 v[112:113], v[100:101], v[132:133], v[112:113] op_sel_hi:[0,1,1] neg_lo:[0,1,0] neg_hi:[0,1,0]
	ds_read_b128 v[76:79], v134 offset:28672
	s_waitcnt lgkmcnt(4)
	v_pk_mul_f32 v[128:129], v[118:119], v[18:19] op_sel:[0,1]
	v_pk_mul_f32 v[130:131], v[118:119], v[106:107] op_sel:[0,1]
	v_pk_fma_f32 v[128:129], v[116:117], v[18:19], v[128:129] op_sel_hi:[1,0,1]
	v_pk_fma_f32 v[130:131], v[116:117], v[106:107], v[130:131] op_sel_hi:[1,0,1]
	ds_read_b128 v[80:83], v134 offset:36864
	v_pk_fma_f32 v[128:129], v[114:115], v[16:17], v[128:129] op_sel:[0,1,0]
	v_pk_fma_f32 v[130:131], v[114:115], v[104:105], v[130:131] op_sel:[0,1,0]
	v_pk_fma_f32 v[128:129], v[112:113], v[16:17], v[128:129] op_sel_hi:[1,0,1]
	v_pk_fma_f32 v[130:131], v[112:113], v[104:105], v[130:131] op_sel_hi:[1,0,1]
	ds_read_b128 v[72:75], v134 offset:20480
	v_add_f32_dpp v128, v128, v128 quad_perm:[1,0,3,2] row_mask:0xf bank_mask:0xf bound_ctrl:1
	v_add_f32_dpp v129, v129, v129 quad_perm:[1,0,3,2] row_mask:0xf bank_mask:0xf bound_ctrl:1
	v_add_f32_dpp v130, v130, v130 quad_perm:[1,0,3,2] row_mask:0xf bank_mask:0xf bound_ctrl:1
	v_add_f32_dpp v131, v131, v131 quad_perm:[1,0,3,2] row_mask:0xf bank_mask:0xf bound_ctrl:1
	ds_read_b128 v[68:71], v134 offset:12288
	v_add_f32_dpp v128, v128, v128 quad_perm:[2,3,0,1] row_mask:0xf bank_mask:0xf bound_ctrl:1
	v_add_f32_dpp v129, v129, v129 quad_perm:[2,3,0,1] row_mask:0xf bank_mask:0xf bound_ctrl:1
	v_add_f32_dpp v130, v130, v130 quad_perm:[2,3,0,1] row_mask:0xf bank_mask:0xf bound_ctrl:1
	v_add_f32_dpp v131, v131, v131 quad_perm:[2,3,0,1] row_mask:0xf bank_mask:0xf bound_ctrl:1
	s_waitcnt lgkmcnt(4)
	v_pk_mul_f32 v[126:127], v[162:163], v[14:15] op_sel:[0,1]
	v_pk_mul_f32 v[124:125], v[162:163], v[14:15] op_sel_hi:[1,0]
	ds_read2_b64 v[156:159], v111 offset0:0 offset1:16
	v_add_f32_dpp v128, v128, v128 row_half_mirror row_mask:0xf bank_mask:0xf bound_ctrl:1
	v_add_f32_dpp v129, v129, v129 row_half_mirror row_mask:0xf bank_mask:0xf bound_ctrl:1
	ds_write2_b32 v143, v130, v131 offset0:0 offset1:4
	v_pk_mul_f32 v[122:123], v[162:163], v[12:13] op_sel:[0,1]
	v_add_f32_dpp v132, v128, v128 row_mirror row_mask:0xf bank_mask:0xf bound_ctrl:1
	v_add_f32_dpp v133, v129, v129 row_mirror row_mask:0xf bank_mask:0xf bound_ctrl:1
	v_pk_mul_f32 v[120:121], v[162:163], v[12:13] op_sel_hi:[1,0]
	ds_read_b128 v[64:67], v134 offset:4096
	v_pk_fma_f32 v[118:119], v[118:119], v[10:11], v[126:127] op_sel:[0,1,0]
	v_pk_fma_f32 v[116:117], v[116:117], v[10:11], v[124:125] op_sel_hi:[1,0,1]
	v_pk_fma_f32 v[114:115], v[114:115], v[8:9], v[122:123] op_sel:[0,1,0]
	v_pk_fma_f32 v[112:113], v[112:113], v[8:9], v[120:121] op_sel_hi:[1,0,1]
	v_pk_fma_f32 v[118:119], v[22:23], v[132:133], v[118:119] op_sel:[1,0,0] neg_lo:[0,1,0] neg_hi:[0,1,0]
	v_pk_fma_f32 v[116:117], v[22:23], v[132:133], v[116:117] op_sel_hi:[0,1,1] neg_lo:[0,1,0] neg_hi:[0,1,0]
	v_pk_fma_f32 v[114:115], v[20:21], v[132:133], v[114:115] op_sel:[1,0,0] neg_lo:[0,1,0] neg_hi:[0,1,0]
	v_pk_fma_f32 v[112:113], v[20:21], v[132:133], v[112:113] op_sel_hi:[0,1,1] neg_lo:[0,1,0] neg_hi:[0,1,0]
	ds_read_b128 v[100:103], v134 offset:28928
	s_waitcnt lgkmcnt(4)
; template <int RPL, int NSW>
; __device__ __forceinline__ void scan_item(const P& p, LAS unsigned char* lds, int seqbase, int L, int head, int dir, int part, int step0, int nsteps, int mode, float* qc, float* smid) {
;     ...
;             for (int s = 0; s < TC; ++s) {
;                 const f32x2 w0 = {xw[0], xw[1]}, w1 = {xw[2], xw[3]}, kd0 = {xkd[0], xkd[1]}, kd1 = {xkd[2], xkd[3]}, kk0 = {xkk[0], xkk[1]}, kk1 = {xkk[2], xkk[3]},
;                             b0 = {xb[0], xb[1]}, b1 = {xb[2], xb[3]}, r0 = {xr[0], xr[1]}, r1 = {xr[2], xr[3]};
;                 float vr[RPL];
; #pragma unroll
;                 for (int q = 0; q < RPL; ++q) vr[q] = vrow[q];
;                 { const int sn = (s + 1 < TC) ? s + 1 : s; SCAN_LD(sn); }
;                 float sa[RPL];
; #pragma unroll
;                 for (int q = 0; q < RPL; ++q) { const f32x2 t = S[q][0] * kk0 + S[q][1] * kk1; sa[q] = t.x + t.y; }
;                 if (RPL == 2) {
;                     sa[0] += dppx<0xB1>(sa[0]); sa[RPL - 1] += dppx<0xB1>(sa[RPL - 1]); sa[0] += dppx<0x4E>(sa[0]); sa[RPL - 1] += dppx<0x4E>(sa[RPL - 1]);
;                     sa[0] += dppx<0x141>(sa[0]); sa[RPL - 1] += dppx<0x141>(sa[RPL - 1]); sa[0] += dppx<0x140>(sa[0]); sa[RPL - 1] += dppx<0x140>(sa[RPL - 1]);
;                 } else {
; #pragma unroll
;                     for (int q = 0; q < RPL; ++q) sa[q] = reduce16(sa[q]);
;                 }
;                 float ov[RPL];
;                 if (RPL == 2) {
;                     const f32x2 vva = {vr[0], vr[0]}, nsa = {-sa[0], -sa[0]}, vvb = {vr[RPL - 1], vr[RPL - 1]}, nsb = {-sa[RPL - 1], -sa[RPL - 1]};
;                     f32x2 a0 = nsa * b0, c0 = nsb * b0, a1 = nsa * b1, c1 = nsb * b1;
;                     a0 = vva * kd0 + a0; c0 = vvb * kd0 + c0; a1 = vva * kd1 + a1; c1 = vvb * kd1 + c1;
;                     S[0][0] = S[0][0] * w0 + a0; S[RPL - 1][0] = S[RPL - 1][0] * w0 + c0; S[0][1] = S[0][1] * w1 + a1; S[RPL - 1][1] = S[RPL - 1][1] * w1 + c1;
;                     f32x2 ua = S[0][0] * r0, ub = S[RPL - 1][0] * r0;
;                     ua = S[0][1] * r1 + ua; ub = S[RPL - 1][1] * r1 + ub;
;                     ov[0] = ua.x + ua.y; ov[RPL - 1] = ub.x + ub.y;
;                 } else {
; #pragma unroll
;                 for (int q = 0; q < RPL; ++q) {
;                     const f32x2 vv = {vr[q], vr[q]}, ns = {-sa[q], -sa[q]};
	v_pk_mul_f32 v[128:129], v[118:119], v[74:75] op_sel:[0,1]
	v_pk_mul_f32 v[130:131], v[118:119], v[26:27] op_sel:[0,1]
	v_pk_fma_f32 v[128:129], v[116:117], v[74:75], v[128:129] op_sel_hi:[1,0,1]
	v_pk_fma_f32 v[130:131], v[116:117], v[26:27], v[130:131] op_sel_hi:[1,0,1]
	ds_read_b128 v[104:107], v134 offset:37120
	v_pk_fma_f32 v[128:129], v[114:115], v[72:73], v[128:129] op_sel:[0,1,0]
	v_pk_fma_f32 v[130:131], v[114:115], v[24:25], v[130:131] op_sel:[0,1,0]
	v_pk_fma_f32 v[128:129], v[112:113], v[72:73], v[128:129] op_sel_hi:[1,0,1]
	v_pk_fma_f32 v[130:131], v[112:113], v[24:25], v[130:131] op_sel_hi:[1,0,1]
	ds_read_b128 v[96:99], v134 offset:20736
	v_add_f32_dpp v128, v128, v128 quad_perm:[1,0,3,2] row_mask:0xf bank_mask:0xf bound_ctrl:1
	v_add_f32_dpp v129, v129, v129 quad_perm:[1,0,3,2] row_mask:0xf bank_mask:0xf bound_ctrl:1
	v_add_f32_dpp v130, v130, v130 quad_perm:[1,0,3,2] row_mask:0xf bank_mask:0xf bound_ctrl:1
	v_add_f32_dpp v131, v131, v131 quad_perm:[1,0,3,2] row_mask:0xf bank_mask:0xf bound_ctrl:1
	ds_read_b128 v[92:95], v134 offset:12544
	v_add_f32_dpp v128, v128, v128 quad_perm:[2,3,0,1] row_mask:0xf bank_mask:0xf bound_ctrl:1
	v_add_f32_dpp v129, v129, v129 quad_perm:[2,3,0,1] row_mask:0xf bank_mask:0xf bound_ctrl:1
	v_add_f32_dpp v130, v130, v130 quad_perm:[2,3,0,1] row_mask:0xf bank_mask:0xf bound_ctrl:1
	v_add_f32_dpp v131, v131, v131 quad_perm:[2,3,0,1] row_mask:0xf bank_mask:0xf bound_ctrl:1
	s_waitcnt lgkmcnt(4)
	v_pk_mul_f32 v[126:127], v[156:157], v[70:71] op_sel:[0,1]
	v_pk_mul_f32 v[124:125], v[156:157], v[70:71] op_sel_hi:[1,0]
	ds_read_b128 v[88:91], v134 offset:4352
	v_add_f32_dpp v128, v128, v128 row_half_mirror row_mask:0xf bank_mask:0xf bound_ctrl:1
	v_add_f32_dpp v129, v129, v129 row_half_mirror row_mask:0xf bank_mask:0xf bound_ctrl:1
	ds_write2_b32 v143, v130, v131 offset0:128 offset1:132
	v_pk_mul_f32 v[122:123], v[156:157], v[68:69] op_sel:[0,1]
	v_add_f32_dpp v132, v128, v128 row_mirror row_mask:0xf bank_mask:0xf bound_ctrl:1
	v_add_f32_dpp v133, v129, v129 row_mirror row_mask:0xf bank_mask:0xf bound_ctrl:1
	v_pk_mul_f32 v[120:121], v[156:157], v[68:69] op_sel_hi:[1,0]
	v_pk_fma_f32 v[118:119], v[118:119], v[66:67], v[126:127] op_sel:[0,1,0]
	v_pk_fma_f32 v[116:117], v[116:117], v[66:67], v[124:125] op_sel_hi:[1,0,1]
	v_pk_fma_f32 v[114:115], v[114:115], v[64:65], v[122:123] op_sel:[0,1,0]
	v_pk_fma_f32 v[112:113], v[112:113], v[64:65], v[120:121] op_sel_hi:[1,0,1]
	v_pk_fma_f32 v[118:119], v[78:79], v[132:133], v[118:119] op_sel:[1,0,0] neg_lo:[0,1,0] neg_hi:[0,1,0]
	v_pk_fma_f32 v[116:117], v[78:79], v[132:133], v[116:117] op_sel_hi:[0,1,1] neg_lo:[0,1,0] neg_hi:[0,1,0]
	v_pk_fma_f32 v[114:115], v[76:77], v[132:133], v[114:115] op_sel:[1,0,0] neg_lo:[0,1,0] neg_hi:[0,1,0]
	v_pk_fma_f32 v[112:113], v[76:77], v[132:133], v[112:113] op_sel_hi:[0,1,1] neg_lo:[0,1,0] neg_hi:[0,1,0]
	ds_read_b128 v[20:23], v134 offset:29184
	s_waitcnt lgkmcnt(4)
	v_pk_mul_f32 v[128:129], v[118:119], v[98:99] op_sel:[0,1]
	v_pk_mul_f32 v[130:131], v[118:119], v[82:83] op_sel:[0,1]
	v_pk_fma_f32 v[128:129], v[116:117], v[98:99], v[128:129] op_sel_hi:[1,0,1]
	v_pk_fma_f32 v[130:131], v[116:117], v[82:83], v[130:131] op_sel_hi:[1,0,1]
	ds_read_b128 v[24:27], v134 offset:37376
	v_pk_fma_f32 v[128:129], v[114:115], v[96:97], v[128:129] op_sel:[0,1,0]
	v_pk_fma_f32 v[130:131], v[114:115], v[80:81], v[130:131] op_sel:[0,1,0]
	v_pk_fma_f32 v[128:129], v[112:113], v[96:97], v[128:129] op_sel_hi:[1,0,1]
	v_pk_fma_f32 v[130:131], v[112:113], v[80:81], v[130:131] op_sel_hi:[1,0,1]
	ds_read_b128 v[16:19], v134 offset:20992
	v_add_f32_dpp v128, v128, v128 quad_perm:[1,0,3,2] row_mask:0xf bank_mask:0xf bound_ctrl:1
	v_add_f32_dpp v129, v129, v129 quad_perm:[1,0,3,2] row_mask:0xf bank_mask:0xf bound_ctrl:1
	v_add_f32_dpp v130, v130, v130 quad_perm:[1,0,3,2] row_mask:0xf bank_mask:0xf bound_ctrl:1
	v_add_f32_dpp v131, v131, v131 quad_perm:[1,0,3,2] row_mask:0xf bank_mask:0xf bound_ctrl:1
	ds_read_b128 v[12:15], v134 offset:12800
	v_add_f32_dpp v128, v128, v128 quad_perm:[2,3,0,1] row_mask:0xf bank_mask:0xf bound_ctrl:1
	v_add_f32_dpp v129, v129, v129 quad_perm:[2,3,0,1] row_mask:0xf bank_mask:0xf bound_ctrl:1
	v_add_f32_dpp v130, v130, v130 quad_perm:[2,3,0,1] row_mask:0xf bank_mask:0xf bound_ctrl:1
	v_add_f32_dpp v131, v131, v131 quad_perm:[2,3,0,1] row_mask:0xf bank_mask:0xf bound_ctrl:1
	s_waitcnt lgkmcnt(4)
	v_pk_mul_f32 v[126:127], v[158:159], v[94:95] op_sel:[0,1]
	v_pk_mul_f32 v[124:125], v[158:159], v[94:95] op_sel_hi:[1,0]
	ds_read2_b64 v[160:163], v111 offset0:32 offset1:48
	v_add_f32_dpp v128, v128, v128 row_half_mirror row_mask:0xf bank_mask:0xf bound_ctrl:1
	v_add_f32_dpp v129, v129, v129 row_half_mirror row_mask:0xf bank_mask:0xf bound_ctrl:1
	ds_write2_b32 v144, v130, v131 offset0:0 offset1:4
	v_pk_mul_f32 v[122:123], v[158:159], v[92:93] op_sel:[0,1]
	v_add_f32_dpp v132, v128, v128 row_mirror row_mask:0xf bank_mask:0xf bound_ctrl:1
	v_add_f32_dpp v133, v129, v129 row_mirror row_mask:0xf bank_mask:0xf bound_ctrl:1
	v_pk_mul_f32 v[120:121], v[158:159], v[92:93] op_sel_hi:[1,0]
	ds_read_b128 v[8:11], v134 offset:4608
	v_pk_fma_f32 v[118:119], v[118:119], v[90:91], v[126:127] op_sel:[0,1,0]
	v_pk_fma_f32 v[116:117], v[116:117], v[90:91], v[124:125] op_sel_hi:[1,0,1]
	v_pk_fma_f32 v[114:115], v[114:115], v[88:89], v[122:123] op_sel:[0,1,0]
	v_pk_fma_f32 v[112:113], v[112:113], v[88:89], v[120:121] op_sel_hi:[1,0,1]
	v_pk_fma_f32 v[118:119], v[102:103], v[132:133], v[118:119] op_sel:[1,0,0] neg_lo:[0,1,0] neg_hi:[0,1,0]
	v_pk_fma_f32 v[116:117], v[102:103], v[132:133], v[116:117] op_sel_hi:[0,1,1] neg_lo:[0,1,0] neg_hi:[0,1,0]
	v_pk_fma_f32 v[114:115], v[100:101], v[132:133], v[114:115] op_sel:[1,0,0] neg_lo:[0,1,0] neg_hi:[0,1,0]
	v_pk_fma_f32 v[112:113], v[100:101], v[132:133], v[112:113] op_sel_hi:[0,1,1] neg_lo:[0,1,0] neg_hi:[0,1,0]
	ds_read_b128 v[76:79], v134 offset:29440
	s_waitcnt lgkmcnt(4)
; template <int RPL, int NSW>
; __device__ __forceinline__ void scan_item(const P& p, LAS unsigned char* lds, int seqbase, int L, int head, int dir, int part, int step0, int nsteps, int mode, float* qc, float* smid) {
;     ...
;             for (int s = 0; s < TC; ++s) {
;                 const f32x2 w0 = {xw[0], xw[1]}, w1 = {xw[2], xw[3]}, kd0 = {xkd[0], xkd[1]}, kd1 = {xkd[2], xkd[3]}, kk0 = {xkk[0], xkk[1]}, kk1 = {xkk[2], xkk[3]},
;                             b0 = {xb[0], xb[1]}, b1 = {xb[2], xb[3]}, r0 = {xr[0], xr[1]}, r1 = {xr[2], xr[3]};
;                 float vr[RPL];
; #pragma unroll
;                 for (int q = 0; q < RPL; ++q) vr[q] = vrow[q];
;                 { const int sn = (s + 1 < TC) ? s + 1 : s; SCAN_LD(sn); }
;                 float sa[RPL];
; #pragma unroll
;                 for (int q = 0; q < RPL; ++q) { const f32x2 t = S[q][0] * kk0 + S[q][1] * kk1; sa[q] = t.x + t.y; }
;                 if (RPL == 2) {
;                     sa[0] += dppx<0xB1>(sa[0]); sa[RPL - 1] += dppx<0xB1>(sa[RPL - 1]); sa[0] += dppx<0x4E>(sa[0]); sa[RPL - 1] += dppx<0x4E>(sa[RPL - 1]);
;                     sa[0] += dppx<0x141>(sa[0]); sa[RPL - 1] += dppx<0x141>(sa[RPL - 1]); sa[0] += dppx<0x140>(sa[0]); sa[RPL - 1] += dppx<0x140>(sa[RPL - 1]);
;                 } else {
; #pragma unroll
;                     for (int q = 0; q < RPL; ++q) sa[q] = reduce16(sa[q]);
;                 }
;                 float ov[RPL];
;                 if (RPL == 2) {
;                     const f32x2 vva = {vr[0], vr[0]}, nsa = {-sa[0], -sa[0]}, vvb = {vr[RPL - 1], vr[RPL - 1]}, nsb = {-sa[RPL - 1], -sa[RPL - 1]};
;                     f32x2 a0 = nsa * b0, c0 = nsb * b0, a1 = nsa * b1, c1 = nsb * b1;
;                     a0 = vva * kd0 + a0; c0 = vvb * kd0 + c0; a1 = vva * kd1 + a1; c1 = vvb * kd1 + c1;
;                     S[0][0] = S[0][0] * w0 + a0; S[RPL - 1][0] = S[RPL - 1][0] * w0 + c0; S[0][1] = S[0][1] * w1 + a1; S[RPL - 1][1] = S[RPL - 1][1] * w1 + c1;
;                     f32x2 ua = S[0][0] * r0, ub = S[RPL - 1][0] * r0;
;                     ua = S[0][1] * r1 + ua; ub = S[RPL - 1][1] * r1 + ub;
;                     ov[0] = ua.x + ua.y; ov[RPL - 1] = ub.x + ub.y;
;                 } else {
; #pragma unroll
;                 for (int q = 0; q < RPL; ++q) {
;                     const f32x2 vv = {vr[q], vr[q]}, ns = {-sa[q], -sa[q]};
	v_pk_mul_f32 v[128:129], v[118:119], v[18:19] op_sel:[0,1]
	v_pk_mul_f32 v[130:131], v[118:119], v[106:107] op_sel:[0,1]
	v_pk_fma_f32 v[128:129], v[116:117], v[18:19], v[128:129] op_sel_hi:[1,0,1]
	v_pk_fma_f32 v[130:131], v[116:117], v[106:107], v[130:131] op_sel_hi:[1,0,1]
	ds_read_b128 v[80:83], v134 offset:37632
	v_pk_fma_f32 v[128:129], v[114:115], v[16:17], v[128:129] op_sel:[0,1,0]
	v_pk_fma_f32 v[130:131], v[114:115], v[104:105], v[130:131] op_sel:[0,1,0]
	v_pk_fma_f32 v[128:129], v[112:113], v[16:17], v[128:129] op_sel_hi:[1,0,1]
	v_pk_fma_f32 v[130:131], v[112:113], v[104:105], v[130:131] op_sel_hi:[1,0,1]
	ds_read_b128 v[72:75], v134 offset:21248
	v_add_f32_dpp v128, v128, v128 quad_perm:[1,0,3,2] row_mask:0xf bank_mask:0xf bound_ctrl:1
	v_add_f32_dpp v129, v129, v129 quad_perm:[1,0,3,2] row_mask:0xf bank_mask:0xf bound_ctrl:1
	v_add_f32_dpp v130, v130, v130 quad_perm:[1,0,3,2] row_mask:0xf bank_mask:0xf bound_ctrl:1
	v_add_f32_dpp v131, v131, v131 quad_perm:[1,0,3,2] row_mask:0xf bank_mask:0xf bound_ctrl:1
	ds_read_b128 v[68:71], v134 offset:13056
	v_add_f32_dpp v128, v128, v128 quad_perm:[2,3,0,1] row_mask:0xf bank_mask:0xf bound_ctrl:1
	v_add_f32_dpp v129, v129, v129 quad_perm:[2,3,0,1] row_mask:0xf bank_mask:0xf bound_ctrl:1
	v_add_f32_dpp v130, v130, v130 quad_perm:[2,3,0,1] row_mask:0xf bank_mask:0xf bound_ctrl:1
	v_add_f32_dpp v131, v131, v131 quad_perm:[2,3,0,1] row_mask:0xf bank_mask:0xf bound_ctrl:1
	s_waitcnt lgkmcnt(4)
	v_pk_mul_f32 v[126:127], v[160:161], v[14:15] op_sel:[0,1]
	v_pk_mul_f32 v[124:125], v[160:161], v[14:15] op_sel_hi:[1,0]
	ds_read_b128 v[64:67], v134 offset:4864
	v_add_f32_dpp v128, v128, v128 row_half_mirror row_mask:0xf bank_mask:0xf bound_ctrl:1
	v_add_f32_dpp v129, v129, v129 row_half_mirror row_mask:0xf bank_mask:0xf bound_ctrl:1
	ds_write2_b32 v144, v130, v131 offset0:128 offset1:132
	v_pk_mul_f32 v[122:123], v[160:161], v[12:13] op_sel:[0,1]
	v_add_f32_dpp v132, v128, v128 row_mirror row_mask:0xf bank_mask:0xf bound_ctrl:1
	v_add_f32_dpp v133, v129, v129 row_mirror row_mask:0xf bank_mask:0xf bound_ctrl:1
	v_pk_mul_f32 v[120:121], v[160:161], v[12:13] op_sel_hi:[1,0]
	v_pk_fma_f32 v[118:119], v[118:119], v[10:11], v[126:127] op_sel:[0,1,0]
	v_pk_fma_f32 v[116:117], v[116:117], v[10:11], v[124:125] op_sel_hi:[1,0,1]
	v_pk_fma_f32 v[114:115], v[114:115], v[8:9], v[122:123] op_sel:[0,1,0]
	v_pk_fma_f32 v[112:113], v[112:113], v[8:9], v[120:121] op_sel_hi:[1,0,1]
	v_pk_fma_f32 v[118:119], v[22:23], v[132:133], v[118:119] op_sel:[1,0,0] neg_lo:[0,1,0] neg_hi:[0,1,0]
	v_pk_fma_f32 v[116:117], v[22:23], v[132:133], v[116:117] op_sel_hi:[0,1,1] neg_lo:[0,1,0] neg_hi:[0,1,0]
	v_pk_fma_f32 v[114:115], v[20:21], v[132:133], v[114:115] op_sel:[1,0,0] neg_lo:[0,1,0] neg_hi:[0,1,0]
	v_pk_fma_f32 v[112:113], v[20:21], v[132:133], v[112:113] op_sel_hi:[0,1,1] neg_lo:[0,1,0] neg_hi:[0,1,0]
	ds_read_b128 v[100:103], v134 offset:29696
	s_waitcnt lgkmcnt(4)
	v_pk_mul_f32 v[128:129], v[118:119], v[74:75] op_sel:[0,1]
	v_pk_mul_f32 v[130:131], v[118:119], v[26:27] op_sel:[0,1]
	v_pk_fma_f32 v[128:129], v[116:117], v[74:75], v[128:129] op_sel_hi:[1,0,1]
	v_pk_fma_f32 v[130:131], v[116:117], v[26:27], v[130:131] op_sel_hi:[1,0,1]
	ds_read_b128 v[104:107], v134 offset:37888
	v_pk_fma_f32 v[128:129], v[114:115], v[72:73], v[128:129] op_sel:[0,1,0]
	v_pk_fma_f32 v[130:131], v[114:115], v[24:25], v[130:131] op_sel:[0,1,0]
	v_pk_fma_f32 v[128:129], v[112:113], v[72:73], v[128:129] op_sel_hi:[1,0,1]
	v_pk_fma_f32 v[130:131], v[112:113], v[24:25], v[130:131] op_sel_hi:[1,0,1]
	ds_read_b128 v[96:99], v134 offset:21504
	v_add_f32_dpp v128, v128, v128 quad_perm:[1,0,3,2] row_mask:0xf bank_mask:0xf bound_ctrl:1
	v_add_f32_dpp v129, v129, v129 quad_perm:[1,0,3,2] row_mask:0xf bank_mask:0xf bound_ctrl:1
	v_add_f32_dpp v130, v130, v130 quad_perm:[1,0,3,2] row_mask:0xf bank_mask:0xf bound_ctrl:1
	v_add_f32_dpp v131, v131, v131 quad_perm:[1,0,3,2] row_mask:0xf bank_mask:0xf bound_ctrl:1
	ds_read_b128 v[92:95], v134 offset:13312
	v_add_f32_dpp v128, v128, v128 quad_perm:[2,3,0,1] row_mask:0xf bank_mask:0xf bound_ctrl:1
	v_add_f32_dpp v129, v129, v129 quad_perm:[2,3,0,1] row_mask:0xf bank_mask:0xf bound_ctrl:1
	v_add_f32_dpp v130, v130, v130 quad_perm:[2,3,0,1] row_mask:0xf bank_mask:0xf bound_ctrl:1
	v_add_f32_dpp v131, v131, v131 quad_perm:[2,3,0,1] row_mask:0xf bank_mask:0xf bound_ctrl:1
	s_waitcnt lgkmcnt(4)
	v_pk_mul_f32 v[126:127], v[162:163], v[70:71] op_sel:[0,1]
	v_pk_mul_f32 v[124:125], v[162:163], v[70:71] op_sel_hi:[1,0]
	ds_read2_b64 v[156:159], v111 offset0:64 offset1:80
	v_add_f32_dpp v128, v128, v128 row_half_mirror row_mask:0xf bank_mask:0xf bound_ctrl:1
	v_add_f32_dpp v129, v129, v129 row_half_mirror row_mask:0xf bank_mask:0xf bound_ctrl:1
	ds_write2_b32 v145, v130, v131 offset0:0 offset1:4
	v_pk_mul_f32 v[122:123], v[162:163], v[68:69] op_sel:[0,1]
	v_add_f32_dpp v132, v128, v128 row_mirror row_mask:0xf bank_mask:0xf bound_ctrl:1
	v_add_f32_dpp v133, v129, v129 row_mirror row_mask:0xf bank_mask:0xf bound_ctrl:1
	v_pk_mul_f32 v[120:121], v[162:163], v[68:69] op_sel_hi:[1,0]
	ds_read_b128 v[88:91], v134 offset:5120
	v_pk_fma_f32 v[118:119], v[118:119], v[66:67], v[126:127] op_sel:[0,1,0]
	v_pk_fma_f32 v[116:117], v[116:117], v[66:67], v[124:125] op_sel_hi:[1,0,1]
	v_pk_fma_f32 v[114:115], v[114:115], v[64:65], v[122:123] op_sel:[0,1,0]
	v_pk_fma_f32 v[112:113], v[112:113], v[64:65], v[120:121] op_sel_hi:[1,0,1]
	v_pk_fma_f32 v[118:119], v[78:79], v[132:133], v[118:119] op_sel:[1,0,0] neg_lo:[0,1,0] neg_hi:[0,1,0]
	v_pk_fma_f32 v[116:117], v[78:79], v[132:133], v[116:117] op_sel_hi:[0,1,1] neg_lo:[0,1,0] neg_hi:[0,1,0]
	v_pk_fma_f32 v[114:115], v[76:77], v[132:133], v[114:115] op_sel:[1,0,0] neg_lo:[0,1,0] neg_hi:[0,1,0]
	v_pk_fma_f32 v[112:113], v[76:77], v[132:133], v[112:113] op_sel_hi:[0,1,1] neg_lo:[0,1,0] neg_hi:[0,1,0]
	ds_read_b128 v[20:23], v134 offset:29952
	s_waitcnt lgkmcnt(4)
; template <int RPL, int NSW>
; __device__ __forceinline__ void scan_item(const P& p, LAS unsigned char* lds, int seqbase, int L, int head, int dir, int part, int step0, int nsteps, int mode, float* qc, float* smid) {
;     ...
;             for (int s = 0; s < TC; ++s) {
;                 const f32x2 w0 = {xw[0], xw[1]}, w1 = {xw[2], xw[3]}, kd0 = {xkd[0], xkd[1]}, kd1 = {xkd[2], xkd[3]}, kk0 = {xkk[0], xkk[1]}, kk1 = {xkk[2], xkk[3]},
;                             b0 = {xb[0], xb[1]}, b1 = {xb[2], xb[3]}, r0 = {xr[0], xr[1]}, r1 = {xr[2], xr[3]};
;                 float vr[RPL];
; #pragma unroll
;                 for (int q = 0; q < RPL; ++q) vr[q] = vrow[q];
;                 { const int sn = (s + 1 < TC) ? s + 1 : s; SCAN_LD(sn); }
;                 float sa[RPL];
; #pragma unroll
;                 for (int q = 0; q < RPL; ++q) { const f32x2 t = S[q][0] * kk0 + S[q][1] * kk1; sa[q] = t.x + t.y; }
;                 if (RPL == 2) {
;                     sa[0] += dppx<0xB1>(sa[0]); sa[RPL - 1] += dppx<0xB1>(sa[RPL - 1]); sa[0] += dppx<0x4E>(sa[0]); sa[RPL - 1] += dppx<0x4E>(sa[RPL - 1]);
;                     sa[0] += dppx<0x141>(sa[0]); sa[RPL - 1] += dppx<0x141>(sa[RPL - 1]); sa[0] += dppx<0x140>(sa[0]); sa[RPL - 1] += dppx<0x140>(sa[RPL - 1]);
;                 } else {
; #pragma unroll
;                     for (int q = 0; q < RPL; ++q) sa[q] = reduce16(sa[q]);
;                 }
;                 float ov[RPL];
;                 if (RPL == 2) {
;                     const f32x2 vva = {vr[0], vr[0]}, nsa = {-sa[0], -sa[0]}, vvb = {vr[RPL - 1], vr[RPL - 1]}, nsb = {-sa[RPL - 1], -sa[RPL - 1]};
;                     f32x2 a0 = nsa * b0, c0 = nsb * b0, a1 = nsa * b1, c1 = nsb * b1;
;                     a0 = vva * kd0 + a0; c0 = vvb * kd0 + c0; a1 = vva * kd1 + a1; c1 = vvb * kd1 + c1;
;                     S[0][0] = S[0][0] * w0 + a0; S[RPL - 1][0] = S[RPL - 1][0] * w0 + c0; S[0][1] = S[0][1] * w1 + a1; S[RPL - 1][1] = S[RPL - 1][1] * w1 + c1;
;                     f32x2 ua = S[0][0] * r0, ub = S[RPL - 1][0] * r0;
;                     ua = S[0][1] * r1 + ua; ub = S[RPL - 1][1] * r1 + ub;
;                     ov[0] = ua.x + ua.y; ov[RPL - 1] = ub.x + ub.y;
;                 } else {
; #pragma unroll
;                 for (int q = 0; q < RPL; ++q) {
;                     const f32x2 vv = {vr[q], vr[q]}, ns = {-sa[q], -sa[q]};
	v_pk_mul_f32 v[128:129], v[118:119], v[98:99] op_sel:[0,1]
	v_pk_mul_f32 v[130:131], v[118:119], v[82:83] op_sel:[0,1]
	v_pk_fma_f32 v[128:129], v[116:117], v[98:99], v[128:129] op_sel_hi:[1,0,1]
	v_pk_fma_f32 v[130:131], v[116:117], v[82:83], v[130:131] op_sel_hi:[1,0,1]
	ds_read_b128 v[24:27], v134 offset:38144
	v_pk_fma_f32 v[128:129], v[114:115], v[96:97], v[128:129] op_sel:[0,1,0]
	v_pk_fma_f32 v[130:131], v[114:115], v[80:81], v[130:131] op_sel:[0,1,0]
	v_pk_fma_f32 v[128:129], v[112:113], v[96:97], v[128:129] op_sel_hi:[1,0,1]
	v_pk_fma_f32 v[130:131], v[112:113], v[80:81], v[130:131] op_sel_hi:[1,0,1]
	ds_read_b128 v[16:19], v134 offset:21760
	v_add_f32_dpp v128, v128, v128 quad_perm:[1,0,3,2] row_mask:0xf bank_mask:0xf bound_ctrl:1
	v_add_f32_dpp v129, v129, v129 quad_perm:[1,0,3,2] row_mask:0xf bank_mask:0xf bound_ctrl:1
	v_add_f32_dpp v130, v130, v130 quad_perm:[1,0,3,2] row_mask:0xf bank_mask:0xf bound_ctrl:1
	v_add_f32_dpp v131, v131, v131 quad_perm:[1,0,3,2] row_mask:0xf bank_mask:0xf bound_ctrl:1
	ds_read_b128 v[12:15], v134 offset:13568
	v_add_f32_dpp v128, v128, v128 quad_perm:[2,3,0,1] row_mask:0xf bank_mask:0xf bound_ctrl:1
	v_add_f32_dpp v129, v129, v129 quad_perm:[2,3,0,1] row_mask:0xf bank_mask:0xf bound_ctrl:1
	v_add_f32_dpp v130, v130, v130 quad_perm:[2,3,0,1] row_mask:0xf bank_mask:0xf bound_ctrl:1
	v_add_f32_dpp v131, v131, v131 quad_perm:[2,3,0,1] row_mask:0xf bank_mask:0xf bound_ctrl:1
	s_waitcnt lgkmcnt(4)
	v_pk_mul_f32 v[126:127], v[156:157], v[94:95] op_sel:[0,1]
	v_pk_mul_f32 v[124:125], v[156:157], v[94:95] op_sel_hi:[1,0]
	ds_read_b128 v[8:11], v134 offset:5376
	v_add_f32_dpp v128, v128, v128 row_half_mirror row_mask:0xf bank_mask:0xf bound_ctrl:1
	v_add_f32_dpp v129, v129, v129 row_half_mirror row_mask:0xf bank_mask:0xf bound_ctrl:1
	ds_write2_b32 v145, v130, v131 offset0:128 offset1:132
	v_pk_mul_f32 v[122:123], v[156:157], v[92:93] op_sel:[0,1]
	v_add_f32_dpp v132, v128, v128 row_mirror row_mask:0xf bank_mask:0xf bound_ctrl:1
	v_add_f32_dpp v133, v129, v129 row_mirror row_mask:0xf bank_mask:0xf bound_ctrl:1
	v_pk_mul_f32 v[120:121], v[156:157], v[92:93] op_sel_hi:[1,0]
	v_pk_fma_f32 v[118:119], v[118:119], v[90:91], v[126:127] op_sel:[0,1,0]
	v_pk_fma_f32 v[116:117], v[116:117], v[90:91], v[124:125] op_sel_hi:[1,0,1]
	v_pk_fma_f32 v[114:115], v[114:115], v[88:89], v[122:123] op_sel:[0,1,0]
	v_pk_fma_f32 v[112:113], v[112:113], v[88:89], v[120:121] op_sel_hi:[1,0,1]
	v_pk_fma_f32 v[118:119], v[102:103], v[132:133], v[118:119] op_sel:[1,0,0] neg_lo:[0,1,0] neg_hi:[0,1,0]
	v_pk_fma_f32 v[116:117], v[102:103], v[132:133], v[116:117] op_sel_hi:[0,1,1] neg_lo:[0,1,0] neg_hi:[0,1,0]
	v_pk_fma_f32 v[114:115], v[100:101], v[132:133], v[114:115] op_sel:[1,0,0] neg_lo:[0,1,0] neg_hi:[0,1,0]
	v_pk_fma_f32 v[112:113], v[100:101], v[132:133], v[112:113] op_sel_hi:[0,1,1] neg_lo:[0,1,0] neg_hi:[0,1,0]
	ds_read_b128 v[76:79], v134 offset:30208
	s_waitcnt lgkmcnt(4)
	v_pk_mul_f32 v[128:129], v[118:119], v[18:19] op_sel:[0,1]
	v_pk_mul_f32 v[130:131], v[118:119], v[106:107] op_sel:[0,1]
	v_pk_fma_f32 v[128:129], v[116:117], v[18:19], v[128:129] op_sel_hi:[1,0,1]
	v_pk_fma_f32 v[130:131], v[116:117], v[106:107], v[130:131] op_sel_hi:[1,0,1]
	ds_read_b128 v[80:83], v134 offset:38400
	v_pk_fma_f32 v[128:129], v[114:115], v[16:17], v[128:129] op_sel:[0,1,0]
	v_pk_fma_f32 v[130:131], v[114:115], v[104:105], v[130:131] op_sel:[0,1,0]
	v_pk_fma_f32 v[128:129], v[112:113], v[16:17], v[128:129] op_sel_hi:[1,0,1]
	v_pk_fma_f32 v[130:131], v[112:113], v[104:105], v[130:131] op_sel_hi:[1,0,1]
	ds_read_b128 v[72:75], v134 offset:22016
	v_add_f32_dpp v128, v128, v128 quad_perm:[1,0,3,2] row_mask:0xf bank_mask:0xf bound_ctrl:1
	v_add_f32_dpp v129, v129, v129 quad_perm:[1,0,3,2] row_mask:0xf bank_mask:0xf bound_ctrl:1
	v_add_f32_dpp v130, v130, v130 quad_perm:[1,0,3,2] row_mask:0xf bank_mask:0xf bound_ctrl:1
	v_add_f32_dpp v131, v131, v131 quad_perm:[1,0,3,2] row_mask:0xf bank_mask:0xf bound_ctrl:1
	ds_read_b128 v[68:71], v134 offset:13824
	v_add_f32_dpp v128, v128, v128 quad_perm:[2,3,0,1] row_mask:0xf bank_mask:0xf bound_ctrl:1
	v_add_f32_dpp v129, v129, v129 quad_perm:[2,3,0,1] row_mask:0xf bank_mask:0xf bound_ctrl:1
	v_add_f32_dpp v130, v130, v130 quad_perm:[2,3,0,1] row_mask:0xf bank_mask:0xf bound_ctrl:1
	v_add_f32_dpp v131, v131, v131 quad_perm:[2,3,0,1] row_mask:0xf bank_mask:0xf bound_ctrl:1
	s_waitcnt lgkmcnt(4)
	v_pk_mul_f32 v[126:127], v[158:159], v[14:15] op_sel:[0,1]
	v_pk_mul_f32 v[124:125], v[158:159], v[14:15] op_sel_hi:[1,0]
	ds_read2_b64 v[160:163], v111 offset0:96 offset1:112
	v_add_f32_dpp v128, v128, v128 row_half_mirror row_mask:0xf bank_mask:0xf bound_ctrl:1
	v_add_f32_dpp v129, v129, v129 row_half_mirror row_mask:0xf bank_mask:0xf bound_ctrl:1
	ds_write2_b32 v146, v130, v131 offset0:0 offset1:4
	v_pk_mul_f32 v[122:123], v[158:159], v[12:13] op_sel:[0,1]
	v_add_f32_dpp v132, v128, v128 row_mirror row_mask:0xf bank_mask:0xf bound_ctrl:1
	v_add_f32_dpp v133, v129, v129 row_mirror row_mask:0xf bank_mask:0xf bound_ctrl:1
	v_pk_mul_f32 v[120:121], v[158:159], v[12:13] op_sel_hi:[1,0]
	ds_read_b128 v[64:67], v134 offset:5632
	v_pk_fma_f32 v[118:119], v[118:119], v[10:11], v[126:127] op_sel:[0,1,0]
	v_pk_fma_f32 v[116:117], v[116:117], v[10:11], v[124:125] op_sel_hi:[1,0,1]
	v_pk_fma_f32 v[114:115], v[114:115], v[8:9], v[122:123] op_sel:[0,1,0]
	v_pk_fma_f32 v[112:113], v[112:113], v[8:9], v[120:121] op_sel_hi:[1,0,1]
	v_pk_fma_f32 v[118:119], v[22:23], v[132:133], v[118:119] op_sel:[1,0,0] neg_lo:[0,1,0] neg_hi:[0,1,0]
	v_pk_fma_f32 v[116:117], v[22:23], v[132:133], v[116:117] op_sel_hi:[0,1,1] neg_lo:[0,1,0] neg_hi:[0,1,0]
	v_pk_fma_f32 v[114:115], v[20:21], v[132:133], v[114:115] op_sel:[1,0,0] neg_lo:[0,1,0] neg_hi:[0,1,0]
	v_pk_fma_f32 v[112:113], v[20:21], v[132:133], v[112:113] op_sel_hi:[0,1,1] neg_lo:[0,1,0] neg_hi:[0,1,0]
	ds_read_b128 v[100:103], v134 offset:30464
	s_waitcnt lgkmcnt(4)
; template <int RPL, int NSW>
; __device__ __forceinline__ void scan_item(const P& p, LAS unsigned char* lds, int seqbase, int L, int head, int dir, int part, int step0, int nsteps, int mode, float* qc, float* smid) {
;     ...
;             for (int s = 0; s < TC; ++s) {
;                 const f32x2 w0 = {xw[0], xw[1]}, w1 = {xw[2], xw[3]}, kd0 = {xkd[0], xkd[1]}, kd1 = {xkd[2], xkd[3]}, kk0 = {xkk[0], xkk[1]}, kk1 = {xkk[2], xkk[3]},
;                             b0 = {xb[0], xb[1]}, b1 = {xb[2], xb[3]}, r0 = {xr[0], xr[1]}, r1 = {xr[2], xr[3]};
;                 float vr[RPL];
; #pragma unroll
;                 for (int q = 0; q < RPL; ++q) vr[q] = vrow[q];
;                 { const int sn = (s + 1 < TC) ? s + 1 : s; SCAN_LD(sn); }
;                 float sa[RPL];
; #pragma unroll
;                 for (int q = 0; q < RPL; ++q) { const f32x2 t = S[q][0] * kk0 + S[q][1] * kk1; sa[q] = t.x + t.y; }
;                 if (RPL == 2) {
;                     sa[0] += dppx<0xB1>(sa[0]); sa[RPL - 1] += dppx<0xB1>(sa[RPL - 1]); sa[0] += dppx<0x4E>(sa[0]); sa[RPL - 1] += dppx<0x4E>(sa[RPL - 1]);
;                     sa[0] += dppx<0x141>(sa[0]); sa[RPL - 1] += dppx<0x141>(sa[RPL - 1]); sa[0] += dppx<0x140>(sa[0]); sa[RPL - 1] += dppx<0x140>(sa[RPL - 1]);
;                 } else {
; #pragma unroll
;                     for (int q = 0; q < RPL; ++q) sa[q] = reduce16(sa[q]);
;                 }
;                 float ov[RPL];
;                 if (RPL == 2) {
;                     const f32x2 vva = {vr[0], vr[0]}, nsa = {-sa[0], -sa[0]}, vvb = {vr[RPL - 1], vr[RPL - 1]}, nsb = {-sa[RPL - 1], -sa[RPL - 1]};
;                     f32x2 a0 = nsa * b0, c0 = nsb * b0, a1 = nsa * b1, c1 = nsb * b1;
;                     a0 = vva * kd0 + a0; c0 = vvb * kd0 + c0; a1 = vva * kd1 + a1; c1 = vvb * kd1 + c1;
;                     S[0][0] = S[0][0] * w0 + a0; S[RPL - 1][0] = S[RPL - 1][0] * w0 + c0; S[0][1] = S[0][1] * w1 + a1; S[RPL - 1][1] = S[RPL - 1][1] * w1 + c1;
;                     f32x2 ua = S[0][0] * r0, ub = S[RPL - 1][0] * r0;
;                     ua = S[0][1] * r1 + ua; ub = S[RPL - 1][1] * r1 + ub;
;                     ov[0] = ua.x + ua.y; ov[RPL - 1] = ub.x + ub.y;
;                 } else {
; #pragma unroll
;                 for (int q = 0; q < RPL; ++q) {
;                     const f32x2 vv = {vr[q], vr[q]}, ns = {-sa[q], -sa[q]};
	v_pk_mul_f32 v[128:129], v[118:119], v[74:75] op_sel:[0,1]
	v_pk_mul_f32 v[130:131], v[118:119], v[26:27] op_sel:[0,1]
	v_pk_fma_f32 v[128:129], v[116:117], v[74:75], v[128:129] op_sel_hi:[1,0,1]
	v_pk_fma_f32 v[130:131], v[116:117], v[26:27], v[130:131] op_sel_hi:[1,0,1]
	ds_read_b128 v[104:107], v134 offset:38656
	v_pk_fma_f32 v[128:129], v[114:115], v[72:73], v[128:129] op_sel:[0,1,0]
	v_pk_fma_f32 v[130:131], v[114:115], v[24:25], v[130:131] op_sel:[0,1,0]
	v_pk_fma_f32 v[128:129], v[112:113], v[72:73], v[128:129] op_sel_hi:[1,0,1]
	v_pk_fma_f32 v[130:131], v[112:113], v[24:25], v[130:131] op_sel_hi:[1,0,1]
	ds_read_b128 v[96:99], v134 offset:22272
	v_add_f32_dpp v128, v128, v128 quad_perm:[1,0,3,2] row_mask:0xf bank_mask:0xf bound_ctrl:1
	v_add_f32_dpp v129, v129, v129 quad_perm:[1,0,3,2] row_mask:0xf bank_mask:0xf bound_ctrl:1
	v_add_f32_dpp v130, v130, v130 quad_perm:[1,0,3,2] row_mask:0xf bank_mask:0xf bound_ctrl:1
	v_add_f32_dpp v131, v131, v131 quad_perm:[1,0,3,2] row_mask:0xf bank_mask:0xf bound_ctrl:1
	ds_read_b128 v[92:95], v134 offset:14080
	v_add_f32_dpp v128, v128, v128 quad_perm:[2,3,0,1] row_mask:0xf bank_mask:0xf bound_ctrl:1
	v_add_f32_dpp v129, v129, v129 quad_perm:[2,3,0,1] row_mask:0xf bank_mask:0xf bound_ctrl:1
	v_add_f32_dpp v130, v130, v130 quad_perm:[2,3,0,1] row_mask:0xf bank_mask:0xf bound_ctrl:1
	v_add_f32_dpp v131, v131, v131 quad_perm:[2,3,0,1] row_mask:0xf bank_mask:0xf bound_ctrl:1
	s_waitcnt lgkmcnt(4)
	v_pk_mul_f32 v[126:127], v[160:161], v[70:71] op_sel:[0,1]
	v_pk_mul_f32 v[124:125], v[160:161], v[70:71] op_sel_hi:[1,0]
	ds_read_b128 v[88:91], v134 offset:5888
	v_add_f32_dpp v128, v128, v128 row_half_mirror row_mask:0xf bank_mask:0xf bound_ctrl:1
	v_add_f32_dpp v129, v129, v129 row_half_mirror row_mask:0xf bank_mask:0xf bound_ctrl:1
	ds_write2_b32 v146, v130, v131 offset0:128 offset1:132
	v_pk_mul_f32 v[122:123], v[160:161], v[68:69] op_sel:[0,1]
	v_add_f32_dpp v132, v128, v128 row_mirror row_mask:0xf bank_mask:0xf bound_ctrl:1
	v_add_f32_dpp v133, v129, v129 row_mirror row_mask:0xf bank_mask:0xf bound_ctrl:1
	v_pk_mul_f32 v[120:121], v[160:161], v[68:69] op_sel_hi:[1,0]
	v_pk_fma_f32 v[118:119], v[118:119], v[66:67], v[126:127] op_sel:[0,1,0]
	v_pk_fma_f32 v[116:117], v[116:117], v[66:67], v[124:125] op_sel_hi:[1,0,1]
	v_pk_fma_f32 v[114:115], v[114:115], v[64:65], v[122:123] op_sel:[0,1,0]
	v_pk_fma_f32 v[112:113], v[112:113], v[64:65], v[120:121] op_sel_hi:[1,0,1]
	v_pk_fma_f32 v[118:119], v[78:79], v[132:133], v[118:119] op_sel:[1,0,0] neg_lo:[0,1,0] neg_hi:[0,1,0]
	v_pk_fma_f32 v[116:117], v[78:79], v[132:133], v[116:117] op_sel_hi:[0,1,1] neg_lo:[0,1,0] neg_hi:[0,1,0]
	v_pk_fma_f32 v[114:115], v[76:77], v[132:133], v[114:115] op_sel:[1,0,0] neg_lo:[0,1,0] neg_hi:[0,1,0]
	v_pk_fma_f32 v[112:113], v[76:77], v[132:133], v[112:113] op_sel_hi:[0,1,1] neg_lo:[0,1,0] neg_hi:[0,1,0]
	ds_read_b128 v[20:23], v134 offset:30720
	s_waitcnt lgkmcnt(4)
	v_pk_mul_f32 v[128:129], v[118:119], v[98:99] op_sel:[0,1]
	v_pk_mul_f32 v[130:131], v[118:119], v[82:83] op_sel:[0,1]
	v_pk_fma_f32 v[128:129], v[116:117], v[98:99], v[128:129] op_sel_hi:[1,0,1]
	v_pk_fma_f32 v[130:131], v[116:117], v[82:83], v[130:131] op_sel_hi:[1,0,1]
	ds_read_b128 v[24:27], v134 offset:38912
	v_pk_fma_f32 v[128:129], v[114:115], v[96:97], v[128:129] op_sel:[0,1,0]
	v_pk_fma_f32 v[130:131], v[114:115], v[80:81], v[130:131] op_sel:[0,1,0]
	v_pk_fma_f32 v[128:129], v[112:113], v[96:97], v[128:129] op_sel_hi:[1,0,1]
	v_pk_fma_f32 v[130:131], v[112:113], v[80:81], v[130:131] op_sel_hi:[1,0,1]
	ds_read_b128 v[16:19], v134 offset:22528
	v_add_f32_dpp v128, v128, v128 quad_perm:[1,0,3,2] row_mask:0xf bank_mask:0xf bound_ctrl:1
	v_add_f32_dpp v129, v129, v129 quad_perm:[1,0,3,2] row_mask:0xf bank_mask:0xf bound_ctrl:1
	v_add_f32_dpp v130, v130, v130 quad_perm:[1,0,3,2] row_mask:0xf bank_mask:0xf bound_ctrl:1
	v_add_f32_dpp v131, v131, v131 quad_perm:[1,0,3,2] row_mask:0xf bank_mask:0xf bound_ctrl:1
	ds_read_b128 v[12:15], v134 offset:14336
	v_add_f32_dpp v128, v128, v128 quad_perm:[2,3,0,1] row_mask:0xf bank_mask:0xf bound_ctrl:1
	v_add_f32_dpp v129, v129, v129 quad_perm:[2,3,0,1] row_mask:0xf bank_mask:0xf bound_ctrl:1
	v_add_f32_dpp v130, v130, v130 quad_perm:[2,3,0,1] row_mask:0xf bank_mask:0xf bound_ctrl:1
	v_add_f32_dpp v131, v131, v131 quad_perm:[2,3,0,1] row_mask:0xf bank_mask:0xf bound_ctrl:1
	s_waitcnt lgkmcnt(4)
	v_pk_mul_f32 v[126:127], v[162:163], v[94:95] op_sel:[0,1]
	v_pk_mul_f32 v[124:125], v[162:163], v[94:95] op_sel_hi:[1,0]
	ds_read2_b64 v[156:159], v111 offset0:128 offset1:144
	v_add_f32_dpp v128, v128, v128 row_half_mirror row_mask:0xf bank_mask:0xf bound_ctrl:1
	v_add_f32_dpp v129, v129, v129 row_half_mirror row_mask:0xf bank_mask:0xf bound_ctrl:1
	ds_write2_b32 v147, v130, v131 offset0:0 offset1:4
	v_pk_mul_f32 v[122:123], v[162:163], v[92:93] op_sel:[0,1]
	v_add_f32_dpp v132, v128, v128 row_mirror row_mask:0xf bank_mask:0xf bound_ctrl:1
	v_add_f32_dpp v133, v129, v129 row_mirror row_mask:0xf bank_mask:0xf bound_ctrl:1
	v_pk_mul_f32 v[120:121], v[162:163], v[92:93] op_sel_hi:[1,0]
	ds_read_b128 v[8:11], v134 offset:6144
	v_pk_fma_f32 v[118:119], v[118:119], v[90:91], v[126:127] op_sel:[0,1,0]
	v_pk_fma_f32 v[116:117], v[116:117], v[90:91], v[124:125] op_sel_hi:[1,0,1]
	v_pk_fma_f32 v[114:115], v[114:115], v[88:89], v[122:123] op_sel:[0,1,0]
	v_pk_fma_f32 v[112:113], v[112:113], v[88:89], v[120:121] op_sel_hi:[1,0,1]
	v_pk_fma_f32 v[118:119], v[102:103], v[132:133], v[118:119] op_sel:[1,0,0] neg_lo:[0,1,0] neg_hi:[0,1,0]
	v_pk_fma_f32 v[116:117], v[102:103], v[132:133], v[116:117] op_sel_hi:[0,1,1] neg_lo:[0,1,0] neg_hi:[0,1,0]
	v_pk_fma_f32 v[114:115], v[100:101], v[132:133], v[114:115] op_sel:[1,0,0] neg_lo:[0,1,0] neg_hi:[0,1,0]
	v_pk_fma_f32 v[112:113], v[100:101], v[132:133], v[112:113] op_sel_hi:[0,1,1] neg_lo:[0,1,0] neg_hi:[0,1,0]
	ds_read_b128 v[76:79], v134 offset:30976
	s_waitcnt lgkmcnt(4)
; template <int RPL, int NSW>
; __device__ __forceinline__ void scan_item(const P& p, LAS unsigned char* lds, int seqbase, int L, int head, int dir, int part, int step0, int nsteps, int mode, float* qc, float* smid) {
;     ...
;             for (int s = 0; s < TC; ++s) {
;                 const f32x2 w0 = {xw[0], xw[1]}, w1 = {xw[2], xw[3]}, kd0 = {xkd[0], xkd[1]}, kd1 = {xkd[2], xkd[3]}, kk0 = {xkk[0], xkk[1]}, kk1 = {xkk[2], xkk[3]},
;                             b0 = {xb[0], xb[1]}, b1 = {xb[2], xb[3]}, r0 = {xr[0], xr[1]}, r1 = {xr[2], xr[3]};
;                 float vr[RPL];
; #pragma unroll
;                 for (int q = 0; q < RPL; ++q) vr[q] = vrow[q];
;                 { const int sn = (s + 1 < TC) ? s + 1 : s; SCAN_LD(sn); }
;                 float sa[RPL];
; #pragma unroll
;                 for (int q = 0; q < RPL; ++q) { const f32x2 t = S[q][0] * kk0 + S[q][1] * kk1; sa[q] = t.x + t.y; }
;                 if (RPL == 2) {
;                     sa[0] += dppx<0xB1>(sa[0]); sa[RPL - 1] += dppx<0xB1>(sa[RPL - 1]); sa[0] += dppx<0x4E>(sa[0]); sa[RPL - 1] += dppx<0x4E>(sa[RPL - 1]);
;                     sa[0] += dppx<0x141>(sa[0]); sa[RPL - 1] += dppx<0x141>(sa[RPL - 1]); sa[0] += dppx<0x140>(sa[0]); sa[RPL - 1] += dppx<0x140>(sa[RPL - 1]);
;                 } else {
; #pragma unroll
;                     for (int q = 0; q < RPL; ++q) sa[q] = reduce16(sa[q]);
;                 }
;                 float ov[RPL];
;                 if (RPL == 2) {
;                     const f32x2 vva = {vr[0], vr[0]}, nsa = {-sa[0], -sa[0]}, vvb = {vr[RPL - 1], vr[RPL - 1]}, nsb = {-sa[RPL - 1], -sa[RPL - 1]};
;                     f32x2 a0 = nsa * b0, c0 = nsb * b0, a1 = nsa * b1, c1 = nsb * b1;
;                     a0 = vva * kd0 + a0; c0 = vvb * kd0 + c0; a1 = vva * kd1 + a1; c1 = vvb * kd1 + c1;
;                     S[0][0] = S[0][0] * w0 + a0; S[RPL - 1][0] = S[RPL - 1][0] * w0 + c0; S[0][1] = S[0][1] * w1 + a1; S[RPL - 1][1] = S[RPL - 1][1] * w1 + c1;
;                     f32x2 ua = S[0][0] * r0, ub = S[RPL - 1][0] * r0;
;                     ua = S[0][1] * r1 + ua; ub = S[RPL - 1][1] * r1 + ub;
;                     ov[0] = ua.x + ua.y; ov[RPL - 1] = ub.x + ub.y;
;                 } else {
; #pragma unroll
;                 for (int q = 0; q < RPL; ++q) {
;                     const f32x2 vv = {vr[q], vr[q]}, ns = {-sa[q], -sa[q]};
	v_pk_mul_f32 v[128:129], v[118:119], v[18:19] op_sel:[0,1]
	v_pk_mul_f32 v[130:131], v[118:119], v[106:107] op_sel:[0,1]
	v_pk_fma_f32 v[128:129], v[116:117], v[18:19], v[128:129] op_sel_hi:[1,0,1]
	v_pk_fma_f32 v[130:131], v[116:117], v[106:107], v[130:131] op_sel_hi:[1,0,1]
	ds_read_b128 v[80:83], v134 offset:39168
	v_pk_fma_f32 v[128:129], v[114:115], v[16:17], v[128:129] op_sel:[0,1,0]
	v_pk_fma_f32 v[130:131], v[114:115], v[104:105], v[130:131] op_sel:[0,1,0]
	v_pk_fma_f32 v[128:129], v[112:113], v[16:17], v[128:129] op_sel_hi:[1,0,1]
	v_pk_fma_f32 v[130:131], v[112:113], v[104:105], v[130:131] op_sel_hi:[1,0,1]
	ds_read_b128 v[72:75], v134 offset:22784
	v_add_f32_dpp v128, v128, v128 quad_perm:[1,0,3,2] row_mask:0xf bank_mask:0xf bound_ctrl:1
	v_add_f32_dpp v129, v129, v129 quad_perm:[1,0,3,2] row_mask:0xf bank_mask:0xf bound_ctrl:1
	v_add_f32_dpp v130, v130, v130 quad_perm:[1,0,3,2] row_mask:0xf bank_mask:0xf bound_ctrl:1
	v_add_f32_dpp v131, v131, v131 quad_perm:[1,0,3,2] row_mask:0xf bank_mask:0xf bound_ctrl:1
	ds_read_b128 v[68:71], v134 offset:14592
	v_add_f32_dpp v128, v128, v128 quad_perm:[2,3,0,1] row_mask:0xf bank_mask:0xf bound_ctrl:1
	v_add_f32_dpp v129, v129, v129 quad_perm:[2,3,0,1] row_mask:0xf bank_mask:0xf bound_ctrl:1
	v_add_f32_dpp v130, v130, v130 quad_perm:[2,3,0,1] row_mask:0xf bank_mask:0xf bound_ctrl:1
	v_add_f32_dpp v131, v131, v131 quad_perm:[2,3,0,1] row_mask:0xf bank_mask:0xf bound_ctrl:1
	s_waitcnt lgkmcnt(4)
	v_pk_mul_f32 v[126:127], v[156:157], v[14:15] op_sel:[0,1]
	v_pk_mul_f32 v[124:125], v[156:157], v[14:15] op_sel_hi:[1,0]
	ds_read_b128 v[64:67], v134 offset:6400
	v_add_f32_dpp v128, v128, v128 row_half_mirror row_mask:0xf bank_mask:0xf bound_ctrl:1
	v_add_f32_dpp v129, v129, v129 row_half_mirror row_mask:0xf bank_mask:0xf bound_ctrl:1
	ds_write2_b32 v147, v130, v131 offset0:128 offset1:132
	v_pk_mul_f32 v[122:123], v[156:157], v[12:13] op_sel:[0,1]
	v_add_f32_dpp v132, v128, v128 row_mirror row_mask:0xf bank_mask:0xf bound_ctrl:1
	v_add_f32_dpp v133, v129, v129 row_mirror row_mask:0xf bank_mask:0xf bound_ctrl:1
	v_pk_mul_f32 v[120:121], v[156:157], v[12:13] op_sel_hi:[1,0]
	v_pk_fma_f32 v[118:119], v[118:119], v[10:11], v[126:127] op_sel:[0,1,0]
	v_pk_fma_f32 v[116:117], v[116:117], v[10:11], v[124:125] op_sel_hi:[1,0,1]
	v_pk_fma_f32 v[114:115], v[114:115], v[8:9], v[122:123] op_sel:[0,1,0]
	v_pk_fma_f32 v[112:113], v[112:113], v[8:9], v[120:121] op_sel_hi:[1,0,1]
	v_pk_fma_f32 v[118:119], v[22:23], v[132:133], v[118:119] op_sel:[1,0,0] neg_lo:[0,1,0] neg_hi:[0,1,0]
	v_pk_fma_f32 v[116:117], v[22:23], v[132:133], v[116:117] op_sel_hi:[0,1,1] neg_lo:[0,1,0] neg_hi:[0,1,0]
	v_pk_fma_f32 v[114:115], v[20:21], v[132:133], v[114:115] op_sel:[1,0,0] neg_lo:[0,1,0] neg_hi:[0,1,0]
	v_pk_fma_f32 v[112:113], v[20:21], v[132:133], v[112:113] op_sel_hi:[0,1,1] neg_lo:[0,1,0] neg_hi:[0,1,0]
	ds_read_b128 v[100:103], v134 offset:31232
	s_waitcnt lgkmcnt(4)
	v_pk_mul_f32 v[128:129], v[118:119], v[74:75] op_sel:[0,1]
	v_pk_mul_f32 v[130:131], v[118:119], v[26:27] op_sel:[0,1]
	v_pk_fma_f32 v[128:129], v[116:117], v[74:75], v[128:129] op_sel_hi:[1,0,1]
	v_pk_fma_f32 v[130:131], v[116:117], v[26:27], v[130:131] op_sel_hi:[1,0,1]
	ds_read_b128 v[104:107], v134 offset:39424
	v_pk_fma_f32 v[128:129], v[114:115], v[72:73], v[128:129] op_sel:[0,1,0]
	v_pk_fma_f32 v[130:131], v[114:115], v[24:25], v[130:131] op_sel:[0,1,0]
	v_pk_fma_f32 v[128:129], v[112:113], v[72:73], v[128:129] op_sel_hi:[1,0,1]
	v_pk_fma_f32 v[130:131], v[112:113], v[24:25], v[130:131] op_sel_hi:[1,0,1]
	ds_read_b128 v[96:99], v134 offset:23040
	v_add_f32_dpp v128, v128, v128 quad_perm:[1,0,3,2] row_mask:0xf bank_mask:0xf bound_ctrl:1
	v_add_f32_dpp v129, v129, v129 quad_perm:[1,0,3,2] row_mask:0xf bank_mask:0xf bound_ctrl:1
	v_add_f32_dpp v130, v130, v130 quad_perm:[1,0,3,2] row_mask:0xf bank_mask:0xf bound_ctrl:1
	v_add_f32_dpp v131, v131, v131 quad_perm:[1,0,3,2] row_mask:0xf bank_mask:0xf bound_ctrl:1
	ds_read_b128 v[92:95], v134 offset:14848
	v_add_f32_dpp v128, v128, v128 quad_perm:[2,3,0,1] row_mask:0xf bank_mask:0xf bound_ctrl:1
	v_add_f32_dpp v129, v129, v129 quad_perm:[2,3,0,1] row_mask:0xf bank_mask:0xf bound_ctrl:1
	v_add_f32_dpp v130, v130, v130 quad_perm:[2,3,0,1] row_mask:0xf bank_mask:0xf bound_ctrl:1
	v_add_f32_dpp v131, v131, v131 quad_perm:[2,3,0,1] row_mask:0xf bank_mask:0xf bound_ctrl:1
	s_waitcnt lgkmcnt(4)
	v_pk_mul_f32 v[126:127], v[158:159], v[70:71] op_sel:[0,1]
	v_pk_mul_f32 v[124:125], v[158:159], v[70:71] op_sel_hi:[1,0]
	ds_read2_b64 v[160:163], v111 offset0:160 offset1:176
	v_add_f32_dpp v128, v128, v128 row_half_mirror row_mask:0xf bank_mask:0xf bound_ctrl:1
	v_add_f32_dpp v129, v129, v129 row_half_mirror row_mask:0xf bank_mask:0xf bound_ctrl:1
	ds_write2_b32 v148, v130, v131 offset0:0 offset1:4
	v_pk_mul_f32 v[122:123], v[158:159], v[68:69] op_sel:[0,1]
	v_add_f32_dpp v132, v128, v128 row_mirror row_mask:0xf bank_mask:0xf bound_ctrl:1
	v_add_f32_dpp v133, v129, v129 row_mirror row_mask:0xf bank_mask:0xf bound_ctrl:1
	v_pk_mul_f32 v[120:121], v[158:159], v[68:69] op_sel_hi:[1,0]
	ds_read_b128 v[88:91], v134 offset:6656
	v_pk_fma_f32 v[118:119], v[118:119], v[66:67], v[126:127] op_sel:[0,1,0]
	v_pk_fma_f32 v[116:117], v[116:117], v[66:67], v[124:125] op_sel_hi:[1,0,1]
	v_pk_fma_f32 v[114:115], v[114:115], v[64:65], v[122:123] op_sel:[0,1,0]
	v_pk_fma_f32 v[112:113], v[112:113], v[64:65], v[120:121] op_sel_hi:[1,0,1]
	v_pk_fma_f32 v[118:119], v[78:79], v[132:133], v[118:119] op_sel:[1,0,0] neg_lo:[0,1,0] neg_hi:[0,1,0]
	v_pk_fma_f32 v[116:117], v[78:79], v[132:133], v[116:117] op_sel_hi:[0,1,1] neg_lo:[0,1,0] neg_hi:[0,1,0]
	v_pk_fma_f32 v[114:115], v[76:77], v[132:133], v[114:115] op_sel:[1,0,0] neg_lo:[0,1,0] neg_hi:[0,1,0]
	v_pk_fma_f32 v[112:113], v[76:77], v[132:133], v[112:113] op_sel_hi:[0,1,1] neg_lo:[0,1,0] neg_hi:[0,1,0]
	ds_read_b128 v[20:23], v134 offset:31488
	s_waitcnt lgkmcnt(4)
; template <int RPL, int NSW>
; __device__ __forceinline__ void scan_item(const P& p, LAS unsigned char* lds, int seqbase, int L, int head, int dir, int part, int step0, int nsteps, int mode, float* qc, float* smid) {
;     ...
;             for (int s = 0; s < TC; ++s) {
;                 const f32x2 w0 = {xw[0], xw[1]}, w1 = {xw[2], xw[3]}, kd0 = {xkd[0], xkd[1]}, kd1 = {xkd[2], xkd[3]}, kk0 = {xkk[0], xkk[1]}, kk1 = {xkk[2], xkk[3]},
;                             b0 = {xb[0], xb[1]}, b1 = {xb[2], xb[3]}, r0 = {xr[0], xr[1]}, r1 = {xr[2], xr[3]};
;                 float vr[RPL];
; #pragma unroll
;                 for (int q = 0; q < RPL; ++q) vr[q] = vrow[q];
;                 { const int sn = (s + 1 < TC) ? s + 1 : s; SCAN_LD(sn); }
;                 float sa[RPL];
; #pragma unroll
;                 for (int q = 0; q < RPL; ++q) { const f32x2 t = S[q][0] * kk0 + S[q][1] * kk1; sa[q] = t.x + t.y; }
;                 if (RPL == 2) {
;                     sa[0] += dppx<0xB1>(sa[0]); sa[RPL - 1] += dppx<0xB1>(sa[RPL - 1]); sa[0] += dppx<0x4E>(sa[0]); sa[RPL - 1] += dppx<0x4E>(sa[RPL - 1]);
;                     sa[0] += dppx<0x141>(sa[0]); sa[RPL - 1] += dppx<0x141>(sa[RPL - 1]); sa[0] += dppx<0x140>(sa[0]); sa[RPL - 1] += dppx<0x140>(sa[RPL - 1]);
;                 } else {
; #pragma unroll
;                     for (int q = 0; q < RPL; ++q) sa[q] = reduce16(sa[q]);
;                 }
;                 float ov[RPL];
;                 if (RPL == 2) {
;                     const f32x2 vva = {vr[0], vr[0]}, nsa = {-sa[0], -sa[0]}, vvb = {vr[RPL - 1], vr[RPL - 1]}, nsb = {-sa[RPL - 1], -sa[RPL - 1]};
;                     f32x2 a0 = nsa * b0, c0 = nsb * b0, a1 = nsa * b1, c1 = nsb * b1;
;                     a0 = vva * kd0 + a0; c0 = vvb * kd0 + c0; a1 = vva * kd1 + a1; c1 = vvb * kd1 + c1;
;                     S[0][0] = S[0][0] * w0 + a0; S[RPL - 1][0] = S[RPL - 1][0] * w0 + c0; S[0][1] = S[0][1] * w1 + a1; S[RPL - 1][1] = S[RPL - 1][1] * w1 + c1;
;                     f32x2 ua = S[0][0] * r0, ub = S[RPL - 1][0] * r0;
;                     ua = S[0][1] * r1 + ua; ub = S[RPL - 1][1] * r1 + ub;
;                     ov[0] = ua.x + ua.y; ov[RPL - 1] = ub.x + ub.y;
;                 } else {
; #pragma unroll
;                 for (int q = 0; q < RPL; ++q) {
;                     const f32x2 vv = {vr[q], vr[q]}, ns = {-sa[q], -sa[q]};
	v_pk_mul_f32 v[128:129], v[118:119], v[98:99] op_sel:[0,1]
	v_pk_mul_f32 v[130:131], v[118:119], v[82:83] op_sel:[0,1]
	v_pk_fma_f32 v[128:129], v[116:117], v[98:99], v[128:129] op_sel_hi:[1,0,1]
	v_pk_fma_f32 v[130:131], v[116:117], v[82:83], v[130:131] op_sel_hi:[1,0,1]
	ds_read_b128 v[24:27], v134 offset:39680
	v_pk_fma_f32 v[128:129], v[114:115], v[96:97], v[128:129] op_sel:[0,1,0]
	v_pk_fma_f32 v[130:131], v[114:115], v[80:81], v[130:131] op_sel:[0,1,0]
	v_pk_fma_f32 v[128:129], v[112:113], v[96:97], v[128:129] op_sel_hi:[1,0,1]
	v_pk_fma_f32 v[130:131], v[112:113], v[80:81], v[130:131] op_sel_hi:[1,0,1]
	ds_read_b128 v[16:19], v134 offset:23296
	v_add_f32_dpp v128, v128, v128 quad_perm:[1,0,3,2] row_mask:0xf bank_mask:0xf bound_ctrl:1
	v_add_f32_dpp v129, v129, v129 quad_perm:[1,0,3,2] row_mask:0xf bank_mask:0xf bound_ctrl:1
	v_add_f32_dpp v130, v130, v130 quad_perm:[1,0,3,2] row_mask:0xf bank_mask:0xf bound_ctrl:1
	v_add_f32_dpp v131, v131, v131 quad_perm:[1,0,3,2] row_mask:0xf bank_mask:0xf bound_ctrl:1
	ds_read_b128 v[12:15], v134 offset:15104
	v_add_f32_dpp v128, v128, v128 quad_perm:[2,3,0,1] row_mask:0xf bank_mask:0xf bound_ctrl:1
	v_add_f32_dpp v129, v129, v129 quad_perm:[2,3,0,1] row_mask:0xf bank_mask:0xf bound_ctrl:1
	v_add_f32_dpp v130, v130, v130 quad_perm:[2,3,0,1] row_mask:0xf bank_mask:0xf bound_ctrl:1
	v_add_f32_dpp v131, v131, v131 quad_perm:[2,3,0,1] row_mask:0xf bank_mask:0xf bound_ctrl:1
	s_waitcnt lgkmcnt(4)
	v_pk_mul_f32 v[126:127], v[160:161], v[94:95] op_sel:[0,1]
	v_pk_mul_f32 v[124:125], v[160:161], v[94:95] op_sel_hi:[1,0]
	ds_read_b128 v[8:11], v134 offset:6912
	v_add_f32_dpp v128, v128, v128 row_half_mirror row_mask:0xf bank_mask:0xf bound_ctrl:1
	v_add_f32_dpp v129, v129, v129 row_half_mirror row_mask:0xf bank_mask:0xf bound_ctrl:1
	ds_write2_b32 v148, v130, v131 offset0:128 offset1:132
	v_pk_mul_f32 v[122:123], v[160:161], v[92:93] op_sel:[0,1]
	v_add_f32_dpp v132, v128, v128 row_mirror row_mask:0xf bank_mask:0xf bound_ctrl:1
	v_add_f32_dpp v133, v129, v129 row_mirror row_mask:0xf bank_mask:0xf bound_ctrl:1
	v_pk_mul_f32 v[120:121], v[160:161], v[92:93] op_sel_hi:[1,0]
	v_pk_fma_f32 v[118:119], v[118:119], v[90:91], v[126:127] op_sel:[0,1,0]
	v_pk_fma_f32 v[116:117], v[116:117], v[90:91], v[124:125] op_sel_hi:[1,0,1]
	v_pk_fma_f32 v[114:115], v[114:115], v[88:89], v[122:123] op_sel:[0,1,0]
	v_pk_fma_f32 v[112:113], v[112:113], v[88:89], v[120:121] op_sel_hi:[1,0,1]
	v_pk_fma_f32 v[118:119], v[102:103], v[132:133], v[118:119] op_sel:[1,0,0] neg_lo:[0,1,0] neg_hi:[0,1,0]
	v_pk_fma_f32 v[116:117], v[102:103], v[132:133], v[116:117] op_sel_hi:[0,1,1] neg_lo:[0,1,0] neg_hi:[0,1,0]
	v_pk_fma_f32 v[114:115], v[100:101], v[132:133], v[114:115] op_sel:[1,0,0] neg_lo:[0,1,0] neg_hi:[0,1,0]
	v_pk_fma_f32 v[112:113], v[100:101], v[132:133], v[112:113] op_sel_hi:[0,1,1] neg_lo:[0,1,0] neg_hi:[0,1,0]
	ds_read_b128 v[76:79], v134 offset:31744
	s_waitcnt lgkmcnt(4)
	v_pk_mul_f32 v[128:129], v[118:119], v[18:19] op_sel:[0,1]
	v_pk_mul_f32 v[130:131], v[118:119], v[106:107] op_sel:[0,1]
	v_pk_fma_f32 v[128:129], v[116:117], v[18:19], v[128:129] op_sel_hi:[1,0,1]
	v_pk_fma_f32 v[130:131], v[116:117], v[106:107], v[130:131] op_sel_hi:[1,0,1]
	ds_read_b128 v[80:83], v134 offset:39936
	v_pk_fma_f32 v[128:129], v[114:115], v[16:17], v[128:129] op_sel:[0,1,0]
	v_pk_fma_f32 v[130:131], v[114:115], v[104:105], v[130:131] op_sel:[0,1,0]
	v_pk_fma_f32 v[128:129], v[112:113], v[16:17], v[128:129] op_sel_hi:[1,0,1]
	v_pk_fma_f32 v[130:131], v[112:113], v[104:105], v[130:131] op_sel_hi:[1,0,1]
	ds_read_b128 v[72:75], v134 offset:23552
	v_add_f32_dpp v128, v128, v128 quad_perm:[1,0,3,2] row_mask:0xf bank_mask:0xf bound_ctrl:1
	v_add_f32_dpp v129, v129, v129 quad_perm:[1,0,3,2] row_mask:0xf bank_mask:0xf bound_ctrl:1
	v_add_f32_dpp v130, v130, v130 quad_perm:[1,0,3,2] row_mask:0xf bank_mask:0xf bound_ctrl:1
	v_add_f32_dpp v131, v131, v131 quad_perm:[1,0,3,2] row_mask:0xf bank_mask:0xf bound_ctrl:1
	ds_read_b128 v[68:71], v134 offset:15360
	v_add_f32_dpp v128, v128, v128 quad_perm:[2,3,0,1] row_mask:0xf bank_mask:0xf bound_ctrl:1
	v_add_f32_dpp v129, v129, v129 quad_perm:[2,3,0,1] row_mask:0xf bank_mask:0xf bound_ctrl:1
	v_add_f32_dpp v130, v130, v130 quad_perm:[2,3,0,1] row_mask:0xf bank_mask:0xf bound_ctrl:1
	v_add_f32_dpp v131, v131, v131 quad_perm:[2,3,0,1] row_mask:0xf bank_mask:0xf bound_ctrl:1
	s_waitcnt lgkmcnt(4)
	v_pk_mul_f32 v[126:127], v[162:163], v[14:15] op_sel:[0,1]
	v_pk_mul_f32 v[124:125], v[162:163], v[14:15] op_sel_hi:[1,0]
	ds_read2_b64 v[156:159], v111 offset0:192 offset1:208
	v_add_f32_dpp v128, v128, v128 row_half_mirror row_mask:0xf bank_mask:0xf bound_ctrl:1
	v_add_f32_dpp v129, v129, v129 row_half_mirror row_mask:0xf bank_mask:0xf bound_ctrl:1
	ds_write2_b32 v149, v130, v131 offset0:0 offset1:4
	v_pk_mul_f32 v[122:123], v[162:163], v[12:13] op_sel:[0,1]
	v_add_f32_dpp v132, v128, v128 row_mirror row_mask:0xf bank_mask:0xf bound_ctrl:1
	v_add_f32_dpp v133, v129, v129 row_mirror row_mask:0xf bank_mask:0xf bound_ctrl:1
	v_pk_mul_f32 v[120:121], v[162:163], v[12:13] op_sel_hi:[1,0]
	ds_read_b128 v[64:67], v134 offset:7168
	v_pk_fma_f32 v[118:119], v[118:119], v[10:11], v[126:127] op_sel:[0,1,0]
	v_pk_fma_f32 v[116:117], v[116:117], v[10:11], v[124:125] op_sel_hi:[1,0,1]
	v_pk_fma_f32 v[114:115], v[114:115], v[8:9], v[122:123] op_sel:[0,1,0]
	v_pk_fma_f32 v[112:113], v[112:113], v[8:9], v[120:121] op_sel_hi:[1,0,1]
	v_pk_fma_f32 v[118:119], v[22:23], v[132:133], v[118:119] op_sel:[1,0,0] neg_lo:[0,1,0] neg_hi:[0,1,0]
	v_pk_fma_f32 v[116:117], v[22:23], v[132:133], v[116:117] op_sel_hi:[0,1,1] neg_lo:[0,1,0] neg_hi:[0,1,0]
	v_pk_fma_f32 v[114:115], v[20:21], v[132:133], v[114:115] op_sel:[1,0,0] neg_lo:[0,1,0] neg_hi:[0,1,0]
	v_pk_fma_f32 v[112:113], v[20:21], v[132:133], v[112:113] op_sel_hi:[0,1,1] neg_lo:[0,1,0] neg_hi:[0,1,0]
	ds_read_b128 v[100:103], v134 offset:32000
	s_waitcnt lgkmcnt(4)
; template <int RPL, int NSW>
; __device__ __forceinline__ void scan_item(const P& p, LAS unsigned char* lds, int seqbase, int L, int head, int dir, int part, int step0, int nsteps, int mode, float* qc, float* smid) {
;     ...
;             for (int s = 0; s < TC; ++s) {
;                 const f32x2 w0 = {xw[0], xw[1]}, w1 = {xw[2], xw[3]}, kd0 = {xkd[0], xkd[1]}, kd1 = {xkd[2], xkd[3]}, kk0 = {xkk[0], xkk[1]}, kk1 = {xkk[2], xkk[3]},
;                             b0 = {xb[0], xb[1]}, b1 = {xb[2], xb[3]}, r0 = {xr[0], xr[1]}, r1 = {xr[2], xr[3]};
;                 float vr[RPL];
; #pragma unroll
;                 for (int q = 0; q < RPL; ++q) vr[q] = vrow[q];
;                 { const int sn = (s + 1 < TC) ? s + 1 : s; SCAN_LD(sn); }
;                 float sa[RPL];
; #pragma unroll
;                 for (int q = 0; q < RPL; ++q) { const f32x2 t = S[q][0] * kk0 + S[q][1] * kk1; sa[q] = t.x + t.y; }
;                 if (RPL == 2) {
;                     sa[0] += dppx<0xB1>(sa[0]); sa[RPL - 1] += dppx<0xB1>(sa[RPL - 1]); sa[0] += dppx<0x4E>(sa[0]); sa[RPL - 1] += dppx<0x4E>(sa[RPL - 1]);
;                     sa[0] += dppx<0x141>(sa[0]); sa[RPL - 1] += dppx<0x141>(sa[RPL - 1]); sa[0] += dppx<0x140>(sa[0]); sa[RPL - 1] += dppx<0x140>(sa[RPL - 1]);
;                 } else {
; #pragma unroll
;                     for (int q = 0; q < RPL; ++q) sa[q] = reduce16(sa[q]);
;                 }
;                 float ov[RPL];
;                 if (RPL == 2) {
;                     const f32x2 vva = {vr[0], vr[0]}, nsa = {-sa[0], -sa[0]}, vvb = {vr[RPL - 1], vr[RPL - 1]}, nsb = {-sa[RPL - 1], -sa[RPL - 1]};
;                     f32x2 a0 = nsa * b0, c0 = nsb * b0, a1 = nsa * b1, c1 = nsb * b1;
;                     a0 = vva * kd0 + a0; c0 = vvb * kd0 + c0; a1 = vva * kd1 + a1; c1 = vvb * kd1 + c1;
;                     S[0][0] = S[0][0] * w0 + a0; S[RPL - 1][0] = S[RPL - 1][0] * w0 + c0; S[0][1] = S[0][1] * w1 + a1; S[RPL - 1][1] = S[RPL - 1][1] * w1 + c1;
;                     f32x2 ua = S[0][0] * r0, ub = S[RPL - 1][0] * r0;
;                     ua = S[0][1] * r1 + ua; ub = S[RPL - 1][1] * r1 + ub;
;                     ov[0] = ua.x + ua.y; ov[RPL - 1] = ub.x + ub.y;
;                 } else {
; #pragma unroll
;                 for (int q = 0; q < RPL; ++q) {
;                     const f32x2 vv = {vr[q], vr[q]}, ns = {-sa[q], -sa[q]};
	v_pk_mul_f32 v[128:129], v[118:119], v[74:75] op_sel:[0,1]
	v_pk_mul_f32 v[130:131], v[118:119], v[26:27] op_sel:[0,1]
	v_pk_fma_f32 v[128:129], v[116:117], v[74:75], v[128:129] op_sel_hi:[1,0,1]
	v_pk_fma_f32 v[130:131], v[116:117], v[26:27], v[130:131] op_sel_hi:[1,0,1]
	ds_read_b128 v[104:107], v134 offset:40192
	v_pk_fma_f32 v[128:129], v[114:115], v[72:73], v[128:129] op_sel:[0,1,0]
	v_pk_fma_f32 v[130:131], v[114:115], v[24:25], v[130:131] op_sel:[0,1,0]
	v_pk_fma_f32 v[128:129], v[112:113], v[72:73], v[128:129] op_sel_hi:[1,0,1]
	v_pk_fma_f32 v[130:131], v[112:113], v[24:25], v[130:131] op_sel_hi:[1,0,1]
	ds_read_b128 v[96:99], v134 offset:23808
	v_add_f32_dpp v128, v128, v128 quad_perm:[1,0,3,2] row_mask:0xf bank_mask:0xf bound_ctrl:1
	v_add_f32_dpp v129, v129, v129 quad_perm:[1,0,3,2] row_mask:0xf bank_mask:0xf bound_ctrl:1
	v_add_f32_dpp v130, v130, v130 quad_perm:[1,0,3,2] row_mask:0xf bank_mask:0xf bound_ctrl:1
	v_add_f32_dpp v131, v131, v131 quad_perm:[1,0,3,2] row_mask:0xf bank_mask:0xf bound_ctrl:1
	ds_read_b128 v[92:95], v134 offset:15616
	v_add_f32_dpp v128, v128, v128 quad_perm:[2,3,0,1] row_mask:0xf bank_mask:0xf bound_ctrl:1
	v_add_f32_dpp v129, v129, v129 quad_perm:[2,3,0,1] row_mask:0xf bank_mask:0xf bound_ctrl:1
	v_add_f32_dpp v130, v130, v130 quad_perm:[2,3,0,1] row_mask:0xf bank_mask:0xf bound_ctrl:1
	v_add_f32_dpp v131, v131, v131 quad_perm:[2,3,0,1] row_mask:0xf bank_mask:0xf bound_ctrl:1
	s_waitcnt lgkmcnt(4)
	v_pk_mul_f32 v[126:127], v[156:157], v[70:71] op_sel:[0,1]
	v_pk_mul_f32 v[124:125], v[156:157], v[70:71] op_sel_hi:[1,0]
	ds_read_b128 v[88:91], v134 offset:7424
	v_add_f32_dpp v128, v128, v128 row_half_mirror row_mask:0xf bank_mask:0xf bound_ctrl:1
	v_add_f32_dpp v129, v129, v129 row_half_mirror row_mask:0xf bank_mask:0xf bound_ctrl:1
	ds_write2_b32 v149, v130, v131 offset0:128 offset1:132
	v_pk_mul_f32 v[122:123], v[156:157], v[68:69] op_sel:[0,1]
	v_add_f32_dpp v132, v128, v128 row_mirror row_mask:0xf bank_mask:0xf bound_ctrl:1
	v_add_f32_dpp v133, v129, v129 row_mirror row_mask:0xf bank_mask:0xf bound_ctrl:1
	v_pk_mul_f32 v[120:121], v[156:157], v[68:69] op_sel_hi:[1,0]
	v_pk_fma_f32 v[118:119], v[118:119], v[66:67], v[126:127] op_sel:[0,1,0]
	v_pk_fma_f32 v[116:117], v[116:117], v[66:67], v[124:125] op_sel_hi:[1,0,1]
	v_pk_fma_f32 v[114:115], v[114:115], v[64:65], v[122:123] op_sel:[0,1,0]
	v_pk_fma_f32 v[112:113], v[112:113], v[64:65], v[120:121] op_sel_hi:[1,0,1]
	v_pk_fma_f32 v[118:119], v[78:79], v[132:133], v[118:119] op_sel:[1,0,0] neg_lo:[0,1,0] neg_hi:[0,1,0]
	v_pk_fma_f32 v[116:117], v[78:79], v[132:133], v[116:117] op_sel_hi:[0,1,1] neg_lo:[0,1,0] neg_hi:[0,1,0]
	v_pk_fma_f32 v[114:115], v[76:77], v[132:133], v[114:115] op_sel:[1,0,0] neg_lo:[0,1,0] neg_hi:[0,1,0]
	v_pk_fma_f32 v[112:113], v[76:77], v[132:133], v[112:113] op_sel_hi:[0,1,1] neg_lo:[0,1,0] neg_hi:[0,1,0]
	ds_read_b128 v[20:23], v134 offset:32256
	s_waitcnt lgkmcnt(4)
	v_pk_mul_f32 v[128:129], v[118:119], v[98:99] op_sel:[0,1]
	v_pk_mul_f32 v[130:131], v[118:119], v[82:83] op_sel:[0,1]
	v_pk_fma_f32 v[128:129], v[116:117], v[98:99], v[128:129] op_sel_hi:[1,0,1]
	v_pk_fma_f32 v[130:131], v[116:117], v[82:83], v[130:131] op_sel_hi:[1,0,1]
	ds_read_b128 v[24:27], v134 offset:40448
	v_pk_fma_f32 v[128:129], v[114:115], v[96:97], v[128:129] op_sel:[0,1,0]
	v_pk_fma_f32 v[130:131], v[114:115], v[80:81], v[130:131] op_sel:[0,1,0]
	v_pk_fma_f32 v[128:129], v[112:113], v[96:97], v[128:129] op_sel_hi:[1,0,1]
	v_pk_fma_f32 v[130:131], v[112:113], v[80:81], v[130:131] op_sel_hi:[1,0,1]
	ds_read_b128 v[16:19], v134 offset:24064
	v_add_f32_dpp v128, v128, v128 quad_perm:[1,0,3,2] row_mask:0xf bank_mask:0xf bound_ctrl:1
	v_add_f32_dpp v129, v129, v129 quad_perm:[1,0,3,2] row_mask:0xf bank_mask:0xf bound_ctrl:1
	v_add_f32_dpp v130, v130, v130 quad_perm:[1,0,3,2] row_mask:0xf bank_mask:0xf bound_ctrl:1
	v_add_f32_dpp v131, v131, v131 quad_perm:[1,0,3,2] row_mask:0xf bank_mask:0xf bound_ctrl:1
	ds_read_b128 v[12:15], v134 offset:15872
	v_add_f32_dpp v128, v128, v128 quad_perm:[2,3,0,1] row_mask:0xf bank_mask:0xf bound_ctrl:1
	v_add_f32_dpp v129, v129, v129 quad_perm:[2,3,0,1] row_mask:0xf bank_mask:0xf bound_ctrl:1
	v_add_f32_dpp v130, v130, v130 quad_perm:[2,3,0,1] row_mask:0xf bank_mask:0xf bound_ctrl:1
	v_add_f32_dpp v131, v131, v131 quad_perm:[2,3,0,1] row_mask:0xf bank_mask:0xf bound_ctrl:1
	s_waitcnt lgkmcnt(4)
	v_pk_mul_f32 v[126:127], v[158:159], v[94:95] op_sel:[0,1]
	v_pk_mul_f32 v[124:125], v[158:159], v[94:95] op_sel_hi:[1,0]
	ds_read2_b64 v[160:163], v111 offset0:224 offset1:240
	v_add_f32_dpp v128, v128, v128 row_half_mirror row_mask:0xf bank_mask:0xf bound_ctrl:1
	v_add_f32_dpp v129, v129, v129 row_half_mirror row_mask:0xf bank_mask:0xf bound_ctrl:1
	ds_write2_b32 v150, v130, v131 offset0:0 offset1:4
	v_pk_mul_f32 v[122:123], v[158:159], v[92:93] op_sel:[0,1]
	v_add_f32_dpp v132, v128, v128 row_mirror row_mask:0xf bank_mask:0xf bound_ctrl:1
	v_add_f32_dpp v133, v129, v129 row_mirror row_mask:0xf bank_mask:0xf bound_ctrl:1
	v_pk_mul_f32 v[120:121], v[158:159], v[92:93] op_sel_hi:[1,0]
	ds_read_b128 v[8:11], v134 offset:7680
	v_pk_fma_f32 v[118:119], v[118:119], v[90:91], v[126:127] op_sel:[0,1,0]
	v_pk_fma_f32 v[116:117], v[116:117], v[90:91], v[124:125] op_sel_hi:[1,0,1]
	v_pk_fma_f32 v[114:115], v[114:115], v[88:89], v[122:123] op_sel:[0,1,0]
	v_pk_fma_f32 v[112:113], v[112:113], v[88:89], v[120:121] op_sel_hi:[1,0,1]
	v_pk_fma_f32 v[118:119], v[102:103], v[132:133], v[118:119] op_sel:[1,0,0] neg_lo:[0,1,0] neg_hi:[0,1,0]
	v_pk_fma_f32 v[116:117], v[102:103], v[132:133], v[116:117] op_sel_hi:[0,1,1] neg_lo:[0,1,0] neg_hi:[0,1,0]
	v_pk_fma_f32 v[114:115], v[100:101], v[132:133], v[114:115] op_sel:[1,0,0] neg_lo:[0,1,0] neg_hi:[0,1,0]
	v_pk_fma_f32 v[112:113], v[100:101], v[132:133], v[112:113] op_sel_hi:[0,1,1] neg_lo:[0,1,0] neg_hi:[0,1,0]
	ds_read_b128 v[76:79], v134 offset:32512
	s_waitcnt lgkmcnt(4)
; template <int RPL, int NSW>
; __device__ __forceinline__ void scan_item(const P& p, LAS unsigned char* lds, int seqbase, int L, int head, int dir, int part, int step0, int nsteps, int mode, float* qc, float* smid) {
;     ...
;             for (int s = 0; s < TC; ++s) {
;                 const f32x2 w0 = {xw[0], xw[1]}, w1 = {xw[2], xw[3]}, kd0 = {xkd[0], xkd[1]}, kd1 = {xkd[2], xkd[3]}, kk0 = {xkk[0], xkk[1]}, kk1 = {xkk[2], xkk[3]},
;                             b0 = {xb[0], xb[1]}, b1 = {xb[2], xb[3]}, r0 = {xr[0], xr[1]}, r1 = {xr[2], xr[3]};
;                 float vr[RPL];
; #pragma unroll
;                 for (int q = 0; q < RPL; ++q) vr[q] = vrow[q];
;                 { const int sn = (s + 1 < TC) ? s + 1 : s; SCAN_LD(sn); }
;                 float sa[RPL];
; #pragma unroll
;                 for (int q = 0; q < RPL; ++q) { const f32x2 t = S[q][0] * kk0 + S[q][1] * kk1; sa[q] = t.x + t.y; }
;                 if (RPL == 2) {
;                     sa[0] += dppx<0xB1>(sa[0]); sa[RPL - 1] += dppx<0xB1>(sa[RPL - 1]); sa[0] += dppx<0x4E>(sa[0]); sa[RPL - 1] += dppx<0x4E>(sa[RPL - 1]);
;                     sa[0] += dppx<0x141>(sa[0]); sa[RPL - 1] += dppx<0x141>(sa[RPL - 1]); sa[0] += dppx<0x140>(sa[0]); sa[RPL - 1] += dppx<0x140>(sa[RPL - 1]);
;                 } else {
; #pragma unroll
;                     for (int q = 0; q < RPL; ++q) sa[q] = reduce16(sa[q]);
;                 }
;                 float ov[RPL];
;                 if (RPL == 2) {
;                     const f32x2 vva = {vr[0], vr[0]}, nsa = {-sa[0], -sa[0]}, vvb = {vr[RPL - 1], vr[RPL - 1]}, nsb = {-sa[RPL - 1], -sa[RPL - 1]};
;                     f32x2 a0 = nsa * b0, c0 = nsb * b0, a1 = nsa * b1, c1 = nsb * b1;
;                     a0 = vva * kd0 + a0; c0 = vvb * kd0 + c0; a1 = vva * kd1 + a1; c1 = vvb * kd1 + c1;
;                     S[0][0] = S[0][0] * w0 + a0; S[RPL - 1][0] = S[RPL - 1][0] * w0 + c0; S[0][1] = S[0][1] * w1 + a1; S[RPL - 1][1] = S[RPL - 1][1] * w1 + c1;
;                     f32x2 ua = S[0][0] * r0, ub = S[RPL - 1][0] * r0;
;                     ua = S[0][1] * r1 + ua; ub = S[RPL - 1][1] * r1 + ub;
;                     ov[0] = ua.x + ua.y; ov[RPL - 1] = ub.x + ub.y;
;                 } else {
; #pragma unroll
;                 for (int q = 0; q < RPL; ++q) {
;                     const f32x2 vv = {vr[q], vr[q]}, ns = {-sa[q], -sa[q]};
	v_pk_mul_f32 v[128:129], v[118:119], v[18:19] op_sel:[0,1]
	v_pk_mul_f32 v[130:131], v[118:119], v[106:107] op_sel:[0,1]
	v_pk_fma_f32 v[128:129], v[116:117], v[18:19], v[128:129] op_sel_hi:[1,0,1]
	v_pk_fma_f32 v[130:131], v[116:117], v[106:107], v[130:131] op_sel_hi:[1,0,1]
	ds_read_b128 v[80:83], v134 offset:40704
	v_pk_fma_f32 v[128:129], v[114:115], v[16:17], v[128:129] op_sel:[0,1,0]
	v_pk_fma_f32 v[130:131], v[114:115], v[104:105], v[130:131] op_sel:[0,1,0]
	v_pk_fma_f32 v[128:129], v[112:113], v[16:17], v[128:129] op_sel_hi:[1,0,1]
	v_pk_fma_f32 v[130:131], v[112:113], v[104:105], v[130:131] op_sel_hi:[1,0,1]
	ds_read_b128 v[72:75], v134 offset:24320
	v_add_f32_dpp v128, v128, v128 quad_perm:[1,0,3,2] row_mask:0xf bank_mask:0xf bound_ctrl:1
	v_add_f32_dpp v129, v129, v129 quad_perm:[1,0,3,2] row_mask:0xf bank_mask:0xf bound_ctrl:1
	v_add_f32_dpp v130, v130, v130 quad_perm:[1,0,3,2] row_mask:0xf bank_mask:0xf bound_ctrl:1
	v_add_f32_dpp v131, v131, v131 quad_perm:[1,0,3,2] row_mask:0xf bank_mask:0xf bound_ctrl:1
	ds_read_b128 v[68:71], v134 offset:16128
	v_add_f32_dpp v128, v128, v128 quad_perm:[2,3,0,1] row_mask:0xf bank_mask:0xf bound_ctrl:1
	v_add_f32_dpp v129, v129, v129 quad_perm:[2,3,0,1] row_mask:0xf bank_mask:0xf bound_ctrl:1
	v_add_f32_dpp v130, v130, v130 quad_perm:[2,3,0,1] row_mask:0xf bank_mask:0xf bound_ctrl:1
	v_add_f32_dpp v131, v131, v131 quad_perm:[2,3,0,1] row_mask:0xf bank_mask:0xf bound_ctrl:1
	s_waitcnt lgkmcnt(4)
	v_pk_mul_f32 v[126:127], v[160:161], v[14:15] op_sel:[0,1]
	v_pk_mul_f32 v[124:125], v[160:161], v[14:15] op_sel_hi:[1,0]
	ds_read_b128 v[64:67], v134 offset:7936
	v_add_f32_dpp v128, v128, v128 row_half_mirror row_mask:0xf bank_mask:0xf bound_ctrl:1
	v_add_f32_dpp v129, v129, v129 row_half_mirror row_mask:0xf bank_mask:0xf bound_ctrl:1
	ds_write2_b32 v150, v130, v131 offset0:128 offset1:132
	v_pk_mul_f32 v[122:123], v[160:161], v[12:13] op_sel:[0,1]
	v_add_f32_dpp v132, v128, v128 row_mirror row_mask:0xf bank_mask:0xf bound_ctrl:1
	v_add_f32_dpp v133, v129, v129 row_mirror row_mask:0xf bank_mask:0xf bound_ctrl:1
	v_pk_mul_f32 v[120:121], v[160:161], v[12:13] op_sel_hi:[1,0]
	v_pk_fma_f32 v[118:119], v[118:119], v[10:11], v[126:127] op_sel:[0,1,0]
	v_pk_fma_f32 v[116:117], v[116:117], v[10:11], v[124:125] op_sel_hi:[1,0,1]
	v_pk_fma_f32 v[114:115], v[114:115], v[8:9], v[122:123] op_sel:[0,1,0]
	v_pk_fma_f32 v[112:113], v[112:113], v[8:9], v[120:121] op_sel_hi:[1,0,1]
	v_pk_fma_f32 v[118:119], v[22:23], v[132:133], v[118:119] op_sel:[1,0,0] neg_lo:[0,1,0] neg_hi:[0,1,0]
	v_pk_fma_f32 v[116:117], v[22:23], v[132:133], v[116:117] op_sel_hi:[0,1,1] neg_lo:[0,1,0] neg_hi:[0,1,0]
	v_pk_fma_f32 v[114:115], v[20:21], v[132:133], v[114:115] op_sel:[1,0,0] neg_lo:[0,1,0] neg_hi:[0,1,0]
	v_pk_fma_f32 v[112:113], v[20:21], v[132:133], v[112:113] op_sel_hi:[0,1,1] neg_lo:[0,1,0] neg_hi:[0,1,0]
	s_waitcnt lgkmcnt(3)
	v_pk_mul_f32 v[128:129], v[118:119], v[74:75] op_sel:[0,1]
	v_pk_mul_f32 v[130:131], v[118:119], v[26:27] op_sel:[0,1]
	v_pk_fma_f32 v[128:129], v[116:117], v[74:75], v[128:129] op_sel_hi:[1,0,1]
	v_pk_fma_f32 v[130:131], v[116:117], v[26:27], v[130:131] op_sel_hi:[1,0,1]
	v_pk_fma_f32 v[128:129], v[114:115], v[72:73], v[128:129] op_sel:[0,1,0]
	v_pk_fma_f32 v[130:131], v[114:115], v[24:25], v[130:131] op_sel:[0,1,0]
	v_pk_fma_f32 v[128:129], v[112:113], v[72:73], v[128:129] op_sel_hi:[1,0,1]
	v_pk_fma_f32 v[130:131], v[112:113], v[24:25], v[130:131] op_sel_hi:[1,0,1]
	s_waitcnt lgkmcnt(2)
	v_pk_mul_f32 v[126:127], v[162:163], v[70:71] op_sel:[0,1]
	v_add_f32_dpp v128, v128, v128 quad_perm:[1,0,3,2] row_mask:0xf bank_mask:0xf bound_ctrl:1
	v_add_f32_dpp v129, v129, v129 quad_perm:[1,0,3,2] row_mask:0xf bank_mask:0xf bound_ctrl:1
	v_add_f32_dpp v130, v130, v130 quad_perm:[1,0,3,2] row_mask:0xf bank_mask:0xf bound_ctrl:1
	v_add_f32_dpp v131, v131, v131 quad_perm:[1,0,3,2] row_mask:0xf bank_mask:0xf bound_ctrl:1
	v_add_f32_dpp v128, v128, v128 quad_perm:[2,3,0,1] row_mask:0xf bank_mask:0xf bound_ctrl:1
	v_add_f32_dpp v129, v129, v129 quad_perm:[2,3,0,1] row_mask:0xf bank_mask:0xf bound_ctrl:1
	v_add_f32_dpp v130, v130, v130 quad_perm:[2,3,0,1] row_mask:0xf bank_mask:0xf bound_ctrl:1
	v_add_f32_dpp v131, v131, v131 quad_perm:[2,3,0,1] row_mask:0xf bank_mask:0xf bound_ctrl:1
	v_pk_mul_f32 v[124:125], v[162:163], v[70:71] op_sel_hi:[1,0]
	v_add_f32_dpp v128, v128, v128 row_half_mirror row_mask:0xf bank_mask:0xf bound_ctrl:1
	v_add_f32_dpp v129, v129, v129 row_half_mirror row_mask:0xf bank_mask:0xf bound_ctrl:1
	ds_write2_b32 v151, v130, v131 offset0:0 offset1:4
	v_pk_mul_f32 v[122:123], v[162:163], v[68:69] op_sel:[0,1]
	v_add_f32_dpp v132, v128, v128 row_mirror row_mask:0xf bank_mask:0xf bound_ctrl:1
	v_add_f32_dpp v133, v129, v129 row_mirror row_mask:0xf bank_mask:0xf bound_ctrl:1
	v_pk_mul_f32 v[120:121], v[162:163], v[68:69] op_sel_hi:[1,0]
	s_waitcnt lgkmcnt(1)
	v_pk_fma_f32 v[118:119], v[118:119], v[66:67], v[126:127] op_sel:[0,1,0]
	v_pk_fma_f32 v[116:117], v[116:117], v[66:67], v[124:125] op_sel_hi:[1,0,1]
	v_pk_fma_f32 v[114:115], v[114:115], v[64:65], v[122:123] op_sel:[0,1,0]
	v_pk_fma_f32 v[112:113], v[112:113], v[64:65], v[120:121] op_sel_hi:[1,0,1]
	v_pk_fma_f32 v[118:119], v[78:79], v[132:133], v[118:119] op_sel:[1,0,0] neg_lo:[0,1,0] neg_hi:[0,1,0]
	v_pk_fma_f32 v[116:117], v[78:79], v[132:133], v[116:117] op_sel_hi:[0,1,1] neg_lo:[0,1,0] neg_hi:[0,1,0]
	v_pk_fma_f32 v[114:115], v[76:77], v[132:133], v[114:115] op_sel:[1,0,0] neg_lo:[0,1,0] neg_hi:[0,1,0]
	v_pk_fma_f32 v[112:113], v[76:77], v[132:133], v[112:113] op_sel_hi:[0,1,1] neg_lo:[0,1,0] neg_hi:[0,1,0]
	v_pk_mul_f32 v[130:131], v[118:119], v[82:83] op_sel:[0,1]
	v_pk_fma_f32 v[130:131], v[116:117], v[82:83], v[130:131] op_sel_hi:[1,0,1]
	v_pk_fma_f32 v[130:131], v[114:115], v[80:81], v[130:131] op_sel:[0,1,0]
	v_pk_fma_f32 v[130:131], v[112:113], v[80:81], v[130:131] op_sel_hi:[1,0,1]
	s_add_i32 s4, s4, 1
	s_cmpk_eq_i32 s4, 0x100
	v_add_f32_dpp v130, v130, v130 quad_perm:[1,0,3,2] row_mask:0xf bank_mask:0xf bound_ctrl:1
	v_add_f32_dpp v131, v131, v131 quad_perm:[1,0,3,2] row_mask:0xf bank_mask:0xf bound_ctrl:1
	s_nop 0
	v_add_f32_dpp v130, v130, v130 quad_perm:[2,3,0,1] row_mask:0xf bank_mask:0xf bound_ctrl:1
	v_add_f32_dpp v131, v131, v131 quad_perm:[2,3,0,1] row_mask:0xf bank_mask:0xf bound_ctrl:1
	ds_write2_b32 v151, v130, v131 offset0:128 offset1:132
	s_waitcnt lgkmcnt(0)
	s_barrier
; template <int RPL, int NSW>
; __device__ __forceinline__ void scan_item(const P& p, LAS unsigned char* lds, int seqbase, int L, int head, int dir, int part, int step0, int nsteps, int mode, float* qc, float* smid) {
;     ...
;             __syncthreads();
;         }
;         if (smid) {
; #pragma unroll
;             for (int q = 0; q < RPL; ++q) { const f32x4 sv = {S[q][0].x, S[q][0].y, S[q][1].x, S[q][1].y}; *(f32x4*)(smid + (size_t)(rowbase + lr0 + q) * 64 + 4 * kq) = sv; } }
	s_cbranch_scc0 .Lmy_scan_chunk
	v_mov_b32_e32 v0, v112
	v_mov_b32_e32 v4, v113
	v_mov_b32_e32 v1, v114
	v_mov_b32_e32 v5, v115
	v_mov_b32_e32 v2, v116
	v_mov_b32_e32 v6, v117
	v_mov_b32_e32 v3, v118
	v_mov_b32_e32 v7, v119
	s_cmp_eq_u64 s[8:9], 0
	s_cbranch_scc1 .LBB0_980
	v_lshlrev_b32_e32 v168, 2, v49
	v_ashrrev_i32_e32 v51, 31, v50
	v_ashrrev_i32_e32 v49, 31, v48
	v_lshl_add_u64 v[8:9], s[8:9], 0, v[168:169]
	v_lshlrev_b64 v[10:11], 8, v[50:51]
	v_lshlrev_b64 v[12:13], 8, v[48:49]
	v_lshl_add_u64 v[10:11], v[8:9], 0, v[10:11]
	v_lshl_add_u64 v[8:9], v[8:9], 0, v[12:13]
	global_store_dwordx4 v[8:9], v[0:3], off
	global_store_dwordx4 v[10:11], v[4:7], off
